# speedup vs baseline: 1.0051x; 1.0037x over previous
; #define STAGE_TILE() do { SW_BEGIN const f32x4 v_ = acc[ai][bj][m][n2]; \
;     *(u32x2*)(smem + mrow * SPITCH + nc0 * 2) = u32x2{cvtpk(v_[0], v_[1]), cvtpk(v_[2], v_[3])}; LOOP_END __syncthreads(); } while (0)
; #define STAGE_TILE_F(XFORM) do { SW_BEGIN f32x4 v = acc[ai][bj][m][n2]; XFORM; \
;     *(u32x2*)(smem + mrow * SPITCH + nc0 * 2) = u32x2{cvtpk_t(v[0], v[1]), cvtpk_t(v[2], v[3])}; LOOP_END __syncthreads(); } while (0)
; template <int kind> __device__ __forceinline__ void gemm_phase_n(const Params& P, int layer, int b, const int wv) {
;     ...
;                 if (kind == G_OUTH) STAGE_TILE_F(v *= rs_lds[3 * 256 + mrow]); else STAGE_TILE();
;                 u16* dst = (u16*)(ws + O_Y) + (size_t)(pm * 256) * 1024 + pn * 256;
;                 DRAIN_BEGIN *(u32x4*)(dst + (size_t)row * 1024 + chunk * 8) = w; LOOP_END
.LBB0_371:
	v_mov_b32_e32 v0, v1
	s_movk_i32 s4, 0x60
	v_mbcnt_lo_u32_b32 v0, -1, v0
	v_mbcnt_hi_u32_b32 v0, -1, v0
	v_or_b32_e32 v130, s57, v0
	s_lshl_b64 s[6:7], s[10:11], 1
	v_and_b32_e32 v0, 15, v130
	v_lshrrev_b32_e32 v131, 1, v130
	v_and_or_b32 v131, v131, s4, v0
	v_readlane_b32 s4, v254, 15
	v_lshrrev_b32_e32 v134, 2, v130
	v_ashrrev_i32_e32 v133, 2, v130
	v_lshl_add_u32 v0, v131, 2, s4
	ds_read_b32 v135, v0 offset:3072
	ds_read_b32 v136, v0 offset:3136
	ds_read_b32 v137, v0 offset:3584
	ds_read_b32 v138, v0 offset:3648
	s_waitcnt lgkmcnt(0)
	v_mov_b32_e32 v132, v135
	v_and_b32_e32 v134, 12, v134
	s_mov_b32 s4, 0x7fffffc0
	v_and_or_b32 v133, v133, s4, v134
	v_lshlrev_b32_e32 v134, 1, v133
	v_pk_mul_f32 v[126:127], v[126:127], v[132:133] op_sel_hi:[1,0]
	v_pk_mul_f32 v[128:129], v[128:129], v[132:133] op_sel_hi:[1,0]
	v_cvt_pk_bf16_f32 v132, v126, v127
	v_mul_u32_u24_e32 v126, 0x220, v131
	v_add3_u32 v126, 0, v134, v126
	v_cvt_pk_bf16_f32 v133, v128, v129
	ds_write_b64 v126, v[132:133]
	v_mov_b32_e32 v128, v136
	s_lshl_b32 s4, s8, 8
	s_ashr_i32 s5, s4, 31
	s_lshl_b64 s[4:5], s[4:5], 11
	s_add_u32 s6, s24, s6
	v_pk_mul_f32 v[122:123], v[122:123], v[128:129] op_sel_hi:[1,0]
	v_pk_mul_f32 v[124:125], v[124:125], v[128:129] op_sel_hi:[1,0]
	v_cvt_pk_bf16_f32 v122, v122, v123
	s_movk_i32 s8, 0x220
	v_cvt_pk_bf16_f32 v123, v124, v125
	ds_write_b64 v126, v[122:123] offset:8704
	v_mov_b32_e32 v122, v137
	v_add_u32_e32 v123, 0x2200, v126
	s_addc_u32 s7, s25, s7
	v_pk_mul_f32 v[118:119], v[118:119], v[122:123] op_sel_hi:[1,0]
	v_pk_mul_f32 v[120:121], v[120:121], v[122:123] op_sel_hi:[1,0]
	v_cvt_pk_bf16_f32 v118, v118, v119
	s_nop 0
	v_cvt_pk_bf16_f32 v119, v120, v121
	ds_write_b64 v123, v[118:119] offset:60928
	v_mov_b32_e32 v118, v138
	v_add_u32_e32 v119, 0xee00, v123
	v_pk_mul_f32 v[114:115], v[114:115], v[118:119] op_sel_hi:[1,0]
	v_pk_mul_f32 v[116:117], v[116:117], v[118:119] op_sel_hi:[1,0]
	v_cvt_pk_bf16_f32 v114, v114, v115
	s_nop 0
	v_cvt_pk_bf16_f32 v115, v116, v117
	ds_write_b64 v119, v[114:115] offset:8704
	s_waitcnt vmcnt(0)
	v_mov_b32_e32 v114, v135
	v_pk_mul_f32 v[110:111], v[110:111], v[114:115] op_sel_hi:[1,0]
	v_pk_mul_f32 v[112:113], v[112:113], v[114:115] op_sel_hi:[1,0]
	v_cvt_pk_bf16_f32 v110, v110, v111
	s_nop 0
	v_cvt_pk_bf16_f32 v111, v112, v113
	ds_write_b64 v126, v[110:111] offset:32
	v_mov_b32_e32 v110, v136
	v_pk_mul_f32 v[106:107], v[106:107], v[110:111] op_sel_hi:[1,0]
	v_pk_mul_f32 v[108:109], v[108:109], v[110:111] op_sel_hi:[1,0]
	v_cvt_pk_bf16_f32 v106, v106, v107
	s_nop 0
	v_cvt_pk_bf16_f32 v107, v108, v109
	ds_write_b64 v126, v[106:107] offset:8736
	v_mov_b32_e32 v106, v137
	v_pk_mul_f32 v[102:103], v[102:103], v[106:107] op_sel_hi:[1,0]
	v_pk_mul_f32 v[104:105], v[104:105], v[106:107] op_sel_hi:[1,0]
	v_cvt_pk_bf16_f32 v102, v102, v103
	s_nop 0
	v_cvt_pk_bf16_f32 v103, v104, v105
	ds_write_b64 v123, v[102:103] offset:60960
	v_mov_b32_e32 v102, v138
	v_pk_mul_f32 v[98:99], v[98:99], v[102:103] op_sel_hi:[1,0]
	v_pk_mul_f32 v[100:101], v[100:101], v[102:103] op_sel_hi:[1,0]
	v_cvt_pk_bf16_f32 v98, v98, v99
	s_nop 0
	v_cvt_pk_bf16_f32 v99, v100, v101
	ds_write_b64 v119, v[98:99] offset:8736
	v_mov_b32_e32 v98, v135
	v_pk_mul_f32 v[94:95], v[94:95], v[98:99] op_sel_hi:[1,0]
	v_pk_mul_f32 v[96:97], v[96:97], v[98:99] op_sel_hi:[1,0]
	v_cvt_pk_bf16_f32 v94, v94, v95
	s_nop 0
	v_cvt_pk_bf16_f32 v95, v96, v97
	ds_write_b64 v126, v[94:95] offset:64
	v_mov_b32_e32 v94, v136
	v_pk_mul_f32 v[90:91], v[90:91], v[94:95] op_sel_hi:[1,0]
	v_pk_mul_f32 v[92:93], v[92:93], v[94:95] op_sel_hi:[1,0]
	v_cvt_pk_bf16_f32 v90, v90, v91
	s_nop 0
	v_cvt_pk_bf16_f32 v91, v92, v93
	ds_write_b64 v126, v[90:91] offset:8768
	v_mov_b32_e32 v90, v137
	v_pk_mul_f32 v[86:87], v[86:87], v[90:91] op_sel_hi:[1,0]
	v_pk_mul_f32 v[88:89], v[88:89], v[90:91] op_sel_hi:[1,0]
	v_cvt_pk_bf16_f32 v86, v86, v87
	s_nop 0
	v_cvt_pk_bf16_f32 v87, v88, v89
	ds_write_b64 v123, v[86:87] offset:60992
	v_mov_b32_e32 v86, v138
	v_pk_mul_f32 v[82:83], v[82:83], v[86:87] op_sel_hi:[1,0]
	v_pk_mul_f32 v[84:85], v[84:85], v[86:87] op_sel_hi:[1,0]
	v_cvt_pk_bf16_f32 v82, v82, v83
	s_nop 0
	v_cvt_pk_bf16_f32 v83, v84, v85
	ds_write_b64 v119, v[82:83] offset:8768
	v_mov_b32_e32 v82, v135
	v_pk_mul_f32 v[78:79], v[78:79], v[82:83] op_sel_hi:[1,0]
	v_pk_mul_f32 v[80:81], v[80:81], v[82:83] op_sel_hi:[1,0]
	v_cvt_pk_bf16_f32 v78, v78, v79
	s_nop 0
	v_cvt_pk_bf16_f32 v79, v80, v81
	ds_write_b64 v126, v[78:79] offset:96
	v_mov_b32_e32 v78, v136
	v_pk_mul_f32 v[74:75], v[74:75], v[78:79] op_sel_hi:[1,0]
	v_pk_mul_f32 v[76:77], v[76:77], v[78:79] op_sel_hi:[1,0]
	v_cvt_pk_bf16_f32 v74, v74, v75
	s_nop 0
	v_cvt_pk_bf16_f32 v75, v76, v77
	ds_write_b64 v126, v[74:75] offset:8800
	v_mov_b32_e32 v74, v137
	v_pk_mul_f32 v[70:71], v[70:71], v[74:75] op_sel_hi:[1,0]
	v_pk_mul_f32 v[72:73], v[72:73], v[74:75] op_sel_hi:[1,0]
; #define STAGE_TILE() do { SW_BEGIN const f32x4 v_ = acc[ai][bj][m][n2]; \
;     *(u32x2*)(smem + mrow * SPITCH + nc0 * 2) = u32x2{cvtpk(v_[0], v_[1]), cvtpk(v_[2], v_[3])}; LOOP_END __syncthreads(); } while (0)
; #define STAGE_TILE_F(XFORM) do { SW_BEGIN f32x4 v = acc[ai][bj][m][n2]; XFORM; \
;     *(u32x2*)(smem + mrow * SPITCH + nc0 * 2) = u32x2{cvtpk_t(v[0], v[1]), cvtpk_t(v[2], v[3])}; LOOP_END __syncthreads(); } while (0)
; template <int kind> __device__ __forceinline__ void gemm_phase_n(const Params& P, int layer, int b, const int wv) {
;     ...
;                 if (kind == G_OUTH) STAGE_TILE_F(v *= rs_lds[3 * 256 + mrow]); else STAGE_TILE();
;                 u16* dst = (u16*)(ws + O_Y) + (size_t)(pm * 256) * 1024 + pn * 256;
;                 DRAIN_BEGIN *(u32x4*)(dst + (size_t)row * 1024 + chunk * 8) = w; LOOP_END
	v_cvt_pk_bf16_f32 v70, v70, v71
	s_nop 0
	v_cvt_pk_bf16_f32 v71, v72, v73
	ds_write_b64 v123, v[70:71] offset:61024
	v_mov_b32_e32 v70, v138
	v_pk_mul_f32 v[66:67], v[66:67], v[70:71] op_sel_hi:[1,0]
	v_pk_mul_f32 v[68:69], v[68:69], v[70:71] op_sel_hi:[1,0]
	v_cvt_pk_bf16_f32 v66, v66, v67
	s_nop 0
	v_cvt_pk_bf16_f32 v67, v68, v69
	ds_write_b64 v119, v[66:67] offset:8800
	v_mov_b32_e32 v66, v135
	v_pk_mul_f32 v[62:63], v[62:63], v[66:67] op_sel_hi:[1,0]
	v_pk_mul_f32 v[64:65], v[64:65], v[66:67] op_sel_hi:[1,0]
	v_cvt_pk_bf16_f32 v62, v62, v63
	s_nop 0
	v_cvt_pk_bf16_f32 v63, v64, v65
	ds_write_b64 v126, v[62:63] offset:256
	v_mov_b32_e32 v62, v136
	v_pk_mul_f32 v[58:59], v[58:59], v[62:63] op_sel_hi:[1,0]
	v_pk_mul_f32 v[60:61], v[60:61], v[62:63] op_sel_hi:[1,0]
	v_cvt_pk_bf16_f32 v58, v58, v59
	s_nop 0
	v_cvt_pk_bf16_f32 v59, v60, v61
	ds_write_b64 v126, v[58:59] offset:8960
	v_mov_b32_e32 v58, v137
	v_pk_mul_f32 v[54:55], v[54:55], v[58:59] op_sel_hi:[1,0]
	v_pk_mul_f32 v[56:57], v[56:57], v[58:59] op_sel_hi:[1,0]
	v_cvt_pk_bf16_f32 v54, v54, v55
	s_nop 0
	v_cvt_pk_bf16_f32 v55, v56, v57
	ds_write_b64 v123, v[54:55] offset:61184
	v_mov_b32_e32 v54, v138
	v_pk_mul_f32 v[50:51], v[50:51], v[54:55] op_sel_hi:[1,0]
	v_pk_mul_f32 v[52:53], v[52:53], v[54:55] op_sel_hi:[1,0]
	v_cvt_pk_bf16_f32 v50, v50, v51
	s_nop 0
	v_cvt_pk_bf16_f32 v51, v52, v53
	ds_write_b64 v119, v[50:51] offset:8960
	v_mov_b32_e32 v50, v135
	v_pk_mul_f32 v[46:47], v[46:47], v[50:51] op_sel_hi:[1,0]
	v_pk_mul_f32 v[48:49], v[48:49], v[50:51] op_sel_hi:[1,0]
	v_cvt_pk_bf16_f32 v46, v46, v47
	s_nop 0
	v_cvt_pk_bf16_f32 v47, v48, v49
	ds_write_b64 v126, v[46:47] offset:288
	v_mov_b32_e32 v46, v136
	v_pk_mul_f32 v[42:43], v[42:43], v[46:47] op_sel_hi:[1,0]
	v_pk_mul_f32 v[44:45], v[44:45], v[46:47] op_sel_hi:[1,0]
	v_cvt_pk_bf16_f32 v42, v42, v43
	s_nop 0
	v_cvt_pk_bf16_f32 v43, v44, v45
	ds_write_b64 v126, v[42:43] offset:8992
	v_mov_b32_e32 v42, v137
	v_pk_mul_f32 v[38:39], v[38:39], v[42:43] op_sel_hi:[1,0]
	v_pk_mul_f32 v[40:41], v[40:41], v[42:43] op_sel_hi:[1,0]
	v_cvt_pk_bf16_f32 v38, v38, v39
	s_nop 0
	v_cvt_pk_bf16_f32 v39, v40, v41
	ds_write_b64 v123, v[38:39] offset:61216
	v_mov_b32_e32 v38, v138
	v_pk_mul_f32 v[34:35], v[34:35], v[38:39] op_sel_hi:[1,0]
	v_pk_mul_f32 v[36:37], v[36:37], v[38:39] op_sel_hi:[1,0]
	v_cvt_pk_bf16_f32 v34, v34, v35
	s_nop 0
	v_cvt_pk_bf16_f32 v35, v36, v37
	ds_write_b64 v119, v[34:35] offset:8992
	v_mov_b32_e32 v34, v135
	v_pk_mul_f32 v[30:31], v[30:31], v[34:35] op_sel_hi:[1,0]
	v_pk_mul_f32 v[32:33], v[32:33], v[34:35] op_sel_hi:[1,0]
	v_cvt_pk_bf16_f32 v30, v30, v31
	s_nop 0
	v_cvt_pk_bf16_f32 v31, v32, v33
	ds_write_b64 v126, v[30:31] offset:320
	v_mov_b32_e32 v30, v136
	v_pk_mul_f32 v[26:27], v[26:27], v[30:31] op_sel_hi:[1,0]
	v_pk_mul_f32 v[28:29], v[28:29], v[30:31] op_sel_hi:[1,0]
	v_cvt_pk_bf16_f32 v26, v26, v27
	s_nop 0
	v_cvt_pk_bf16_f32 v27, v28, v29
	ds_write_b64 v126, v[26:27] offset:9024
	v_mov_b32_e32 v26, v137
	v_pk_mul_f32 v[22:23], v[22:23], v[26:27] op_sel_hi:[1,0]
	v_pk_mul_f32 v[24:25], v[24:25], v[26:27] op_sel_hi:[1,0]
	v_cvt_pk_bf16_f32 v22, v22, v23
	s_nop 0
	v_cvt_pk_bf16_f32 v23, v24, v25
	ds_write_b64 v123, v[22:23] offset:61248
	v_mov_b32_e32 v22, v138
	v_pk_mul_f32 v[18:19], v[18:19], v[22:23] op_sel_hi:[1,0]
	v_pk_mul_f32 v[20:21], v[20:21], v[22:23] op_sel_hi:[1,0]
	v_cvt_pk_bf16_f32 v18, v18, v19
	s_nop 0
	v_cvt_pk_bf16_f32 v19, v20, v21
	ds_write_b64 v119, v[18:19] offset:9024
	v_mov_b32_e32 v18, v135
	v_pk_mul_f32 v[14:15], v[14:15], v[18:19] op_sel_hi:[1,0]
	v_pk_mul_f32 v[16:17], v[16:17], v[18:19] op_sel_hi:[1,0]
	v_cvt_pk_bf16_f32 v14, v14, v15
	s_nop 0
	v_cvt_pk_bf16_f32 v15, v16, v17
	ds_write_b64 v126, v[14:15] offset:352
	v_mov_b32_e32 v14, v136
	v_lshlrev_b32_e32 v15, 4, v130
	v_ashrrev_i32_e32 v16, 5, v130
	v_ashrrev_i32_e32 v17, 31, v16
	v_pk_mul_f32 v[10:11], v[10:11], v[14:15] op_sel_hi:[1,0]
	v_pk_mul_f32 v[12:13], v[12:13], v[14:15] op_sel_hi:[1,0]
	v_cvt_pk_bf16_f32 v10, v10, v11
	v_mul_lo_u32 v14, v16, s8
	v_cvt_pk_bf16_f32 v11, v12, v13
	ds_write_b64 v126, v[10:11] offset:9056
	v_mov_b32_e32 v10, v137
	v_and_b32_e32 v11, 0x1f0, v15
	v_lshlrev_b64 v[12:13], 11, v[16:17]
	v_pk_mul_f32 v[6:7], v[6:7], v[10:11] op_sel_hi:[1,0]
	v_pk_mul_f32 v[8:9], v[8:9], v[10:11] op_sel_hi:[1,0]
	v_cvt_pk_bf16_f32 v6, v6, v7
	s_nop 0
	v_cvt_pk_bf16_f32 v7, v8, v9
	ds_write_b64 v123, v[6:7] offset:61280
	v_mov_b32_e32 v8, v138
	v_lshl_add_u64 v[6:7], v[12:13], 0, s[4:5]
	v_or_b32_e32 v6, v6, v11
	v_add3_u32 v0, v14, v11, 0
	v_lshl_add_u64 v[6:7], s[6:7], 0, v[6:7]
	v_pk_mul_f32 v[2:3], v[2:3], v[8:9] op_sel_hi:[1,0]
	s_mov_b64 s[4:5], 0
	v_pk_mul_f32 v[4:5], v[4:5], v[8:9] op_sel_hi:[1,0]
	v_cvt_pk_bf16_f32 v2, v2, v3
	s_nop 0
	v_cvt_pk_bf16_f32 v3, v4, v5
	ds_write_b64 v119, v[2:3] offset:9056
	s_waitcnt lgkmcnt(0)
	s_barrier

; #define STAGE_TILE_F(XFORM) do { SW_BEGIN f32x4 v = acc[ai][bj][m][n2]; XFORM; \
;     *(u32x2*)(smem + mrow * SPITCH + nc0 * 2) = u32x2{cvtpk_t(v[0], v[1]), cvtpk_t(v[2], v[3])}; LOOP_END __syncthreads(); } while (0)
; template <int kind> __device__ __forceinline__ void gemm_phase_n(const Params& P, int layer, int b, const int wv) {
;     ...
;                 } else {
;                     STAGE_TILE_F(v *= rs_lds[mrow]);
;                     u16* base = sub == 0 ? (u16*)(ws + O_QN) : (pn < 8 ? (u16*)(ws + O_KN) : (u16*)(ws + O_V));
;                     const int hb = (pn & 7) * 2;
.LBB0_592:
	s_or_b64 exec, exec, s[2:3]
	v_mov_b32_e32 v0, v1
	v_cmp_gt_i32_e32 vcc, 8, v137
	v_mbcnt_lo_u32_b32 v0, -1, v0
	v_mbcnt_hi_u32_b32 v0, -1, v0
	v_or_b32_e32 v0, s57, v0
	s_xor_b64 s[2:3], s[4:5], -1
	v_bfe_u32 v131, v0, 6, 2
	v_and_b32_e32 v130, 15, v0
	v_ashrrev_i32_e32 v133, 8, v0
	v_bfe_u32 v146, v0, 4, 2
	v_lshlrev_b32_e32 v134, 8, v145
	s_or_b64 s[2:3], s[2:3], vcc
	v_lshl_or_b32 v135, v131, 5, v130
	s_and_saveexec_b64 s[16:17], s[2:3]
	s_xor_b64 s[2:3], exec, s[16:17]
	s_cbranch_execz .LBB0_595
	v_lshl_add_u32 v131, v135, 2, 0
	v_add_u32_e32 v131, 0x22000, v131
	ds_read_b32 v139, v131
	ds_read_b32 v140, v131 offset:64
	ds_read_b32 v141, v131 offset:512
	ds_read_b32 v142, v131 offset:576
	s_waitcnt lgkmcnt(0)
	v_mov_b32_e32 v132, v139
	v_lshlrev_b32_e32 v136, 7, v133
	v_lshl_add_u32 v138, v146, 3, 0
	v_cmp_gt_i32_e32 vcc, 8, v137
	v_pk_mul_f32 v[126:127], v[126:127], v[132:133] op_sel_hi:[1,0]
	v_pk_mul_f32 v[128:129], v[128:129], v[132:133] op_sel_hi:[1,0]
	v_cvt_pk_bf16_f32 v132, v126, v127
	v_mul_u32_u24_e32 v126, 0x220, v135
	v_add3_u32 v126, v138, v136, v126
	v_cvt_pk_bf16_f32 v133, v128, v129
	ds_write_b64 v126, v[132:133]
	v_mov_b32_e32 v128, v140
	v_ashrrev_i32_e32 v135, 31, v134
	v_pk_mul_f32 v[106:107], v[106:107], v[128:129] op_sel_hi:[1,0]
	v_pk_mul_f32 v[108:109], v[108:109], v[128:129] op_sel_hi:[1,0]
	v_cvt_pk_bf16_f32 v106, v106, v107
	s_nop 0
	v_cvt_pk_bf16_f32 v107, v108, v109
	ds_write_b64 v126, v[106:107] offset:8704
	v_mov_b32_e32 v108, v141
	v_add_u32_e32 v106, 0x2200, v126
	v_pk_mul_f32 v[82:83], v[82:83], v[108:109] op_sel_hi:[1,0]
	v_pk_mul_f32 v[84:85], v[84:85], v[108:109] op_sel_hi:[1,0]
	v_cvt_pk_bf16_f32 v82, v82, v83
	s_nop 0
	v_cvt_pk_bf16_f32 v83, v84, v85
	ds_write_b64 v106, v[82:83] offset:60928
	v_mov_b32_e32 v84, v142
	v_add_u32_e32 v82, 0xee00, v106
	v_pk_mul_f32 v[50:51], v[50:51], v[84:85] op_sel_hi:[1,0]
	v_pk_mul_f32 v[52:53], v[52:53], v[84:85] op_sel_hi:[1,0]
	v_cvt_pk_bf16_f32 v50, v50, v51
	s_nop 0
	v_cvt_pk_bf16_f32 v51, v52, v53
	ds_write_b64 v82, v[50:51] offset:8704
	s_waitcnt vmcnt(0)
	v_mov_b32_e32 v50, v139
	v_pk_mul_f32 v[52:53], v[120:121], v[50:51] op_sel_hi:[1,0]
	v_pk_mul_f32 v[50:51], v[118:119], v[50:51] op_sel_hi:[1,0]
	s_nop 0
	v_cvt_pk_bf16_f32 v50, v50, v51
	v_cvt_pk_bf16_f32 v51, v52, v53
	ds_write_b64 v126, v[50:51] offset:32
	v_mov_b32_e32 v50, v140
	v_pk_mul_f32 v[52:53], v[96:97], v[50:51] op_sel_hi:[1,0]
	v_pk_mul_f32 v[50:51], v[94:95], v[50:51] op_sel_hi:[1,0]
	s_nop 0
	v_cvt_pk_bf16_f32 v50, v50, v51
	v_cvt_pk_bf16_f32 v51, v52, v53
	ds_write_b64 v126, v[50:51] offset:8736
	v_mov_b32_e32 v50, v141
	v_pk_mul_f32 v[52:53], v[64:65], v[50:51] op_sel_hi:[1,0]
	v_pk_mul_f32 v[50:51], v[62:63], v[50:51] op_sel_hi:[1,0]
	s_nop 0
	v_cvt_pk_bf16_f32 v50, v50, v51
	v_cvt_pk_bf16_f32 v51, v52, v53
	ds_write_b64 v106, v[50:51] offset:60960
	v_mov_b32_e32 v50, v142
	v_pk_mul_f32 v[30:31], v[30:31], v[50:51] op_sel_hi:[1,0]
	v_pk_mul_f32 v[32:33], v[32:33], v[50:51] op_sel_hi:[1,0]
	v_cvt_pk_bf16_f32 v30, v30, v31
	s_nop 0
	v_cvt_pk_bf16_f32 v31, v32, v33
	ds_write_b64 v82, v[30:31] offset:8736
	v_mov_b32_e32 v30, v139
	v_pk_mul_f32 v[32:33], v[112:113], v[30:31] op_sel_hi:[1,0]
	v_pk_mul_f32 v[30:31], v[110:111], v[30:31] op_sel_hi:[1,0]
	s_nop 0
	v_cvt_pk_bf16_f32 v30, v30, v31
	v_cvt_pk_bf16_f32 v31, v32, v33
	ds_write_b64 v126, v[30:31] offset:64
	v_mov_b32_e32 v30, v140
	v_pk_mul_f32 v[32:33], v[88:89], v[30:31] op_sel_hi:[1,0]
	v_pk_mul_f32 v[30:31], v[86:87], v[30:31] op_sel_hi:[1,0]
	s_nop 0
	v_cvt_pk_bf16_f32 v30, v30, v31
	v_cvt_pk_bf16_f32 v31, v32, v33
	ds_write_b64 v126, v[30:31] offset:8768
	v_mov_b32_e32 v30, v141
	v_pk_mul_f32 v[32:33], v[56:57], v[30:31] op_sel_hi:[1,0]
	v_pk_mul_f32 v[30:31], v[54:55], v[30:31] op_sel_hi:[1,0]
	s_nop 0
	v_cvt_pk_bf16_f32 v30, v30, v31
	v_cvt_pk_bf16_f32 v31, v32, v33
	ds_write_b64 v106, v[30:31] offset:60992
	v_mov_b32_e32 v30, v142
	v_pk_mul_f32 v[22:23], v[22:23], v[30:31] op_sel_hi:[1,0]
	v_pk_mul_f32 v[24:25], v[24:25], v[30:31] op_sel_hi:[1,0]
	v_cvt_pk_bf16_f32 v22, v22, v23
	s_nop 0
	v_cvt_pk_bf16_f32 v23, v24, v25
	ds_write_b64 v82, v[22:23] offset:8768
	v_mov_b32_e32 v22, v139
	v_pk_mul_f32 v[24:25], v[104:105], v[22:23] op_sel_hi:[1,0]
	v_pk_mul_f32 v[22:23], v[102:103], v[22:23] op_sel_hi:[1,0]
	s_nop 0
	v_cvt_pk_bf16_f32 v22, v22, v23
	v_cvt_pk_bf16_f32 v23, v24, v25
	ds_write_b64 v126, v[22:23] offset:96
	v_mov_b32_e32 v22, v140
	v_pk_mul_f32 v[24:25], v[76:77], v[22:23] op_sel_hi:[1,0]
	v_pk_mul_f32 v[22:23], v[74:75], v[22:23] op_sel_hi:[1,0]
	s_nop 0
	v_cvt_pk_bf16_f32 v22, v22, v23
	v_cvt_pk_bf16_f32 v23, v24, v25
	ds_write_b64 v126, v[22:23] offset:8800
	v_mov_b32_e32 v22, v141
	v_pk_mul_f32 v[24:25], v[44:45], v[22:23] op_sel_hi:[1,0]
	v_pk_mul_f32 v[22:23], v[42:43], v[22:23] op_sel_hi:[1,0]
	s_nop 0
	v_cvt_pk_bf16_f32 v22, v22, v23
	v_cvt_pk_bf16_f32 v23, v24, v25
	ds_write_b64 v106, v[22:23] offset:61024
	v_mov_b32_e32 v22, v142
	v_pk_mul_f32 v[14:15], v[14:15], v[22:23] op_sel_hi:[1,0]
; #define STAGE_TILE_F(XFORM) do { SW_BEGIN f32x4 v = acc[ai][bj][m][n2]; XFORM; \
;     *(u32x2*)(smem + mrow * SPITCH + nc0 * 2) = u32x2{cvtpk_t(v[0], v[1]), cvtpk_t(v[2], v[3])}; LOOP_END __syncthreads(); } while (0)
; template <int kind> __device__ __forceinline__ void gemm_phase_n(const Params& P, int layer, int b, const int wv) {
;     ...
;                 } else {
;                     STAGE_TILE_F(v *= rs_lds[mrow]);
;                     u16* base = sub == 0 ? (u16*)(ws + O_QN) : (pn < 8 ? (u16*)(ws + O_KN) : (u16*)(ws + O_V));
;                     const int hb = (pn & 7) * 2;
;                     DRAIN_BEGIN const int h = hb + (chunk >> 4);
;                         *(u32x4*)(base + ((size_t)h * S + s0 + row) * 128 + (chunk & 15) * 8) = w; LOOP_END
	v_pk_mul_f32 v[16:17], v[16:17], v[22:23] op_sel_hi:[1,0]
	v_cvt_pk_bf16_f32 v14, v14, v15
	s_nop 0
	v_cvt_pk_bf16_f32 v15, v16, v17
	ds_write_b64 v82, v[14:15] offset:8800
	v_mov_b32_e32 v14, v139
	v_pk_mul_f32 v[16:17], v[124:125], v[14:15] op_sel_hi:[1,0]
	v_pk_mul_f32 v[14:15], v[122:123], v[14:15] op_sel_hi:[1,0]
	s_nop 0
	v_cvt_pk_bf16_f32 v14, v14, v15
	v_cvt_pk_bf16_f32 v15, v16, v17
	ds_write_b64 v126, v[14:15] offset:256
	v_mov_b32_e32 v14, v140
	v_pk_mul_f32 v[16:17], v[92:93], v[14:15] op_sel_hi:[1,0]
	v_pk_mul_f32 v[14:15], v[90:91], v[14:15] op_sel_hi:[1,0]
	s_nop 0
	v_cvt_pk_bf16_f32 v14, v14, v15
	v_cvt_pk_bf16_f32 v15, v16, v17
	ds_write_b64 v126, v[14:15] offset:8960
	v_mov_b32_e32 v14, v141
	v_pk_mul_f32 v[16:17], v[60:61], v[14:15] op_sel_hi:[1,0]
	v_pk_mul_f32 v[14:15], v[58:59], v[14:15] op_sel_hi:[1,0]
	s_nop 0
	v_cvt_pk_bf16_f32 v14, v14, v15
	v_cvt_pk_bf16_f32 v15, v16, v17
	ds_write_b64 v106, v[14:15] offset:61184
	v_mov_b32_e32 v14, v142
	v_pk_mul_f32 v[16:17], v[28:29], v[14:15] op_sel_hi:[1,0]
	v_pk_mul_f32 v[14:15], v[26:27], v[14:15] op_sel_hi:[1,0]
	s_nop 0
	v_cvt_pk_bf16_f32 v14, v14, v15
	v_cvt_pk_bf16_f32 v15, v16, v17
	ds_write_b64 v82, v[14:15] offset:8960
	v_mov_b32_e32 v14, v139
	v_pk_mul_f32 v[16:17], v[116:117], v[14:15] op_sel_hi:[1,0]
	v_pk_mul_f32 v[14:15], v[114:115], v[14:15] op_sel_hi:[1,0]
	s_nop 0
	v_cvt_pk_bf16_f32 v14, v14, v15
	v_cvt_pk_bf16_f32 v15, v16, v17
	ds_write_b64 v126, v[14:15] offset:288
	v_mov_b32_e32 v14, v140
	v_pk_mul_f32 v[16:17], v[80:81], v[14:15] op_sel_hi:[1,0]
	v_pk_mul_f32 v[14:15], v[78:79], v[14:15] op_sel_hi:[1,0]
	s_nop 0
	v_cvt_pk_bf16_f32 v14, v14, v15
	v_cvt_pk_bf16_f32 v15, v16, v17
	ds_write_b64 v126, v[14:15] offset:8992
	v_mov_b32_e32 v14, v141
	v_pk_mul_f32 v[16:17], v[48:49], v[14:15] op_sel_hi:[1,0]
	v_pk_mul_f32 v[14:15], v[46:47], v[14:15] op_sel_hi:[1,0]
	s_nop 0
	v_cvt_pk_bf16_f32 v14, v14, v15
	v_cvt_pk_bf16_f32 v15, v16, v17
	ds_write_b64 v106, v[14:15] offset:61216
	v_mov_b32_e32 v14, v142
	v_pk_mul_f32 v[16:17], v[20:21], v[14:15] op_sel_hi:[1,0]
	v_pk_mul_f32 v[14:15], v[18:19], v[14:15] op_sel_hi:[1,0]
	v_and_b32_e32 v18, 31, v0
	v_cvt_pk_bf16_f32 v14, v14, v15
	v_cvt_pk_bf16_f32 v15, v16, v17
	ds_write_b64 v82, v[14:15] offset:8992
	v_mov_b32_e32 v14, v139
	v_bfe_u32 v19, v0, 4, 1
	v_lshlrev_b32_e32 v18, 4, v18
	v_pk_mul_f32 v[16:17], v[100:101], v[14:15] op_sel_hi:[1,0]
	v_pk_mul_f32 v[14:15], v[98:99], v[14:15] op_sel_hi:[1,0]
	s_nop 0
	v_cvt_pk_bf16_f32 v14, v14, v15
	v_cvt_pk_bf16_f32 v15, v16, v17
	ds_write_b64 v126, v[14:15] offset:320
	v_mov_b32_e32 v14, v140
	v_pk_mul_f32 v[16:17], v[68:69], v[14:15] op_sel_hi:[1,0]
	v_pk_mul_f32 v[14:15], v[66:67], v[14:15] op_sel_hi:[1,0]
	s_nop 0
	v_cvt_pk_bf16_f32 v14, v14, v15
	v_cvt_pk_bf16_f32 v15, v16, v17
	ds_write_b64 v126, v[14:15] offset:9024
	v_mov_b32_e32 v14, v141
	v_pk_mul_f32 v[16:17], v[36:37], v[14:15] op_sel_hi:[1,0]
	v_pk_mul_f32 v[14:15], v[34:35], v[14:15] op_sel_hi:[1,0]
	s_nop 0
	v_cvt_pk_bf16_f32 v14, v14, v15
	v_cvt_pk_bf16_f32 v15, v16, v17
	ds_write_b64 v106, v[14:15] offset:61248
	v_mov_b32_e32 v14, v142
	v_mov_b32_e32 v15, 0x1d980000
	v_mov_b32_e32 v16, 0x1b980000
	v_cndmask_b32_e32 v15, v15, v16, vcc
	v_ashrrev_i32_e32 v16, 5, v0
	v_pk_mul_f32 v[6:7], v[6:7], v[14:15] op_sel_hi:[1,0]
	v_pk_mul_f32 v[8:9], v[8:9], v[14:15] op_sel_hi:[1,0]
	v_cvt_pk_bf16_f32 v6, v6, v7
	v_mov_b32_e32 v0, 0x18980000
	v_cvt_pk_bf16_f32 v7, v8, v9
	ds_write_b64 v82, v[6:7] offset:9024
	v_mov_b32_e32 v6, v139
	v_mov_b32_e32 v7, v1
	v_cndmask_b32_e64 v0, v15, v0, s[4:5]
	v_lshlrev_b32_e32 v17, 1, v137
	v_and_or_b32 v19, v17, 14, v19
	v_pk_mul_f32 v[14:15], v[70:71], v[6:7] op_sel_hi:[1,0]
	v_pk_mul_f32 v[8:9], v[72:73], v[6:7] op_sel_hi:[1,0]
	v_cvt_pk_bf16_f32 v14, v14, v15
	v_ashrrev_i32_e32 v17, 31, v16
	v_cvt_pk_bf16_f32 v15, v8, v9
	ds_write_b64 v126, v[14:15] offset:352
	v_mov_b32_e32 v6, v140
	s_movk_i32 s4, 0x220
	v_mul_lo_u32 v20, v16, s4
	v_add3_u32 v132, v20, v18, 0
	s_mov_b64 s[4:5], 0
	v_pk_mul_f32 v[14:15], v[38:39], v[6:7] op_sel_hi:[1,0]
	v_pk_mul_f32 v[8:9], v[40:41], v[6:7] op_sel_hi:[1,0]
	v_cvt_pk_bf16_f32 v14, v14, v15
	v_lshlrev_b32_e32 v6, 13, v19
	v_cvt_pk_bf16_f32 v15, v8, v9
	ds_write_b64 v126, v[14:15] offset:9056
	v_mov_b32_e32 v8, v141
	v_lshl_add_u64 v[14:15], v[16:17], 0, v[134:135]
	v_lshl_add_u64 v[6:7], v[14:15], 0, v[6:7]
	v_lshlrev_b64 v[6:7], 8, v[6:7]
	v_lshl_add_u64 v[6:7], v[0:1], 0, v[6:7]
	v_pk_mul_f32 v[12:13], v[12:13], v[8:9] op_sel_hi:[1,0]
	v_pk_mul_f32 v[8:9], v[10:11], v[8:9] op_sel_hi:[1,0]
	v_lshl_or_b32 v6, v130, 4, v6
	v_cvt_pk_bf16_f32 v8, v8, v9
	v_cvt_pk_bf16_f32 v9, v12, v13
	ds_write_b64 v106, v[8:9] offset:61280
	v_mov_b32_e32 v8, v142
	v_lshl_add_u64 v[130:131], s[6:7], 0, v[6:7]
	v_pk_mul_f32 v[2:3], v[2:3], v[8:9] op_sel_hi:[1,0]
	v_pk_mul_f32 v[4:5], v[4:5], v[8:9] op_sel_hi:[1,0]
	v_cvt_pk_bf16_f32 v2, v2, v3
	s_nop 0
	v_cvt_pk_bf16_f32 v3, v4, v5
	ds_write_b64 v82, v[2:3] offset:9056
	s_waitcnt lgkmcnt(0)
	s_barrier

; #define STAGE_TILE_F(XFORM) do { SW_BEGIN f32x4 v = acc[ai][bj][m][n2]; XFORM; \
;     *(u32x2*)(smem + mrow * SPITCH + nc0 * 2) = u32x2{cvtpk_t(v[0], v[1]), cvtpk_t(v[2], v[3])}; LOOP_END __syncthreads(); } while (0)
; template <int kind> __device__ __forceinline__ void gemm_phase_n(const Params& P, int layer, int b, const int wv) {
;     ...
;                 if (sub == 0) {
;                     STAGE_TILE_F(if (mrow < nc0) v[0] = 0.f; if (mrow < nc0 + 1) v[1] = 0.f; if (mrow < nc0 + 2) v[2] = 0.f; if (mrow < nc0 + 3) v[3] = 0.f);
;                     u16* dst = (u16*)(ws + O_AQ) + (size_t)pm * 256 * 512;
.LBB0_617:
	s_and_b64 vcc, exec, s[12:13]
	s_cbranch_vccz .LBB0_602
	v_lshlrev_b32_e32 v132, 6, v138
	v_lshl_or_b32 v133, v139, 2, v132
	v_or_b32_e32 v138, 2, v133
	v_mov_b32_e32 v132, s73
	v_cmp_lt_i32_e32 vcc, v137, v133
	v_or_b32_e32 v139, 3, v133
	v_cmp_gt_i32_e64 s[4:5], v137, v133
	v_cndmask_b32_e32 v132, v126, v132, vcc
	v_cmp_ge_i32_e64 s[6:7], v137, v138
	v_lshl_add_u32 v140, v133, 1, 0
	v_cndmask_b32_e64 v126, v132, v126, s[4:5]
	v_cndmask_b32_e64 v127, 0, v127, s[4:5]
	v_cndmask_b32_e64 v128, 0, v128, s[6:7]
	v_cmp_ge_i32_e64 s[6:7], v137, v139
	s_movk_i32 s9, 0x220
	v_cvt_pk_bf16_f32 v126, v126, v127
	v_cndmask_b32_e64 v103, 0, v103, s[4:5]
	v_cndmask_b32_e64 v129, 0, v129, s[6:7]
	v_cvt_pk_bf16_f32 v127, v128, v129
	v_mad_u32_u24 v128, v137, s9, v140
	ds_write_b64 v128, v[126:127]
	v_or_b32_e32 v126, 16, v137
	v_mov_b32_e32 v128, s73
	v_cmp_lt_i32_e64 s[6:7], v126, v133
	v_cndmask_b32_e64 v35, 0, v35, s[4:5]
	s_ashr_i32 s11, s10, 31
	v_cndmask_b32_e64 v127, v118, v128, s[6:7]
	v_cmp_gt_i32_e64 s[6:7], v126, v133
	s_nop 1
	v_cndmask_b32_e64 v118, v127, v118, s[6:7]
	v_cndmask_b32_e64 v119, 0, v119, s[6:7]
	v_cmp_ge_i32_e64 s[6:7], v126, v138
	v_cvt_pk_bf16_f32 v118, v118, v119
	s_nop 1
	v_cndmask_b32_e64 v120, 0, v120, s[6:7]
	v_cmp_ge_i32_e64 s[6:7], v126, v139
	s_nop 1
	v_cndmask_b32_e64 v121, 0, v121, s[6:7]
	v_cvt_pk_bf16_f32 v119, v120, v121
	v_mov_b32_e32 v120, 0x2200
	v_mad_u32_u24 v127, v137, s9, v120
	v_add_u32_e32 v120, v140, v127
	ds_write_b64 v120, v[118:119]
	v_or_b32_e32 v118, 0x80, v137
	v_mov_b32_e32 v120, s73
	v_cmp_lt_i32_e64 s[6:7], v118, v133
	s_nop 1
	v_cndmask_b32_e64 v119, v122, v120, s[6:7]
	v_cmp_gt_i32_e64 s[6:7], v118, v133
	s_nop 1
	v_cndmask_b32_e64 v119, v119, v122, s[6:7]
	v_cndmask_b32_e64 v120, 0, v123, s[6:7]
	v_cmp_ge_i32_e64 s[6:7], v118, v138
	v_cvt_pk_bf16_f32 v120, v119, v120
	v_add_u32_e32 v119, v140, v136
	s_nop 0
	v_cndmask_b32_e64 v121, 0, v124, s[6:7]
	v_cmp_ge_i32_e64 s[6:7], v118, v139
	s_nop 1
	v_cndmask_b32_e64 v122, 0, v125, s[6:7]
	v_cvt_pk_bf16_f32 v121, v121, v122
	ds_write_b64 v119, v[120:121]
	v_or_b32_e32 v119, 0x90, v137
	v_mov_b32_e32 v120, s73
	v_cmp_lt_i32_e64 s[6:7], v119, v133
	s_nop 1
	v_cndmask_b32_e64 v120, v114, v120, s[6:7]
	v_cmp_gt_i32_e64 s[6:7], v119, v133
	s_nop 1
	v_cndmask_b32_e64 v114, v120, v114, s[6:7]
	v_cndmask_b32_e64 v115, 0, v115, s[6:7]
	v_cmp_ge_i32_e64 s[6:7], v119, v138
	v_cvt_pk_bf16_f32 v114, v114, v115
	s_nop 1
	v_cndmask_b32_e64 v116, 0, v116, s[6:7]
	v_cmp_ge_i32_e64 s[6:7], v119, v139
	s_nop 1
	v_cndmask_b32_e64 v117, 0, v117, s[6:7]
	v_cvt_pk_bf16_f32 v115, v116, v117
	v_add_u32_e32 v116, v140, v135
	ds_write_b64 v116, v[114:115]
	v_or_b32_e32 v115, 16, v133
	v_mov_b32_e32 v114, s73
	v_cmp_lt_i32_e64 s[6:7], v137, v115
	v_or_b32_e32 v116, 18, v133
	v_or_b32_e32 v117, 19, v133
	v_cndmask_b32_e64 v114, v110, v114, s[6:7]
	v_cmp_gt_i32_e64 s[6:7], v137, v115
	v_lshl_add_u32 v120, v115, 1, 0
	s_nop 0
	v_cndmask_b32_e64 v110, v114, v110, s[6:7]
	v_cndmask_b32_e64 v111, 0, v111, s[6:7]
	v_cmp_ge_i32_e64 s[6:7], v137, v116
	v_cvt_pk_bf16_f32 v110, v110, v111
	s_nop 1
	v_cndmask_b32_e64 v112, 0, v112, s[6:7]
	v_cmp_ge_i32_e64 s[6:7], v137, v117
	s_nop 1
	v_cndmask_b32_e64 v113, 0, v113, s[6:7]
	v_cvt_pk_bf16_f32 v111, v112, v113
	v_mad_u32_u24 v112, v137, s9, v120
	ds_write_b64 v112, v[110:111]
	v_mov_b32_e32 v110, s73
	v_cndmask_b32_e32 v110, v102, v110, vcc
	v_cmp_ge_i32_e64 s[6:7], v126, v116
	v_cndmask_b32_e64 v102, v110, v102, s[4:5]
	v_cvt_pk_bf16_f32 v102, v102, v103
	s_nop 0
	v_cndmask_b32_e64 v104, 0, v104, s[6:7]
	v_cmp_ge_i32_e64 s[6:7], v126, v117
	s_nop 1
	v_cndmask_b32_e64 v105, 0, v105, s[6:7]
	v_cvt_pk_bf16_f32 v103, v104, v105
	v_add_u32_e32 v104, v120, v127
	ds_write_b64 v104, v[102:103]
	v_mov_b32_e32 v102, s73
	v_cmp_lt_i32_e64 s[6:7], v118, v115
	s_nop 1
	v_cndmask_b32_e64 v102, v106, v102, s[6:7]
	v_cmp_gt_i32_e64 s[6:7], v118, v115
	s_nop 1
	v_cndmask_b32_e64 v102, v102, v106, s[6:7]
	v_cndmask_b32_e64 v103, 0, v107, s[6:7]
	v_cmp_ge_i32_e64 s[6:7], v118, v116
	v_cvt_pk_bf16_f32 v102, v102, v103
	s_nop 1
	v_cndmask_b32_e64 v104, 0, v108, s[6:7]
	v_cmp_ge_i32_e64 s[6:7], v118, v117
	s_nop 1
	v_cndmask_b32_e64 v105, 0, v109, s[6:7]
	v_cvt_pk_bf16_f32 v103, v104, v105
	v_add_u32_e32 v104, v120, v136
	ds_write_b64 v104, v[102:103]
	v_mov_b32_e32 v102, s73
	v_cmp_lt_i32_e64 s[6:7], v119, v115
	s_nop 1
	v_cndmask_b32_e64 v102, v98, v102, s[6:7]
	v_cmp_gt_i32_e64 s[6:7], v119, v115
	s_nop 1
	v_cndmask_b32_e64 v98, v102, v98, s[6:7]
	v_cndmask_b32_e64 v99, 0, v99, s[6:7]
	v_cmp_ge_i32_e64 s[6:7], v119, v116
	v_cvt_pk_bf16_f32 v98, v98, v99
	s_nop 1
	v_cndmask_b32_e64 v100, 0, v100, s[6:7]
	v_cmp_ge_i32_e64 s[6:7], v119, v117
	s_nop 1
	v_cndmask_b32_e64 v101, 0, v101, s[6:7]
	v_cvt_pk_bf16_f32 v99, v100, v101
	v_add_u32_e32 v100, v120, v135
	ds_write_b64 v100, v[98:99]
	v_or_b32_e32 v99, 32, v133
	v_mov_b32_e32 v98, s73
	v_cmp_lt_i32_e64 s[6:7], v137, v99
	v_or_b32_e32 v100, 34, v133
	v_or_b32_e32 v101, 35, v133
	v_cndmask_b32_e64 v98, v94, v98, s[6:7]
	v_cmp_gt_i32_e64 s[6:7], v137, v99
	v_lshl_add_u32 v102, v99, 1, 0
	s_nop 0
	v_cndmask_b32_e64 v94, v98, v94, s[6:7]
	v_cndmask_b32_e64 v95, 0, v95, s[6:7]
	v_cmp_ge_i32_e64 s[6:7], v137, v100
	v_cvt_pk_bf16_f32 v94, v94, v95
	s_nop 1
	v_cndmask_b32_e64 v96, 0, v96, s[6:7]
	v_cmp_ge_i32_e64 s[6:7], v137, v101
	s_nop 1
	v_cndmask_b32_e64 v97, 0, v97, s[6:7]
	v_cvt_pk_bf16_f32 v95, v96, v97
	v_mad_u32_u24 v96, v137, s9, v102
	ds_write_b64 v96, v[94:95]
	v_mov_b32_e32 v94, s73
	v_cmp_lt_i32_e64 s[6:7], v126, v99
	s_nop 1
	v_cndmask_b32_e64 v94, v86, v94, s[6:7]
	v_cmp_gt_i32_e64 s[6:7], v126, v99
; #define STAGE_TILE_F(XFORM) do { SW_BEGIN f32x4 v = acc[ai][bj][m][n2]; XFORM; \
;     *(u32x2*)(smem + mrow * SPITCH + nc0 * 2) = u32x2{cvtpk_t(v[0], v[1]), cvtpk_t(v[2], v[3])}; LOOP_END __syncthreads(); } while (0)
; template <int kind> __device__ __forceinline__ void gemm_phase_n(const Params& P, int layer, int b, const int wv) {
;     ...
;                 if (sub == 0) {
;                     STAGE_TILE_F(if (mrow < nc0) v[0] = 0.f; if (mrow < nc0 + 1) v[1] = 0.f; if (mrow < nc0 + 2) v[2] = 0.f; if (mrow < nc0 + 3) v[3] = 0.f);
;                     u16* dst = (u16*)(ws + O_AQ) + (size_t)pm * 256 * 512;
	s_nop 1
	v_cndmask_b32_e64 v86, v94, v86, s[6:7]
	v_cndmask_b32_e64 v87, 0, v87, s[6:7]
	v_cmp_ge_i32_e64 s[6:7], v126, v100
	v_cvt_pk_bf16_f32 v86, v86, v87
	s_nop 1
	v_cndmask_b32_e64 v88, 0, v88, s[6:7]
	v_cmp_ge_i32_e64 s[6:7], v126, v101
	s_nop 1
	v_cndmask_b32_e64 v89, 0, v89, s[6:7]
	v_cvt_pk_bf16_f32 v87, v88, v89
	v_add_u32_e32 v88, v102, v127
	ds_write_b64 v88, v[86:87]
	v_mov_b32_e32 v86, s73
	v_cmp_lt_i32_e64 s[6:7], v118, v99
	s_nop 1
	v_cndmask_b32_e64 v86, v90, v86, s[6:7]
	v_cmp_gt_i32_e64 s[6:7], v118, v99
	s_nop 1
	v_cndmask_b32_e64 v86, v86, v90, s[6:7]
	v_cndmask_b32_e64 v87, 0, v91, s[6:7]
	v_cmp_ge_i32_e64 s[6:7], v118, v100
	v_cvt_pk_bf16_f32 v86, v86, v87
	s_nop 1
	v_cndmask_b32_e64 v88, 0, v92, s[6:7]
	v_cmp_ge_i32_e64 s[6:7], v118, v101
	s_nop 1
	v_cndmask_b32_e64 v89, 0, v93, s[6:7]
	v_cvt_pk_bf16_f32 v87, v88, v89
	v_add_u32_e32 v88, v102, v136
	ds_write_b64 v88, v[86:87]
	v_mov_b32_e32 v86, s73
	v_cmp_lt_i32_e64 s[6:7], v119, v99
	s_nop 1
	v_cndmask_b32_e64 v86, v82, v86, s[6:7]
	v_cmp_gt_i32_e64 s[6:7], v119, v99
	s_nop 1
	v_cndmask_b32_e64 v82, v86, v82, s[6:7]
	v_cndmask_b32_e64 v83, 0, v83, s[6:7]
	v_cmp_ge_i32_e64 s[6:7], v119, v100
	v_cvt_pk_bf16_f32 v82, v82, v83
	s_nop 1
	v_cndmask_b32_e64 v84, 0, v84, s[6:7]
	v_cmp_ge_i32_e64 s[6:7], v119, v101
	s_nop 1
	v_cndmask_b32_e64 v85, 0, v85, s[6:7]
	v_cvt_pk_bf16_f32 v83, v84, v85
	v_add_u32_e32 v84, v102, v135
	ds_write_b64 v84, v[82:83]
	v_or_b32_e32 v83, 48, v133
	v_mov_b32_e32 v82, s73
	v_cmp_lt_i32_e64 s[6:7], v137, v83
	v_or_b32_e32 v84, 50, v133
	v_or_b32_e32 v85, 51, v133
	v_cndmask_b32_e64 v82, v78, v82, s[6:7]
	v_cmp_gt_i32_e64 s[6:7], v137, v83
	v_lshl_add_u32 v86, v83, 1, 0
	s_nop 0
	v_cndmask_b32_e64 v78, v82, v78, s[6:7]
	v_cndmask_b32_e64 v79, 0, v79, s[6:7]
	v_cmp_ge_i32_e64 s[6:7], v137, v84
	v_cvt_pk_bf16_f32 v78, v78, v79
	s_nop 1
	v_cndmask_b32_e64 v80, 0, v80, s[6:7]
	v_cmp_ge_i32_e64 s[6:7], v137, v85
	s_nop 1
	v_cndmask_b32_e64 v81, 0, v81, s[6:7]
	v_cvt_pk_bf16_f32 v79, v80, v81
	v_mad_u32_u24 v80, v137, s9, v86
	ds_write_b64 v80, v[78:79]
	v_mov_b32_e32 v78, s73
	v_cmp_lt_i32_e64 s[6:7], v126, v83
	s_nop 1
	v_cndmask_b32_e64 v78, v70, v78, s[6:7]
	v_cmp_gt_i32_e64 s[6:7], v126, v83
	s_nop 1
	v_cndmask_b32_e64 v70, v78, v70, s[6:7]
	v_cndmask_b32_e64 v71, 0, v71, s[6:7]
	v_cmp_ge_i32_e64 s[6:7], v126, v84
	v_cvt_pk_bf16_f32 v70, v70, v71
	s_nop 1
	v_cndmask_b32_e64 v72, 0, v72, s[6:7]
	v_cmp_ge_i32_e64 s[6:7], v126, v85
	s_nop 1
	v_cndmask_b32_e64 v73, 0, v73, s[6:7]
	v_cvt_pk_bf16_f32 v71, v72, v73
	v_add_u32_e32 v72, v86, v127
	ds_write_b64 v72, v[70:71]
	v_mov_b32_e32 v70, s73
	v_cmp_lt_i32_e64 s[6:7], v118, v83
	s_nop 1
	v_cndmask_b32_e64 v70, v74, v70, s[6:7]
	v_cmp_gt_i32_e64 s[6:7], v118, v83
	s_nop 1
	v_cndmask_b32_e64 v70, v70, v74, s[6:7]
	v_cndmask_b32_e64 v71, 0, v75, s[6:7]
	v_cmp_ge_i32_e64 s[6:7], v118, v84
	v_cvt_pk_bf16_f32 v70, v70, v71
	s_nop 1
	v_cndmask_b32_e64 v72, 0, v76, s[6:7]
	v_cmp_ge_i32_e64 s[6:7], v118, v85
	s_nop 1
	v_cndmask_b32_e64 v73, 0, v77, s[6:7]
	v_cvt_pk_bf16_f32 v71, v72, v73
	v_add_u32_e32 v72, v86, v136
	ds_write_b64 v72, v[70:71]
	v_mov_b32_e32 v70, s73
	v_cmp_lt_i32_e64 s[6:7], v119, v83
	s_nop 1
	v_cndmask_b32_e64 v70, v66, v70, s[6:7]
	v_cmp_gt_i32_e64 s[6:7], v119, v83
	s_nop 1
	v_cndmask_b32_e64 v66, v70, v66, s[6:7]
	v_cndmask_b32_e64 v67, 0, v67, s[6:7]
	v_cmp_ge_i32_e64 s[6:7], v119, v84
	v_cvt_pk_bf16_f32 v66, v66, v67
	s_nop 1
	v_cndmask_b32_e64 v68, 0, v68, s[6:7]
	v_cmp_ge_i32_e64 s[6:7], v119, v85
	s_nop 1
	v_cndmask_b32_e64 v69, 0, v69, s[6:7]
	v_cvt_pk_bf16_f32 v67, v68, v69
	v_add_u32_e32 v68, v86, v135
	ds_write_b64 v68, v[66:67]
	v_add_u32_e32 v67, 0x80, v133
	v_mov_b32_e32 v66, s73
	v_cmp_lt_i32_e64 s[6:7], v137, v67
	v_add_u32_e32 v68, 0x82, v133
	v_add_u32_e32 v69, 0x83, v133
	v_cndmask_b32_e64 v66, v62, v66, s[6:7]
	v_cmp_gt_i32_e64 s[6:7], v137, v67
	v_lshl_add_u32 v70, v67, 1, 0
	s_nop 0
	v_cndmask_b32_e64 v62, v66, v62, s[6:7]
	v_cndmask_b32_e64 v63, 0, v63, s[6:7]
	v_cmp_ge_i32_e64 s[6:7], v137, v68
	v_cvt_pk_bf16_f32 v62, v62, v63
	s_nop 1
	v_cndmask_b32_e64 v64, 0, v64, s[6:7]
	v_cmp_ge_i32_e64 s[6:7], v137, v69
	s_nop 1
	v_cndmask_b32_e64 v65, 0, v65, s[6:7]
	v_cvt_pk_bf16_f32 v63, v64, v65
	v_mad_u32_u24 v64, v137, s9, v70
	ds_write_b64 v64, v[62:63]
	v_mov_b32_e32 v62, s73
	v_cmp_lt_i32_e64 s[6:7], v126, v67
	s_nop 1
	v_cndmask_b32_e64 v62, v54, v62, s[6:7]
	v_cmp_gt_i32_e64 s[6:7], v126, v67
	s_nop 1
	v_cndmask_b32_e64 v54, v62, v54, s[6:7]
	v_cndmask_b32_e64 v55, 0, v55, s[6:7]
	v_cmp_ge_i32_e64 s[6:7], v126, v68
	v_cvt_pk_bf16_f32 v54, v54, v55
	s_nop 1
	v_cndmask_b32_e64 v56, 0, v56, s[6:7]
	v_cmp_ge_i32_e64 s[6:7], v126, v69
	s_nop 1
	v_cndmask_b32_e64 v57, 0, v57, s[6:7]
	v_cvt_pk_bf16_f32 v55, v56, v57
	v_add_u32_e32 v56, v70, v127
	ds_write_b64 v56, v[54:55]
	v_mov_b32_e32 v54, s73
	v_cndmask_b32_e32 v54, v58, v54, vcc
	v_cmp_ge_i32_e64 s[6:7], v118, v68
	v_cndmask_b32_e64 v54, v54, v58, s[4:5]
	v_cndmask_b32_e64 v55, 0, v59, s[4:5]
	v_cndmask_b32_e64 v56, 0, v60, s[6:7]
	v_cmp_ge_i32_e64 s[6:7], v118, v69
	v_cvt_pk_bf16_f32 v54, v54, v55
	s_nop 1
	v_cndmask_b32_e64 v57, 0, v61, s[6:7]
	v_cvt_pk_bf16_f32 v55, v56, v57
	v_add_u32_e32 v56, v70, v136
	ds_write_b64 v56, v[54:55]
	v_mov_b32_e32 v54, s73
	v_cmp_lt_i32_e64 s[6:7], v119, v67
	s_nop 1
	v_cndmask_b32_e64 v54, v50, v54, s[6:7]
	v_cmp_gt_i32_e64 s[6:7], v119, v67
	s_nop 1
	v_cndmask_b32_e64 v50, v54, v50, s[6:7]
	v_cndmask_b32_e64 v51, 0, v51, s[6:7]
	v_cmp_ge_i32_e64 s[6:7], v119, v68
	v_cvt_pk_bf16_f32 v50, v50, v51
	s_nop 1
	v_cndmask_b32_e64 v52, 0, v52, s[6:7]
	v_cmp_ge_i32_e64 s[6:7], v119, v69
; #define STAGE_TILE_F(XFORM) do { SW_BEGIN f32x4 v = acc[ai][bj][m][n2]; XFORM; \
;     *(u32x2*)(smem + mrow * SPITCH + nc0 * 2) = u32x2{cvtpk_t(v[0], v[1]), cvtpk_t(v[2], v[3])}; LOOP_END __syncthreads(); } while (0)
; template <int kind> __device__ __forceinline__ void gemm_phase_n(const Params& P, int layer, int b, const int wv) {
;     ...
;                 if (sub == 0) {
;                     STAGE_TILE_F(if (mrow < nc0) v[0] = 0.f; if (mrow < nc0 + 1) v[1] = 0.f; if (mrow < nc0 + 2) v[2] = 0.f; if (mrow < nc0 + 3) v[3] = 0.f);
;                     u16* dst = (u16*)(ws + O_AQ) + (size_t)pm * 256 * 512;
;                     DRAIN_BEGIN *(u32x4*)(dst + (size_t)row * 512 + chunk * 8) = w; LOOP_END
	s_nop 1
	v_cndmask_b32_e64 v53, 0, v53, s[6:7]
	v_cvt_pk_bf16_f32 v51, v52, v53
	v_add_u32_e32 v52, v70, v135
	ds_write_b64 v52, v[50:51]
	v_add_u32_e32 v51, 0x90, v133
	v_mov_b32_e32 v50, s73
	v_cmp_lt_i32_e64 s[6:7], v137, v51
	v_add_u32_e32 v52, 0x92, v133
	v_add_u32_e32 v53, 0x93, v133
	v_cndmask_b32_e64 v50, v46, v50, s[6:7]
	v_cmp_gt_i32_e64 s[6:7], v137, v51
	v_lshl_add_u32 v54, v51, 1, 0
	s_nop 0
	v_cndmask_b32_e64 v46, v50, v46, s[6:7]
	v_cndmask_b32_e64 v47, 0, v47, s[6:7]
	v_cmp_ge_i32_e64 s[6:7], v137, v52
	v_cvt_pk_bf16_f32 v46, v46, v47
	s_nop 1
	v_cndmask_b32_e64 v48, 0, v48, s[6:7]
	v_cmp_ge_i32_e64 s[6:7], v137, v53
	s_nop 1
	v_cndmask_b32_e64 v49, 0, v49, s[6:7]
	v_cvt_pk_bf16_f32 v47, v48, v49
	v_mad_u32_u24 v48, v137, s9, v54
	ds_write_b64 v48, v[46:47]
	v_mov_b32_e32 v46, s73
	v_cmp_lt_i32_e64 s[6:7], v126, v51
	s_nop 1
	v_cndmask_b32_e64 v46, v42, v46, s[6:7]
	v_cmp_gt_i32_e64 s[6:7], v126, v51
	s_nop 1
	v_cndmask_b32_e64 v42, v46, v42, s[6:7]
	v_cndmask_b32_e64 v43, 0, v43, s[6:7]
	v_cmp_ge_i32_e64 s[6:7], v126, v52
	v_cvt_pk_bf16_f32 v42, v42, v43
	s_nop 1
	v_cndmask_b32_e64 v44, 0, v44, s[6:7]
	v_cmp_ge_i32_e64 s[6:7], v126, v53
	s_nop 1
	v_cndmask_b32_e64 v45, 0, v45, s[6:7]
	v_cvt_pk_bf16_f32 v43, v44, v45
	v_add_u32_e32 v44, v54, v127
	ds_write_b64 v44, v[42:43]
	v_mov_b32_e32 v42, s73
	v_cmp_lt_i32_e64 s[6:7], v118, v51
	s_nop 1
	v_cndmask_b32_e64 v42, v38, v42, s[6:7]
	v_cmp_gt_i32_e64 s[6:7], v118, v51
	s_nop 1
	v_cndmask_b32_e64 v38, v42, v38, s[6:7]
	v_cndmask_b32_e64 v39, 0, v39, s[6:7]
	v_cmp_ge_i32_e64 s[6:7], v118, v52
	v_cvt_pk_bf16_f32 v38, v38, v39
	s_nop 1
	v_cndmask_b32_e64 v40, 0, v40, s[6:7]
	v_cmp_ge_i32_e64 s[6:7], v118, v53
	s_nop 1
	v_cndmask_b32_e64 v41, 0, v41, s[6:7]
	v_cvt_pk_bf16_f32 v39, v40, v41
	v_add_u32_e32 v40, v54, v136
	ds_write_b64 v40, v[38:39]
	v_mov_b32_e32 v38, s73
	v_cndmask_b32_e32 v38, v34, v38, vcc
	v_cmp_ge_i32_e32 vcc, v119, v52
	v_cndmask_b32_e64 v34, v38, v34, s[4:5]
	v_cvt_pk_bf16_f32 v34, v34, v35
	s_lshl_b64 s[4:5], s[10:11], 18
	v_cndmask_b32_e32 v36, 0, v36, vcc
	v_cmp_ge_i32_e32 vcc, v119, v53
	s_nop 1
	v_cndmask_b32_e32 v37, 0, v37, vcc
	v_cvt_pk_bf16_f32 v35, v36, v37
	v_add_u32_e32 v36, v54, v135
	ds_write_b64 v36, v[34:35]
	v_add_u32_e32 v35, 0xa0, v133
	v_mov_b32_e32 v34, s73
	v_cmp_lt_i32_e32 vcc, v137, v35
	v_add_u32_e32 v36, 0xa2, v133
	v_add_u32_e32 v37, 0xa3, v133
	v_cndmask_b32_e32 v34, v30, v34, vcc
	v_cmp_gt_i32_e32 vcc, v137, v35
	v_lshl_add_u32 v38, v35, 1, 0
	s_nop 0
	v_cndmask_b32_e32 v30, v34, v30, vcc
	v_cndmask_b32_e32 v31, 0, v31, vcc
	v_cmp_ge_i32_e32 vcc, v137, v36
	v_cvt_pk_bf16_f32 v30, v30, v31
	s_nop 1
	v_cndmask_b32_e32 v32, 0, v32, vcc
	v_cmp_ge_i32_e32 vcc, v137, v37
	s_nop 1
	v_cndmask_b32_e32 v33, 0, v33, vcc
	v_cvt_pk_bf16_f32 v31, v32, v33
	v_mad_u32_u24 v32, v137, s9, v38
	ds_write_b64 v32, v[30:31]
	v_mov_b32_e32 v30, s73
	v_cmp_lt_i32_e32 vcc, v126, v35
	s_nop 1
	v_cndmask_b32_e32 v30, v26, v30, vcc
	v_cmp_gt_i32_e32 vcc, v126, v35
	s_nop 1
	v_cndmask_b32_e32 v26, v30, v26, vcc
	v_cndmask_b32_e32 v27, 0, v27, vcc
	v_cmp_ge_i32_e32 vcc, v126, v36
	v_cvt_pk_bf16_f32 v26, v26, v27
	s_nop 1
	v_cndmask_b32_e32 v28, 0, v28, vcc
	v_cmp_ge_i32_e32 vcc, v126, v37
	s_nop 1
	v_cndmask_b32_e32 v29, 0, v29, vcc
	v_cvt_pk_bf16_f32 v27, v28, v29
	v_add_u32_e32 v28, v38, v127
	ds_write_b64 v28, v[26:27]
	v_mov_b32_e32 v26, s73
	v_cmp_lt_i32_e32 vcc, v118, v35
	s_nop 1
	v_cndmask_b32_e32 v26, v22, v26, vcc
	v_cmp_gt_i32_e32 vcc, v118, v35
	s_nop 1
	v_cndmask_b32_e32 v22, v26, v22, vcc
	v_cndmask_b32_e32 v23, 0, v23, vcc
	v_cmp_ge_i32_e32 vcc, v118, v36
	v_cvt_pk_bf16_f32 v22, v22, v23
	s_nop 1
	v_cndmask_b32_e32 v24, 0, v24, vcc
	v_cmp_ge_i32_e32 vcc, v118, v37
	s_nop 1
	v_cndmask_b32_e32 v25, 0, v25, vcc
	v_cvt_pk_bf16_f32 v23, v24, v25
	v_add_u32_e32 v24, v38, v136
	ds_write_b64 v24, v[22:23]
	v_mov_b32_e32 v22, s73
	v_cmp_lt_i32_e32 vcc, v119, v35
	s_nop 1
	v_cndmask_b32_e32 v22, v18, v22, vcc
	v_cmp_gt_i32_e32 vcc, v119, v35
	s_nop 1
	v_cndmask_b32_e32 v18, v22, v18, vcc
	v_cndmask_b32_e32 v19, 0, v19, vcc
	v_cmp_ge_i32_e32 vcc, v119, v36
	v_cvt_pk_bf16_f32 v18, v18, v19
	s_nop 1
	v_cndmask_b32_e32 v20, 0, v20, vcc
	v_cmp_ge_i32_e32 vcc, v119, v37
	s_nop 1
	v_cndmask_b32_e32 v21, 0, v21, vcc
	v_cvt_pk_bf16_f32 v19, v20, v21
	v_add_u32_e32 v20, v38, v135
	ds_write_b64 v20, v[18:19]
	v_add_u32_e32 v19, 0xb0, v133
	v_mov_b32_e32 v18, s73
	v_cmp_lt_i32_e32 vcc, v137, v19
	v_add_u32_e32 v20, 0xb2, v133
	v_add_u32_e32 v21, 0xb3, v133
	v_cndmask_b32_e32 v18, v14, v18, vcc
	v_cmp_gt_i32_e32 vcc, v137, v19
	v_lshl_add_u32 v22, v19, 1, 0
	s_nop 0
	v_cndmask_b32_e32 v14, v18, v14, vcc
	v_cndmask_b32_e32 v15, 0, v15, vcc
	v_cmp_ge_i32_e32 vcc, v137, v20
	v_cvt_pk_bf16_f32 v14, v14, v15
	s_nop 1
	v_cndmask_b32_e32 v16, 0, v16, vcc
	v_cmp_ge_i32_e32 vcc, v137, v21
	s_nop 1
	v_cndmask_b32_e32 v17, 0, v17, vcc
	v_cvt_pk_bf16_f32 v15, v16, v17
	v_mad_u32_u24 v16, v137, s9, v22
	ds_write_b64 v16, v[14:15]
	v_mov_b32_e32 v14, s73
	v_cmp_lt_i32_e32 vcc, v126, v19
	s_nop 1
	v_cndmask_b32_e32 v14, v10, v14, vcc
	v_cmp_gt_i32_e32 vcc, v126, v19
	s_nop 1
	v_cndmask_b32_e32 v10, v14, v10, vcc
	v_cndmask_b32_e32 v11, 0, v11, vcc
	v_cmp_ge_i32_e32 vcc, v126, v20
	v_cvt_pk_bf16_f32 v10, v10, v11
	s_nop 1
	v_cndmask_b32_e32 v12, 0, v12, vcc
	v_cmp_ge_i32_e32 vcc, v126, v21
	s_nop 1
	v_cndmask_b32_e32 v13, 0, v13, vcc
	v_cvt_pk_bf16_f32 v11, v12, v13
	v_add_u32_e32 v12, v22, v127
	ds_write_b64 v12, v[10:11]
	v_mov_b32_e32 v10, s73
	v_cmp_lt_i32_e32 vcc, v118, v19
	s_nop 1
	v_cndmask_b32_e32 v10, v6, v10, vcc
	v_cmp_gt_i32_e32 vcc, v118, v19
	s_nop 1
	v_cndmask_b32_e32 v6, v10, v6, vcc
	v_cndmask_b32_e32 v7, 0, v7, vcc
	v_cmp_ge_i32_e32 vcc, v118, v20
	v_cvt_pk_bf16_f32 v6, v6, v7
	s_nop 1
	v_cndmask_b32_e32 v8, 0, v8, vcc
	v_cmp_ge_i32_e32 vcc, v118, v21
	s_nop 1
	v_cndmask_b32_e32 v9, 0, v9, vcc
	v_cvt_pk_bf16_f32 v7, v8, v9
	v_add_u32_e32 v8, v22, v136
	ds_write_b64 v8, v[6:7]
	v_mov_b32_e32 v6, s73
	v_cmp_lt_i32_e32 vcc, v119, v19
	s_nop 1
	v_cndmask_b32_e32 v6, v2, v6, vcc
	v_cmp_gt_i32_e32 vcc, v119, v19
	s_nop 1
	v_cndmask_b32_e32 v2, v6, v2, vcc
	v_cndmask_b32_e32 v3, 0, v3, vcc
	v_cmp_ge_i32_e32 vcc, v119, v20
	v_cvt_pk_bf16_f32 v2, v2, v3
	s_nop 1
	v_cndmask_b32_e32 v4, 0, v4, vcc
	v_cmp_ge_i32_e32 vcc, v119, v21
	s_nop 1
	v_cndmask_b32_e32 v5, 0, v5, vcc
	v_cvt_pk_bf16_f32 v3, v4, v5
	v_add_u32_e32 v4, v22, v135
	ds_write_b64 v4, v[2:3]
	v_lshlrev_b64 v[2:3], 10, v[130:131]
	v_lshl_add_u64 v[2:3], s[4:5], 0, v[2:3]
	v_or_b32_e32 v2, v2, v0
	v_lshl_add_u64 v[2:3], s[2:3], 0, v[2:3]
	v_add3_u32 v0, v134, v0, 0
	s_mov_b64 s[4:5], 0
	s_waitcnt vmcnt(0) lgkmcnt(0)
	s_barrier

; __device__ __forceinline__ float sigmf(float x) { return __builtin_amdgcn_rcpf(1.f + __expf(-x)); }
; #define STAGE_TILE_F(XFORM) do { SW_BEGIN f32x4 v = acc[ai][bj][m][n2]; XFORM; \
;     *(u32x2*)(smem + mrow * SPITCH + nc0 * 2) = u32x2{cvtpk_t(v[0], v[1]), cvtpk_t(v[2], v[3])}; LOOP_END __syncthreads(); } while (0)
; template <int kind> __device__ __forceinline__ void gemm_phase_n(const Params& P, int layer, int b, const int wv) {
;     ...
;                 float* out = P.out; const u16* x1b = (const u16*)(ws + O_XBB);
;                 u16* xb = (u16*)(ws + O_XBA); float* rowss = (float*)(ws + O_ROWSS);
;                 STAGE_TILE_F(v[0] = sigmf(v[0]); v[1] = sigmf(v[1]); v[2] = sigmf(v[2]); v[3] = sigmf(v[3]));
.LBB0_639:
	v_mul_f32_e32 v3, 0xbfb8aa3b, v122
	v_mul_f32_e32 v132, 0xbfb8aa3b, v123
	v_exp_f32_e32 v3, v3
	v_exp_f32_e32 v132, v132
	v_mul_f32_e32 v133, 0xbfb8aa3b, v117
	v_exp_f32_e32 v133, v133
	v_mul_f32_e32 v0, 0xbfb8aa3b, v120
	v_mul_f32_e32 v2, 0xbfb8aa3b, v121
	v_exp_f32_e32 v0, v0
	v_exp_f32_e32 v2, v2
	v_add_f32_e32 v3, 1.0, v3
	v_add_f32_e32 v132, 1.0, v132
	v_rcp_f32_e32 v3, v3
	v_rcp_f32_e32 v132, v132
	s_nop 0
	v_cvt_pk_bf16_f32 v3, v3, v132
	v_add_f32_e32 v132, 1.0, v133
	v_mul_f32_e32 v133, 0xbfb8aa3b, v118
	v_mul_f32_e32 v134, 0xbfb8aa3b, v119
	v_exp_f32_e32 v133, v133
	v_exp_f32_e32 v134, v134
	v_add_f32_e32 v0, 1.0, v0
	v_add_f32_e32 v2, 1.0, v2
	v_mul_f32_e32 v135, 0xbfb8aa3b, v129
	v_rcp_f32_e32 v0, v0
	v_rcp_f32_e32 v2, v2
	v_exp_f32_e32 v135, v135
	v_cvt_pk_bf16_f32 v2, v0, v2
	v_mul_f32_e32 v0, 0xbfb8aa3b, v116
	v_exp_f32_e32 v0, v0
	v_add_f32_e32 v133, 1.0, v133
	v_add_f32_e32 v134, 1.0, v134
	v_rcp_f32_e32 v133, v133
	v_rcp_f32_e32 v134, v134
	s_nop 0
	v_cvt_pk_bf16_f32 v133, v133, v134
	v_add_f32_e32 v134, 1.0, v135
	v_mul_f32_e32 v135, 0xbfb8aa3b, v130
	v_mul_f32_e32 v136, 0xbfb8aa3b, v131
	v_exp_f32_e32 v135, v135
	v_exp_f32_e32 v136, v136
	v_add_f32_e32 v0, 1.0, v0
	v_mul_f32_e32 v137, 0xbfb8aa3b, v125
	v_rcp_f32_e32 v0, v0
	v_rcp_f32_e32 v132, v132
	v_exp_f32_e32 v137, v137
	v_cvt_pk_bf16_f32 v132, v0, v132
	v_mul_f32_e32 v0, 0xbfb8aa3b, v128
	v_exp_f32_e32 v0, v0
	v_add_f32_e32 v135, 1.0, v135
	v_add_f32_e32 v136, 1.0, v136
	v_rcp_f32_e32 v135, v135
	v_rcp_f32_e32 v136, v136
	s_nop 0
	v_cvt_pk_bf16_f32 v135, v135, v136
	v_add_f32_e32 v136, 1.0, v137
	v_mul_f32_e32 v137, 0xbfb8aa3b, v126
	v_exp_f32_e32 v137, v137
	v_mul_f32_e32 v138, 0xbfb8aa3b, v127
	v_add_f32_e32 v0, 1.0, v0
	v_exp_f32_e32 v138, v138
	v_rcp_f32_e32 v0, v0
	v_rcp_f32_e32 v134, v134
	s_nop 0
	v_cvt_pk_bf16_f32 v134, v0, v134
	v_mul_f32_e32 v0, 0xbfb8aa3b, v124
	v_exp_f32_e32 v0, v0
	v_add_f32_e32 v137, 1.0, v137
	v_rcp_f32_e32 v137, v137
	v_add_f32_e32 v138, 1.0, v138
	v_add_u32_e32 v139, v159, v156
	v_rcp_f32_e32 v138, v138
	ds_write_b64 v139, v[134:135]
	v_cvt_pk_bf16_f32 v135, v137, v138
	v_mul_f32_e32 v137, 0xbfb8aa3b, v105
	v_exp_f32_e32 v137, v137
	v_add_f32_e32 v0, 1.0, v0
	v_rcp_f32_e32 v136, v136
	v_rcp_f32_e32 v0, v0
	s_nop 0
	v_cvt_pk_bf16_f32 v134, v0, v136
	v_mul_f32_e32 v136, 0xbfb8aa3b, v104
	v_add_u32_e32 v0, v159, v155
	v_exp_f32_e32 v136, v136
	ds_write_b64 v0, v[134:135]
	v_add_f32_e32 v134, 1.0, v137
	v_mul_f32_e32 v137, 0xbfb8aa3b, v100
	v_mul_f32_e32 v138, 0xbfb8aa3b, v101
	v_exp_f32_e32 v137, v137
	v_exp_f32_e32 v138, v138
	v_add_f32_e32 v0, 1.0, v136
	v_rcp_f32_e32 v0, v0
	v_mul_f32_e32 v135, 0xbfb8aa3b, v106
	v_rcp_f32_e32 v134, v134
	v_exp_f32_e32 v135, v135
	v_mul_f32_e32 v136, 0xbfb8aa3b, v107
	v_cvt_pk_bf16_f32 v134, v0, v134
	v_add_f32_e32 v0, 1.0, v137
	v_add_f32_e32 v137, 1.0, v138
	v_mul_f32_e32 v138, 0xbfb8aa3b, v102
	v_mul_f32_e32 v139, 0xbfb8aa3b, v103
	v_exp_f32_e32 v136, v136
	v_exp_f32_e32 v138, v138
	v_exp_f32_e32 v139, v139
	v_add_f32_e32 v135, 1.0, v135
	v_rcp_f32_e32 v135, v135
	v_add_f32_e32 v136, 1.0, v136
	v_rcp_f32_e32 v0, v0
	v_add_f32_e32 v138, 1.0, v138
	v_add_f32_e32 v139, 1.0, v139
	v_rcp_f32_e32 v136, v136
	v_rcp_f32_e32 v137, v137
	v_rcp_f32_e32 v138, v138
	v_rcp_f32_e32 v139, v139
	v_cvt_pk_bf16_f32 v135, v135, v136
	ds_write2_b64 v158, v[2:3], v[134:135] offset1:4
	v_cvt_pk_bf16_f32 v2, v0, v137
	v_cvt_pk_bf16_f32 v3, v138, v139
	v_mul_f32_e32 v0, 0xbfb8aa3b, v112
	v_mul_f32_e32 v134, 0xbfb8aa3b, v113
	v_exp_f32_e32 v0, v0
	v_exp_f32_e32 v134, v134
	ds_write2_b64 v157, v[132:133], v[2:3] offset0:64 offset1:68
	v_mul_f32_e32 v3, 0xbfb8aa3b, v114
	v_mul_f32_e32 v132, 0xbfb8aa3b, v115
	v_exp_f32_e32 v3, v3
	v_exp_f32_e32 v132, v132
	v_mul_f32_e32 v133, 0xbfb8aa3b, v109
	v_exp_f32_e32 v133, v133
	v_add_f32_e32 v0, 1.0, v0
	v_add_f32_e32 v2, 1.0, v134
	v_rcp_f32_e32 v0, v0
	v_rcp_f32_e32 v2, v2
	v_add_f32_e32 v3, 1.0, v3
	v_add_f32_e32 v132, 1.0, v132
	v_rcp_f32_e32 v3, v3
	v_rcp_f32_e32 v132, v132
	v_cvt_pk_bf16_f32 v2, v0, v2
	v_mul_f32_e32 v0, 0xbfb8aa3b, v108
	v_exp_f32_e32 v0, v0
	v_cvt_pk_bf16_f32 v3, v3, v132
	v_add_f32_e32 v132, 1.0, v133
	v_mul_f32_e32 v133, 0xbfb8aa3b, v110
	v_exp_f32_e32 v133, v133
	v_mul_f32_e32 v134, 0xbfb8aa3b, v111
	v_exp_f32_e32 v134, v134
	v_add_f32_e32 v0, 1.0, v0
	v_rcp_f32_e32 v132, v132
	v_add_u32_e32 v135, v165, v156
	v_rcp_f32_e32 v0, v0
	v_add_f32_e32 v133, 1.0, v133
	ds_write_b64 v135, v[2:3]
	v_cvt_pk_bf16_f32 v2, v0, v132
	v_mul_f32_e32 v132, 0xbfb8aa3b, v88
	v_rcp_f32_e32 v133, v133
	v_add_f32_e32 v134, 1.0, v134
	v_exp_f32_e32 v132, v132
	v_rcp_f32_e32 v134, v134
	s_nop 0
	v_cvt_pk_bf16_f32 v3, v133, v134
	v_mul_f32_e32 v133, 0xbfb8aa3b, v89
	v_exp_f32_e32 v133, v133
	v_add_u32_e32 v0, v165, v155
	ds_write_b64 v0, v[2:3]
	v_add_f32_e32 v0, 1.0, v132
	v_mul_f32_e32 v3, 0xbfb8aa3b, v90
	v_mul_f32_e32 v132, 0xbfb8aa3b, v91
	v_exp_f32_e32 v3, v3
	v_exp_f32_e32 v132, v132
	v_add_f32_e32 v2, 1.0, v133
	v_mul_f32_e32 v133, 0xbfb8aa3b, v85
	v_exp_f32_e32 v133, v133
	v_add_f32_e32 v3, 1.0, v3
	v_add_f32_e32 v132, 1.0, v132
	v_rcp_f32_e32 v3, v3
	v_rcp_f32_e32 v132, v132
	s_nop 0
	v_cvt_pk_bf16_f32 v3, v3, v132
	v_add_f32_e32 v132, 1.0, v133
	v_mul_f32_e32 v133, 0xbfb8aa3b, v86
	v_mul_f32_e32 v134, 0xbfb8aa3b, v87
	v_exp_f32_e32 v133, v133
	v_exp_f32_e32 v134, v134
	v_mul_f32_e32 v135, 0xbfb8aa3b, v97
	v_rcp_f32_e32 v0, v0
	v_rcp_f32_e32 v2, v2
	v_exp_f32_e32 v135, v135
	v_cvt_pk_bf16_f32 v2, v0, v2
	v_mul_f32_e32 v0, 0xbfb8aa3b, v84
	v_exp_f32_e32 v0, v0
	v_add_f32_e32 v133, 1.0, v133
	v_add_f32_e32 v134, 1.0, v134
	v_rcp_f32_e32 v133, v133
; __device__ __forceinline__ float sigmf(float x) { return __builtin_amdgcn_rcpf(1.f + __expf(-x)); }
; #define STAGE_TILE_F(XFORM) do { SW_BEGIN f32x4 v = acc[ai][bj][m][n2]; XFORM; \
;     *(u32x2*)(smem + mrow * SPITCH + nc0 * 2) = u32x2{cvtpk_t(v[0], v[1]), cvtpk_t(v[2], v[3])}; LOOP_END __syncthreads(); } while (0)
; template <int kind> __device__ __forceinline__ void gemm_phase_n(const Params& P, int layer, int b, const int wv) {
;     ...
;                 float* out = P.out; const u16* x1b = (const u16*)(ws + O_XBB);
;                 u16* xb = (u16*)(ws + O_XBA); float* rowss = (float*)(ws + O_ROWSS);
;                 STAGE_TILE_F(v[0] = sigmf(v[0]); v[1] = sigmf(v[1]); v[2] = sigmf(v[2]); v[3] = sigmf(v[3]));
	v_rcp_f32_e32 v134, v134
	s_nop 0
	v_cvt_pk_bf16_f32 v133, v133, v134
	v_add_f32_e32 v134, 1.0, v135
	v_mul_f32_e32 v135, 0xbfb8aa3b, v98
	v_mul_f32_e32 v136, 0xbfb8aa3b, v99
	v_exp_f32_e32 v135, v135
	v_exp_f32_e32 v136, v136
	v_add_f32_e32 v0, 1.0, v0
	v_mul_f32_e32 v137, 0xbfb8aa3b, v93
	v_rcp_f32_e32 v0, v0
	v_rcp_f32_e32 v132, v132
	v_exp_f32_e32 v137, v137
	v_cvt_pk_bf16_f32 v132, v0, v132
	v_mul_f32_e32 v0, 0xbfb8aa3b, v96
	v_exp_f32_e32 v0, v0
	v_add_f32_e32 v135, 1.0, v135
	v_add_f32_e32 v136, 1.0, v136
	v_rcp_f32_e32 v135, v135
	v_rcp_f32_e32 v136, v136
	s_nop 0
	v_cvt_pk_bf16_f32 v135, v135, v136
	v_add_f32_e32 v136, 1.0, v137
	v_mul_f32_e32 v137, 0xbfb8aa3b, v94
	v_exp_f32_e32 v137, v137
	v_mul_f32_e32 v138, 0xbfb8aa3b, v95
	v_add_f32_e32 v0, 1.0, v0
	v_exp_f32_e32 v138, v138
	v_rcp_f32_e32 v0, v0
	v_rcp_f32_e32 v134, v134
	s_nop 0
	v_cvt_pk_bf16_f32 v134, v0, v134
	v_mul_f32_e32 v0, 0xbfb8aa3b, v92
	v_exp_f32_e32 v0, v0
	v_add_f32_e32 v137, 1.0, v137
	v_rcp_f32_e32 v137, v137
	v_add_f32_e32 v138, 1.0, v138
	v_add_u32_e32 v139, v164, v156
	v_rcp_f32_e32 v138, v138
	ds_write_b64 v139, v[134:135]
	v_cvt_pk_bf16_f32 v135, v137, v138
	v_mul_f32_e32 v137, 0xbfb8aa3b, v57
	v_exp_f32_e32 v137, v137
	v_add_f32_e32 v0, 1.0, v0
	v_rcp_f32_e32 v136, v136
	v_rcp_f32_e32 v0, v0
	s_nop 0
	v_cvt_pk_bf16_f32 v134, v0, v136
	v_mul_f32_e32 v136, 0xbfb8aa3b, v56
	v_add_u32_e32 v0, v164, v155
	v_exp_f32_e32 v136, v136
	ds_write_b64 v0, v[134:135]
	v_add_f32_e32 v134, 1.0, v137
	v_mul_f32_e32 v137, 0xbfb8aa3b, v52
	v_mul_f32_e32 v138, 0xbfb8aa3b, v53
	v_exp_f32_e32 v137, v137
	v_exp_f32_e32 v138, v138
	v_add_f32_e32 v0, 1.0, v136
	v_rcp_f32_e32 v0, v0
	v_mul_f32_e32 v135, 0xbfb8aa3b, v58
	v_rcp_f32_e32 v134, v134
	v_exp_f32_e32 v135, v135
	v_mul_f32_e32 v136, 0xbfb8aa3b, v59
	v_cvt_pk_bf16_f32 v134, v0, v134
	v_add_f32_e32 v0, 1.0, v137
	v_add_f32_e32 v137, 1.0, v138
	v_mul_f32_e32 v138, 0xbfb8aa3b, v54
	v_mul_f32_e32 v139, 0xbfb8aa3b, v55
	v_exp_f32_e32 v136, v136
	v_exp_f32_e32 v138, v138
	v_exp_f32_e32 v139, v139
	v_add_f32_e32 v135, 1.0, v135
	v_rcp_f32_e32 v135, v135
	v_add_f32_e32 v136, 1.0, v136
	v_rcp_f32_e32 v0, v0
	v_add_f32_e32 v138, 1.0, v138
	v_add_f32_e32 v139, 1.0, v139
	v_rcp_f32_e32 v136, v136
	v_rcp_f32_e32 v137, v137
	v_rcp_f32_e32 v138, v138
	v_rcp_f32_e32 v139, v139
	v_cvt_pk_bf16_f32 v135, v135, v136
	ds_write2_b64 v158, v[2:3], v[134:135] offset0:8 offset1:12
	v_cvt_pk_bf16_f32 v2, v0, v137
	v_cvt_pk_bf16_f32 v3, v138, v139
	v_mul_f32_e32 v0, 0xbfb8aa3b, v80
	v_mul_f32_e32 v134, 0xbfb8aa3b, v81
	v_exp_f32_e32 v0, v0
	v_exp_f32_e32 v134, v134
	ds_write2_b64 v157, v[132:133], v[2:3] offset0:72 offset1:76
	v_mul_f32_e32 v3, 0xbfb8aa3b, v82
	v_mul_f32_e32 v132, 0xbfb8aa3b, v83
	v_exp_f32_e32 v3, v3
	v_exp_f32_e32 v132, v132
	v_mul_f32_e32 v133, 0xbfb8aa3b, v69
	v_exp_f32_e32 v133, v133
	v_add_f32_e32 v0, 1.0, v0
	v_add_f32_e32 v2, 1.0, v134
	v_rcp_f32_e32 v0, v0
	v_rcp_f32_e32 v2, v2
	v_add_f32_e32 v3, 1.0, v3
	v_add_f32_e32 v132, 1.0, v132
	v_rcp_f32_e32 v3, v3
	v_rcp_f32_e32 v132, v132
	v_cvt_pk_bf16_f32 v2, v0, v2
	v_mul_f32_e32 v0, 0xbfb8aa3b, v68
	v_exp_f32_e32 v0, v0
	v_cvt_pk_bf16_f32 v3, v3, v132
	v_add_f32_e32 v132, 1.0, v133
	v_mul_f32_e32 v133, 0xbfb8aa3b, v70
	v_exp_f32_e32 v133, v133
	v_mul_f32_e32 v134, 0xbfb8aa3b, v71
	v_exp_f32_e32 v134, v134
	v_add_f32_e32 v0, 1.0, v0
	v_rcp_f32_e32 v132, v132
	v_add_u32_e32 v135, v163, v156
	v_rcp_f32_e32 v0, v0
	v_add_f32_e32 v133, 1.0, v133
	ds_write_b64 v135, v[2:3]
	v_cvt_pk_bf16_f32 v2, v0, v132
	v_mul_f32_e32 v132, 0xbfb8aa3b, v72
	v_rcp_f32_e32 v133, v133
	v_add_f32_e32 v134, 1.0, v134
	v_exp_f32_e32 v132, v132
	v_rcp_f32_e32 v134, v134
	s_nop 0
	v_cvt_pk_bf16_f32 v3, v133, v134
	v_mul_f32_e32 v133, 0xbfb8aa3b, v73
	v_exp_f32_e32 v133, v133
	v_add_u32_e32 v0, v163, v155
	ds_write_b64 v0, v[2:3]
	v_add_f32_e32 v0, 1.0, v132
	v_mul_f32_e32 v3, 0xbfb8aa3b, v74
	v_mul_f32_e32 v132, 0xbfb8aa3b, v75
	v_exp_f32_e32 v3, v3
	v_exp_f32_e32 v132, v132
	v_add_f32_e32 v2, 1.0, v133
	v_mul_f32_e32 v133, 0xbfb8aa3b, v61
	v_exp_f32_e32 v133, v133
	v_add_f32_e32 v3, 1.0, v3
	v_add_f32_e32 v132, 1.0, v132
	v_rcp_f32_e32 v3, v3
	v_rcp_f32_e32 v132, v132
	s_nop 0
	v_cvt_pk_bf16_f32 v3, v3, v132
	v_add_f32_e32 v132, 1.0, v133
	v_mul_f32_e32 v133, 0xbfb8aa3b, v62
	v_mul_f32_e32 v134, 0xbfb8aa3b, v63
	v_exp_f32_e32 v133, v133
	v_exp_f32_e32 v134, v134
	v_mul_f32_e32 v135, 0xbfb8aa3b, v77
	v_rcp_f32_e32 v0, v0
	v_rcp_f32_e32 v2, v2
	v_exp_f32_e32 v135, v135
	v_cvt_pk_bf16_f32 v2, v0, v2
	v_mul_f32_e32 v0, 0xbfb8aa3b, v60
	v_exp_f32_e32 v0, v0
	v_add_f32_e32 v133, 1.0, v133
	v_add_f32_e32 v134, 1.0, v134
	v_rcp_f32_e32 v133, v133
	v_rcp_f32_e32 v134, v134
	s_nop 0
	v_cvt_pk_bf16_f32 v133, v133, v134
	v_add_f32_e32 v134, 1.0, v135
	v_mul_f32_e32 v135, 0xbfb8aa3b, v78
	v_mul_f32_e32 v136, 0xbfb8aa3b, v79
	v_exp_f32_e32 v135, v135
	v_exp_f32_e32 v136, v136
	v_add_f32_e32 v0, 1.0, v0
	v_mul_f32_e32 v137, 0xbfb8aa3b, v65
	v_rcp_f32_e32 v0, v0
	v_rcp_f32_e32 v132, v132
	v_exp_f32_e32 v137, v137
	v_cvt_pk_bf16_f32 v132, v0, v132
	v_mul_f32_e32 v0, 0xbfb8aa3b, v76
	v_exp_f32_e32 v0, v0
	v_add_f32_e32 v135, 1.0, v135
	v_add_f32_e32 v136, 1.0, v136
	v_rcp_f32_e32 v135, v135
	v_rcp_f32_e32 v136, v136
	s_nop 0
	v_cvt_pk_bf16_f32 v135, v135, v136
	v_add_f32_e32 v136, 1.0, v137
	v_mul_f32_e32 v137, 0xbfb8aa3b, v66
	v_exp_f32_e32 v137, v137
	v_mul_f32_e32 v138, 0xbfb8aa3b, v67
	v_add_f32_e32 v0, 1.0, v0
	v_exp_f32_e32 v138, v138
	v_rcp_f32_e32 v0, v0
	v_rcp_f32_e32 v134, v134
	s_nop 0
	v_cvt_pk_bf16_f32 v134, v0, v134
	v_mul_f32_e32 v0, 0xbfb8aa3b, v64
	v_exp_f32_e32 v0, v0
	v_add_f32_e32 v137, 1.0, v137
; __device__ __forceinline__ float sigmf(float x) { return __builtin_amdgcn_rcpf(1.f + __expf(-x)); }
; #define STAGE_TILE_F(XFORM) do { SW_BEGIN f32x4 v = acc[ai][bj][m][n2]; XFORM; \
;     *(u32x2*)(smem + mrow * SPITCH + nc0 * 2) = u32x2{cvtpk_t(v[0], v[1]), cvtpk_t(v[2], v[3])}; LOOP_END __syncthreads(); } while (0)
; template <int kind> __device__ __forceinline__ void gemm_phase_n(const Params& P, int layer, int b, const int wv) {
;     ...
;                 float* out = P.out; const u16* x1b = (const u16*)(ws + O_XBB);
;                 u16* xb = (u16*)(ws + O_XBA); float* rowss = (float*)(ws + O_ROWSS);
;                 STAGE_TILE_F(v[0] = sigmf(v[0]); v[1] = sigmf(v[1]); v[2] = sigmf(v[2]); v[3] = sigmf(v[3]));
	v_rcp_f32_e32 v137, v137
	v_add_f32_e32 v138, 1.0, v138
	v_add_u32_e32 v139, v162, v156
	v_rcp_f32_e32 v138, v138
	ds_write_b64 v139, v[134:135]
	v_cvt_pk_bf16_f32 v135, v137, v138
	v_mul_f32_e32 v137, 0xbfb8aa3b, v45
	v_exp_f32_e32 v137, v137
	v_add_f32_e32 v0, 1.0, v0
	v_rcp_f32_e32 v136, v136
	v_rcp_f32_e32 v0, v0
	s_nop 0
	v_cvt_pk_bf16_f32 v134, v0, v136
	v_mul_f32_e32 v136, 0xbfb8aa3b, v44
	v_add_u32_e32 v0, v162, v155
	v_exp_f32_e32 v136, v136
	ds_write_b64 v0, v[134:135]
	v_add_f32_e32 v134, 1.0, v137
	v_mul_f32_e32 v137, 0xbfb8aa3b, v40
	v_mul_f32_e32 v138, 0xbfb8aa3b, v41
	v_exp_f32_e32 v137, v137
	v_exp_f32_e32 v138, v138
	v_add_f32_e32 v0, 1.0, v136
	v_rcp_f32_e32 v0, v0
	v_mul_f32_e32 v135, 0xbfb8aa3b, v46
	v_rcp_f32_e32 v134, v134
	v_exp_f32_e32 v135, v135
	v_mul_f32_e32 v136, 0xbfb8aa3b, v47
	v_cvt_pk_bf16_f32 v134, v0, v134
	v_add_f32_e32 v0, 1.0, v137
	v_add_f32_e32 v137, 1.0, v138
	v_mul_f32_e32 v138, 0xbfb8aa3b, v42
	v_mul_f32_e32 v139, 0xbfb8aa3b, v43
	v_exp_f32_e32 v136, v136
	v_exp_f32_e32 v138, v138
	v_exp_f32_e32 v139, v139
	v_add_f32_e32 v135, 1.0, v135
	v_rcp_f32_e32 v135, v135
	v_add_f32_e32 v136, 1.0, v136
	v_rcp_f32_e32 v0, v0
	v_add_f32_e32 v138, 1.0, v138
	v_add_f32_e32 v139, 1.0, v139
	v_rcp_f32_e32 v136, v136
	v_rcp_f32_e32 v137, v137
	v_rcp_f32_e32 v138, v138
	v_rcp_f32_e32 v139, v139
	v_cvt_pk_bf16_f32 v135, v135, v136
	ds_write2_b64 v158, v[2:3], v[134:135] offset0:32 offset1:36
	v_cvt_pk_bf16_f32 v2, v0, v137
	v_cvt_pk_bf16_f32 v3, v138, v139
	v_mul_f32_e32 v0, 0xbfb8aa3b, v48
	v_mul_f32_e32 v134, 0xbfb8aa3b, v49
	v_exp_f32_e32 v0, v0
	v_exp_f32_e32 v134, v134
	ds_write2_b64 v157, v[132:133], v[2:3] offset0:96 offset1:100
	v_mul_f32_e32 v3, 0xbfb8aa3b, v50
	v_mul_f32_e32 v132, 0xbfb8aa3b, v51
	v_exp_f32_e32 v3, v3
	v_exp_f32_e32 v132, v132
	v_mul_f32_e32 v133, 0xbfb8aa3b, v37
	v_exp_f32_e32 v133, v133
	v_add_f32_e32 v0, 1.0, v0
	v_add_f32_e32 v2, 1.0, v134
	v_rcp_f32_e32 v0, v0
	v_rcp_f32_e32 v2, v2
	v_add_f32_e32 v3, 1.0, v3
	v_add_f32_e32 v132, 1.0, v132
	v_rcp_f32_e32 v3, v3
	v_rcp_f32_e32 v132, v132
	v_cvt_pk_bf16_f32 v2, v0, v2
	v_mul_f32_e32 v0, 0xbfb8aa3b, v36
	v_exp_f32_e32 v0, v0
	v_cvt_pk_bf16_f32 v3, v3, v132
	v_add_f32_e32 v132, 1.0, v133
	v_mul_f32_e32 v133, 0xbfb8aa3b, v38
	v_exp_f32_e32 v133, v133
	v_mul_f32_e32 v134, 0xbfb8aa3b, v39
	v_exp_f32_e32 v134, v134
	v_add_f32_e32 v0, 1.0, v0
	v_rcp_f32_e32 v132, v132
	v_add_u32_e32 v135, v161, v156
	v_rcp_f32_e32 v0, v0
	v_add_f32_e32 v133, 1.0, v133
	ds_write_b64 v135, v[2:3]
	v_cvt_pk_bf16_f32 v2, v0, v132
	v_mul_f32_e32 v132, 0xbfb8aa3b, v28
	v_rcp_f32_e32 v133, v133
	v_add_f32_e32 v134, 1.0, v134
	v_exp_f32_e32 v132, v132
	v_rcp_f32_e32 v134, v134
	s_nop 0
	v_cvt_pk_bf16_f32 v3, v133, v134
	v_mul_f32_e32 v133, 0xbfb8aa3b, v29
	v_exp_f32_e32 v133, v133
	v_add_u32_e32 v0, v161, v155
	ds_write_b64 v0, v[2:3]
	v_add_f32_e32 v0, 1.0, v132
	v_mul_f32_e32 v3, 0xbfb8aa3b, v30
	v_mul_f32_e32 v132, 0xbfb8aa3b, v31
	v_exp_f32_e32 v3, v3
	v_exp_f32_e32 v132, v132
	v_add_f32_e32 v2, 1.0, v133
	v_mul_f32_e32 v133, 0xbfb8aa3b, v21
	v_exp_f32_e32 v133, v133
	v_rcp_f32_e32 v0, v0
	v_rcp_f32_e32 v2, v2
	v_add_f32_e32 v3, 1.0, v3
	v_add_f32_e32 v132, 1.0, v132
	v_cvt_pk_bf16_f32 v2, v0, v2
	v_mul_f32_e32 v0, 0xbfb8aa3b, v20
	v_rcp_f32_e32 v3, v3
	v_rcp_f32_e32 v132, v132
	v_exp_f32_e32 v0, v0
	v_cvt_pk_bf16_f32 v3, v3, v132
	v_add_f32_e32 v132, 1.0, v133
	v_mul_f32_e32 v133, 0xbfb8aa3b, v22
	v_mul_f32_e32 v134, 0xbfb8aa3b, v23
	v_exp_f32_e32 v133, v133
	v_exp_f32_e32 v134, v134
	v_mul_f32_e32 v135, 0xbfb8aa3b, v33
	v_add_f32_e32 v0, 1.0, v0
	v_exp_f32_e32 v135, v135
	v_rcp_f32_e32 v0, v0
	v_rcp_f32_e32 v132, v132
	v_add_f32_e32 v133, 1.0, v133
	v_add_f32_e32 v134, 1.0, v134
	v_cvt_pk_bf16_f32 v132, v0, v132
	v_mul_f32_e32 v0, 0xbfb8aa3b, v32
	v_rcp_f32_e32 v133, v133
	v_rcp_f32_e32 v134, v134
	v_exp_f32_e32 v0, v0
	v_cvt_pk_bf16_f32 v133, v133, v134
	v_add_f32_e32 v134, 1.0, v135
	v_mul_f32_e32 v135, 0xbfb8aa3b, v34
	v_mul_f32_e32 v136, 0xbfb8aa3b, v35
	v_exp_f32_e32 v135, v135
	v_exp_f32_e32 v136, v136
	v_mul_f32_e32 v137, 0xbfb8aa3b, v25
	v_add_f32_e32 v0, 1.0, v0
	v_exp_f32_e32 v137, v137
	v_rcp_f32_e32 v0, v0
	v_rcp_f32_e32 v134, v134
; __device__ __forceinline__ float sigmf(float x) { return __builtin_amdgcn_rcpf(1.f + __expf(-x)); }
; #define STAGE_TILE_F(XFORM) do { SW_BEGIN f32x4 v = acc[ai][bj][m][n2]; XFORM; \
;     *(u32x2*)(smem + mrow * SPITCH + nc0 * 2) = u32x2{cvtpk_t(v[0], v[1]), cvtpk_t(v[2], v[3])}; LOOP_END __syncthreads(); } while (0)
; template <int kind> __device__ __forceinline__ void gemm_phase_n(const Params& P, int layer, int b, const int wv) {
;     ...
;                 STAGE_TILE_F(v[0] = sigmf(v[0]); v[1] = sigmf(v[1]); v[2] = sigmf(v[2]); v[3] = sigmf(v[3]));
;                 DRAIN_BEGIN const size_t t = pm * 256 + row; const size_t idx = t * 1024 + pn * 256 + chunk * 8;
	v_add_f32_e32 v135, 1.0, v135
	v_add_f32_e32 v136, 1.0, v136
	v_cvt_pk_bf16_f32 v134, v0, v134
	v_mul_f32_e32 v0, 0xbfb8aa3b, v24
	v_rcp_f32_e32 v135, v135
	v_rcp_f32_e32 v136, v136
	v_exp_f32_e32 v0, v0
	v_cvt_pk_bf16_f32 v135, v135, v136
	v_add_f32_e32 v136, 1.0, v137
	v_mul_f32_e32 v137, 0xbfb8aa3b, v26
	v_mul_f32_e32 v138, 0xbfb8aa3b, v27
	v_exp_f32_e32 v137, v137
	v_exp_f32_e32 v138, v138
	v_add_f32_e32 v0, 1.0, v0
	v_rcp_f32_e32 v0, v0
	v_add_u32_e32 v139, v160, v156
	v_rcp_f32_e32 v136, v136
	v_add_f32_e32 v137, 1.0, v137
	v_add_f32_e32 v138, 1.0, v138
	ds_write_b64 v139, v[134:135]
	v_cvt_pk_bf16_f32 v134, v0, v136
	v_add_u32_e32 v0, v160, v155
	v_rcp_f32_e32 v137, v137
	v_rcp_f32_e32 v138, v138
	s_nop 0
	v_cvt_pk_bf16_f32 v135, v137, v138
	ds_write_b64 v0, v[134:135]
	v_mul_f32_e32 v0, 0xbfb8aa3b, v12
	v_mul_f32_e32 v134, 0xbfb8aa3b, v13
	v_exp_f32_e32 v0, v0
	v_exp_f32_e32 v134, v134
	v_mul_f32_e32 v138, 0xbfb8aa3b, v8
	v_mul_f32_e32 v139, 0xbfb8aa3b, v9
	v_exp_f32_e32 v138, v138
	v_exp_f32_e32 v139, v139
	v_add_f32_e32 v0, 1.0, v0
	v_add_f32_e32 v134, 1.0, v134
	v_rcp_f32_e32 v0, v0
	v_mul_f32_e32 v135, 0xbfb8aa3b, v14
	v_rcp_f32_e32 v134, v134
	v_exp_f32_e32 v135, v135
	v_mul_f32_e32 v137, 0xbfb8aa3b, v15
	v_cvt_pk_bf16_f32 v134, v0, v134
	v_add_f32_e32 v0, 1.0, v138
	v_add_f32_e32 v138, 1.0, v139
	v_mul_f32_e32 v139, 0xbfb8aa3b, v10
	v_mul_f32_e32 v140, 0xbfb8aa3b, v11
	v_exp_f32_e32 v137, v137
	v_exp_f32_e32 v139, v139
	v_exp_f32_e32 v140, v140
	v_add_f32_e32 v135, 1.0, v135
	v_rcp_f32_e32 v135, v135
	v_add_f32_e32 v137, 1.0, v137
	v_rcp_f32_e32 v0, v0
	v_add_f32_e32 v139, 1.0, v139
	v_add_f32_e32 v140, 1.0, v140
	v_rcp_f32_e32 v137, v137
	v_rcp_f32_e32 v138, v138
	v_rcp_f32_e32 v139, v139
	v_rcp_f32_e32 v140, v140
	v_cvt_pk_bf16_f32 v135, v135, v137
	ds_write2_b64 v158, v[2:3], v[134:135] offset0:40 offset1:44
	v_cvt_pk_bf16_f32 v2, v0, v138
	v_cvt_pk_bf16_f32 v3, v139, v140
	v_mul_f32_e32 v0, 0xbfb8aa3b, v16
	v_mul_f32_e32 v134, 0xbfb8aa3b, v17
	v_exp_f32_e32 v0, v0
	v_exp_f32_e32 v134, v134
	ds_write2_b64 v157, v[132:133], v[2:3] offset0:104 offset1:108
	v_mul_f32_e32 v3, 0xbfb8aa3b, v18
	v_mul_f32_e32 v132, 0xbfb8aa3b, v19
	v_exp_f32_e32 v3, v3
	v_exp_f32_e32 v132, v132
	v_mul_f32_e32 v133, 0xbfb8aa3b, v5
	v_exp_f32_e32 v133, v133
	v_add_f32_e32 v0, 1.0, v0
	v_add_f32_e32 v2, 1.0, v134
	v_rcp_f32_e32 v0, v0
	v_rcp_f32_e32 v2, v2
	v_add_f32_e32 v3, 1.0, v3
	v_add_f32_e32 v132, 1.0, v132
	v_rcp_f32_e32 v3, v3
	v_rcp_f32_e32 v132, v132
	v_cvt_pk_bf16_f32 v2, v0, v2
	v_mul_f32_e32 v0, 0xbfb8aa3b, v4
	v_exp_f32_e32 v0, v0
	v_cvt_pk_bf16_f32 v3, v3, v132
	v_add_f32_e32 v132, 1.0, v133
	v_mul_f32_e32 v133, 0xbfb8aa3b, v6
	v_mul_f32_e32 v134, 0xbfb8aa3b, v7
	v_exp_f32_e32 v133, v133
	v_exp_f32_e32 v134, v134
	v_add_u32_e32 v136, 0x160, v159
	v_add_f32_e32 v0, 1.0, v0
	v_rcp_f32_e32 v0, v0
	v_add_f32_e32 v133, 1.0, v133
	v_add_f32_e32 v134, 1.0, v134
	v_add_u32_e32 v135, v136, v156
	v_rcp_f32_e32 v132, v132
	v_rcp_f32_e32 v133, v133
	v_rcp_f32_e32 v134, v134
	ds_write_b64 v135, v[2:3]
	v_cvt_pk_bf16_f32 v2, v0, v132
	v_cvt_pk_bf16_f32 v3, v133, v134
	v_add_u32_e32 v0, v136, v155
	ds_write_b64 v0, v[2:3]
	v_ashrrev_i32_e32 v2, 5, v154
	v_and_b32_e32 v3, 31, v154
	v_lshlrev_b32_e32 v134, 4, v3
	v_lshlrev_b32_e32 v0, 3, v3
	v_cmp_eq_u32_e64 s[4:5], 0, v3
	v_ashrrev_i32_e32 v3, 31, v2
	v_lshlrev_b64 v[132:133], 9, v[2:3]
	v_readlane_b32 s6, v254, 7
	v_or_b32_e32 v132, v132, v134
	v_readlane_b32 s7, v254, 8
	v_add_u32_e32 v166, s22, v2
	v_or_b32_e32 v140, s18, v0
	v_lshl_add_u64 v[142:143], s[6:7], 0, v[132:133]
	s_movk_i32 s6, 0x220
	v_mul_lo_u32 v132, v2, s6
	v_lshl_add_u64 v[2:3], s[22:23], 0, v[2:3]
	v_add3_u32 v167, v132, v134, 0
	v_lshlrev_b64 v[132:133], 6, v[2:3]
	v_lshlrev_b64 v[2:3], 10, v[2:3]
	v_lshl_add_u64 v[2:3], s[18:19], 0, v[2:3]
	v_readlane_b32 s6, v254, 11
	v_lshl_add_u64 v[2:3], v[2:3], 0, v[0:1]
	v_readlane_b32 s7, v254, 12
	v_mov_b32_e32 v141, s19
	s_mov_b32 s30, 0
	v_lshl_add_u64 v[144:145], s[26:27], 0, v[132:133]
	v_lshl_add_u64 v[146:147], v[2:3], 1, s[88:89]
	v_lshl_add_u64 v[148:149], v[2:3], 2, s[6:7]
	s_waitcnt vmcnt(0) lgkmcnt(0)
	s_barrier
	s_branch .LBB0_641

; __device__ __forceinline__ float siluf(float x) { return x * __builtin_amdgcn_rcpf(1.f + __expf(-x)); }
; #define STAGE_TILE_F(XFORM) do { SW_BEGIN f32x4 v = acc[ai][bj][m][n2]; XFORM; \
;     *(u32x2*)(smem + mrow * SPITCH + nc0 * 2) = u32x2{cvtpk_t(v[0], v[1]), cvtpk_t(v[2], v[3])}; LOOP_END __syncthreads(); } while (0)
; template <int kind> __device__ __forceinline__ void gemm_phase_n(const Params& P, int layer, int b, const int wv) {
;     ...
;                 } else if (pn < 12) {
;                     STAGE_TILE_F(const float r = rs_lds[mrow]; v[0] = siluf(v[0] * r); v[1] = siluf(v[1] * r); v[2] = siluf(v[2] * r); v[3] = siluf(v[3] * r));
;                     u16* dst = (u16*)(ws + O_SG) + (size_t)t0 * 2048 + (pn - 4) * 256;
.LBB0_682:
	s_andn2_b64 vcc, exec, s[2:3]
	s_cbranch_vccnz .LBB0_685
	v_lshl_or_b32 v134, v140, 5, v141
	v_lshl_add_u32 v0, v134, 2, 0
	v_add_u32_e32 v0, 0x22000, v0
	ds_read_b32 v148, v0
	ds_read_b32 v149, v0 offset:64
	ds_read_b32 v150, v0 offset:512
	ds_read_b32 v151, v0 offset:576
	s_waitcnt lgkmcnt(0)
	v_mov_b32_e32 v132, v148
	v_lshlrev_b32_e32 v130, 7, v142
	v_lshl_add_u32 v131, v143, 3, 0
	v_mul_u32_u24_e32 v134, 0x220, v134
	v_add3_u32 v131, v131, v130, v134
	v_mul_f32_e32 v133, v126, v132
	v_mul_f32_e32 v135, 0xbfb8aa3b, v133
	v_exp_f32_e32 v135, v135
	s_lshl_b64 s[2:3], s[10:11], 12
	v_add_f32_e32 v135, 1.0, v135
	v_rcp_f32_e32 v135, v135
	s_nop 0
	v_mul_f32_e32 v133, v133, v135
	v_mul_f32_e32 v135, v127, v132
	v_mul_f32_e32 v136, 0xbfb8aa3b, v135
	v_exp_f32_e32 v136, v136
	s_nop 0
	v_add_f32_e32 v136, 1.0, v136
	v_rcp_f32_e32 v136, v136
	s_nop 0
	v_mul_f32_e32 v135, v135, v136
	v_mul_f32_e32 v136, v128, v132
	v_mul_f32_e32 v138, 0xbfb8aa3b, v136
	v_exp_f32_e32 v138, v138
	v_mul_f32_e32 v132, v129, v132
	v_add_f32_e32 v138, 1.0, v138
	v_rcp_f32_e32 v138, v138
	s_nop 0
	v_mul_f32_e32 v136, v136, v138
	v_mul_f32_e32 v138, 0xbfb8aa3b, v132
	v_exp_f32_e32 v138, v138
	s_nop 0
	v_add_f32_e32 v138, 1.0, v138
	v_rcp_f32_e32 v138, v138
	s_nop 0
	v_mul_f32_e32 v138, v132, v138
	v_cvt_pk_bf16_f32 v132, v133, v135
	v_cvt_pk_bf16_f32 v133, v136, v138
	ds_write_b64 v131, v[132:133]
	v_mov_b32_e32 v130, v149
	v_mul_f32_e32 v132, v118, v130
	v_mul_f32_e32 v133, 0xbfb8aa3b, v132
	v_exp_f32_e32 v133, v133
	s_nop 0
	v_add_f32_e32 v133, 1.0, v133
	v_rcp_f32_e32 v133, v133
	s_nop 0
	v_mul_f32_e32 v132, v132, v133
	v_mul_f32_e32 v133, v119, v130
	v_mul_f32_e32 v134, 0xbfb8aa3b, v133
	v_exp_f32_e32 v134, v134
	s_nop 0
	v_add_f32_e32 v134, 1.0, v134
	v_rcp_f32_e32 v134, v134
	s_nop 0
	v_mul_f32_e32 v133, v133, v134
	v_mul_f32_e32 v134, v120, v130
	v_mul_f32_e32 v135, 0xbfb8aa3b, v134
	v_exp_f32_e32 v135, v135
	v_mul_f32_e32 v130, v121, v130
	v_cvt_pk_bf16_f32 v132, v132, v133
	v_add_f32_e32 v135, 1.0, v135
	v_rcp_f32_e32 v135, v135
	s_nop 0
	v_mul_f32_e32 v134, v134, v135
	v_mul_f32_e32 v135, 0xbfb8aa3b, v130
	v_exp_f32_e32 v135, v135
	s_nop 0
	v_add_f32_e32 v135, 1.0, v135
	v_rcp_f32_e32 v135, v135
	s_nop 0
	v_mul_f32_e32 v130, v130, v135
	v_cvt_pk_bf16_f32 v133, v134, v130
	ds_write_b64 v131, v[132:133] offset:8704
	v_mov_b32_e32 v132, v150
	v_add_u32_e32 v130, 0x2200, v131
	v_mul_f32_e32 v133, v122, v132
	v_mul_f32_e32 v134, 0xbfb8aa3b, v133
	v_exp_f32_e32 v134, v134
	s_nop 0
	v_add_f32_e32 v134, 1.0, v134
	v_rcp_f32_e32 v134, v134
	s_nop 0
	v_mul_f32_e32 v133, v133, v134
	v_mul_f32_e32 v134, v123, v132
	v_mul_f32_e32 v135, 0xbfb8aa3b, v134
	v_exp_f32_e32 v135, v135
	s_nop 0
	v_add_f32_e32 v135, 1.0, v135
	v_rcp_f32_e32 v135, v135
	s_nop 0
	v_mul_f32_e32 v134, v134, v135
	v_mul_f32_e32 v135, v124, v132
	v_mul_f32_e32 v136, 0xbfb8aa3b, v135
	v_exp_f32_e32 v136, v136
	v_mul_f32_e32 v132, v125, v132
	v_cvt_pk_bf16_f32 v134, v133, v134
	v_add_f32_e32 v136, 1.0, v136
	v_rcp_f32_e32 v136, v136
	s_nop 0
	v_mul_f32_e32 v135, v135, v136
	v_mul_f32_e32 v136, 0xbfb8aa3b, v132
	v_exp_f32_e32 v136, v136
	s_nop 0
	v_add_f32_e32 v136, 1.0, v136
	v_rcp_f32_e32 v136, v136
	s_nop 0
	v_mul_f32_e32 v132, v132, v136
	v_cvt_pk_bf16_f32 v135, v135, v132
	ds_write_b64 v130, v[134:135] offset:60928
	v_mov_b32_e32 v133, v151
	v_add_u32_e32 v132, 0xee00, v130
	v_mul_f32_e32 v134, v114, v133
	v_mul_f32_e32 v135, 0xbfb8aa3b, v134
	v_exp_f32_e32 v135, v135
	s_nop 0
	v_add_f32_e32 v135, 1.0, v135
	v_rcp_f32_e32 v135, v135
	s_nop 0
	v_mul_f32_e32 v134, v134, v135
	v_mul_f32_e32 v135, v115, v133
	v_mul_f32_e32 v136, 0xbfb8aa3b, v135
	v_exp_f32_e32 v136, v136
	s_nop 0
	v_add_f32_e32 v136, 1.0, v136
	v_rcp_f32_e32 v136, v136
	s_nop 0
	v_mul_f32_e32 v135, v135, v136
	v_mul_f32_e32 v136, v116, v133
	v_mul_f32_e32 v138, 0xbfb8aa3b, v136
	v_exp_f32_e32 v138, v138
	v_mul_f32_e32 v133, v117, v133
	v_cvt_pk_bf16_f32 v134, v134, v135
	v_add_f32_e32 v138, 1.0, v138
	v_rcp_f32_e32 v138, v138
	s_nop 0
	v_mul_f32_e32 v136, v136, v138
	v_mul_f32_e32 v138, 0xbfb8aa3b, v133
	v_exp_f32_e32 v138, v138
	s_nop 0
	v_add_f32_e32 v138, 1.0, v138
	v_rcp_f32_e32 v138, v138
	s_nop 0
	v_mul_f32_e32 v133, v133, v138
	v_cvt_pk_bf16_f32 v135, v136, v133
	ds_write_b64 v132, v[134:135] offset:8704
	v_mov_b32_e32 v133, v148
	v_mul_f32_e32 v134, v110, v133
	v_mul_f32_e32 v135, 0xbfb8aa3b, v134
	v_exp_f32_e32 v135, v135
	s_nop 0
	v_add_f32_e32 v135, 1.0, v135
	v_rcp_f32_e32 v135, v135
	s_nop 0
	v_mul_f32_e32 v134, v134, v135
	v_mul_f32_e32 v135, v111, v133
	v_mul_f32_e32 v136, 0xbfb8aa3b, v135
	v_exp_f32_e32 v136, v136
	s_nop 0
	v_add_f32_e32 v136, 1.0, v136
	v_rcp_f32_e32 v136, v136
	s_nop 0
	v_mul_f32_e32 v135, v135, v136
	v_mul_f32_e32 v136, v112, v133
	v_mul_f32_e32 v138, 0xbfb8aa3b, v136
	v_exp_f32_e32 v138, v138
	v_mul_f32_e32 v133, v113, v133
	v_cvt_pk_bf16_f32 v134, v134, v135
	v_add_f32_e32 v138, 1.0, v138
	v_rcp_f32_e32 v138, v138
	s_nop 0
	v_mul_f32_e32 v136, v136, v138
	v_mul_f32_e32 v138, 0xbfb8aa3b, v133
	v_exp_f32_e32 v138, v138
	s_nop 0
	v_add_f32_e32 v138, 1.0, v138
	v_rcp_f32_e32 v138, v138
	s_nop 0
	v_mul_f32_e32 v133, v133, v138
	v_cvt_pk_bf16_f32 v135, v136, v133
	ds_write_b64 v131, v[134:135] offset:32
	v_mov_b32_e32 v133, v149
	v_mul_f32_e32 v134, v102, v133
	v_mul_f32_e32 v135, 0xbfb8aa3b, v134
	v_exp_f32_e32 v135, v135
	s_nop 0
	v_add_f32_e32 v135, 1.0, v135
	v_rcp_f32_e32 v135, v135
	s_nop 0
	v_mul_f32_e32 v134, v134, v135
	v_mul_f32_e32 v135, v103, v133
	v_mul_f32_e32 v136, 0xbfb8aa3b, v135
	v_exp_f32_e32 v136, v136
	s_nop 0
	v_add_f32_e32 v136, 1.0, v136
	v_rcp_f32_e32 v136, v136
; __device__ __forceinline__ float siluf(float x) { return x * __builtin_amdgcn_rcpf(1.f + __expf(-x)); }
; #define STAGE_TILE_F(XFORM) do { SW_BEGIN f32x4 v = acc[ai][bj][m][n2]; XFORM; \
;     *(u32x2*)(smem + mrow * SPITCH + nc0 * 2) = u32x2{cvtpk_t(v[0], v[1]), cvtpk_t(v[2], v[3])}; LOOP_END __syncthreads(); } while (0)
; template <int kind> __device__ __forceinline__ void gemm_phase_n(const Params& P, int layer, int b, const int wv) {
;     ...
;                 } else if (pn < 12) {
;                     STAGE_TILE_F(const float r = rs_lds[mrow]; v[0] = siluf(v[0] * r); v[1] = siluf(v[1] * r); v[2] = siluf(v[2] * r); v[3] = siluf(v[3] * r));
;                     u16* dst = (u16*)(ws + O_SG) + (size_t)t0 * 2048 + (pn - 4) * 256;
	s_nop 0
	v_mul_f32_e32 v135, v135, v136
	v_mul_f32_e32 v136, v104, v133
	v_mul_f32_e32 v138, 0xbfb8aa3b, v136
	v_exp_f32_e32 v138, v138
	v_mul_f32_e32 v133, v105, v133
	v_cvt_pk_bf16_f32 v134, v134, v135
	v_add_f32_e32 v138, 1.0, v138
	v_rcp_f32_e32 v138, v138
	s_nop 0
	v_mul_f32_e32 v136, v136, v138
	v_mul_f32_e32 v138, 0xbfb8aa3b, v133
	v_exp_f32_e32 v138, v138
	s_nop 0
	v_add_f32_e32 v138, 1.0, v138
	v_rcp_f32_e32 v138, v138
	s_nop 0
	v_mul_f32_e32 v133, v133, v138
	v_cvt_pk_bf16_f32 v135, v136, v133
	ds_write_b64 v131, v[134:135] offset:8736
	v_mov_b32_e32 v133, v150
	v_mul_f32_e32 v134, v106, v133
	v_mul_f32_e32 v135, 0xbfb8aa3b, v134
	v_exp_f32_e32 v135, v135
	s_nop 0
	v_add_f32_e32 v135, 1.0, v135
	v_rcp_f32_e32 v135, v135
	s_nop 0
	v_mul_f32_e32 v134, v134, v135
	v_mul_f32_e32 v135, v107, v133
	v_mul_f32_e32 v136, 0xbfb8aa3b, v135
	v_exp_f32_e32 v136, v136
	s_nop 0
	v_add_f32_e32 v136, 1.0, v136
	v_rcp_f32_e32 v136, v136
	s_nop 0
	v_mul_f32_e32 v135, v135, v136
	v_mul_f32_e32 v136, v108, v133
	v_mul_f32_e32 v138, 0xbfb8aa3b, v136
	v_exp_f32_e32 v138, v138
	v_mul_f32_e32 v133, v109, v133
	v_cvt_pk_bf16_f32 v134, v134, v135
	v_add_f32_e32 v138, 1.0, v138
	v_rcp_f32_e32 v138, v138
	s_nop 0
	v_mul_f32_e32 v136, v136, v138
	v_mul_f32_e32 v138, 0xbfb8aa3b, v133
	v_exp_f32_e32 v138, v138
	s_nop 0
	v_add_f32_e32 v138, 1.0, v138
	v_rcp_f32_e32 v138, v138
	s_nop 0
	v_mul_f32_e32 v133, v133, v138
	v_cvt_pk_bf16_f32 v135, v136, v133
	ds_write_b64 v130, v[134:135] offset:60960
	v_mov_b32_e32 v133, v151
	v_mul_f32_e32 v134, v98, v133
	v_mul_f32_e32 v135, 0xbfb8aa3b, v134
	v_exp_f32_e32 v135, v135
	s_nop 0
	v_add_f32_e32 v135, 1.0, v135
	v_rcp_f32_e32 v135, v135
	s_nop 0
	v_mul_f32_e32 v134, v134, v135
	v_mul_f32_e32 v135, v99, v133
	v_mul_f32_e32 v136, 0xbfb8aa3b, v135
	v_exp_f32_e32 v136, v136
	s_nop 0
	v_add_f32_e32 v136, 1.0, v136
	v_rcp_f32_e32 v136, v136
	s_nop 0
	v_mul_f32_e32 v135, v135, v136
	v_mul_f32_e32 v136, v100, v133
	v_mul_f32_e32 v138, 0xbfb8aa3b, v136
	v_exp_f32_e32 v138, v138
	v_mul_f32_e32 v133, v101, v133
	v_cvt_pk_bf16_f32 v134, v134, v135
	v_add_f32_e32 v138, 1.0, v138
	v_rcp_f32_e32 v138, v138
	s_nop 0
	v_mul_f32_e32 v136, v136, v138
	v_mul_f32_e32 v138, 0xbfb8aa3b, v133
	v_exp_f32_e32 v138, v138
	s_nop 0
	v_add_f32_e32 v138, 1.0, v138
	v_rcp_f32_e32 v138, v138
	s_nop 0
	v_mul_f32_e32 v133, v133, v138
	v_cvt_pk_bf16_f32 v135, v136, v133
	ds_write_b64 v132, v[134:135] offset:8736
	v_mov_b32_e32 v133, v148
	v_mul_f32_e32 v134, v94, v133
	v_mul_f32_e32 v135, 0xbfb8aa3b, v134
	v_exp_f32_e32 v135, v135
	s_nop 0
	v_add_f32_e32 v135, 1.0, v135
	v_rcp_f32_e32 v135, v135
	s_nop 0
	v_mul_f32_e32 v134, v134, v135
	v_mul_f32_e32 v135, v95, v133
	v_mul_f32_e32 v136, 0xbfb8aa3b, v135
	v_exp_f32_e32 v136, v136
	s_nop 0
	v_add_f32_e32 v136, 1.0, v136
	v_rcp_f32_e32 v136, v136
	s_nop 0
	v_mul_f32_e32 v135, v135, v136
	v_mul_f32_e32 v136, v96, v133
	v_mul_f32_e32 v138, 0xbfb8aa3b, v136
	v_exp_f32_e32 v138, v138
	v_mul_f32_e32 v133, v97, v133
	v_cvt_pk_bf16_f32 v134, v134, v135
	v_add_f32_e32 v138, 1.0, v138
	v_rcp_f32_e32 v138, v138
	s_nop 0
	v_mul_f32_e32 v136, v136, v138
	v_mul_f32_e32 v138, 0xbfb8aa3b, v133
	v_exp_f32_e32 v138, v138
	s_nop 0
	v_add_f32_e32 v138, 1.0, v138
	v_rcp_f32_e32 v138, v138
	s_nop 0
	v_mul_f32_e32 v133, v133, v138
	v_cvt_pk_bf16_f32 v135, v136, v133
	ds_write_b64 v131, v[134:135] offset:64
	v_mov_b32_e32 v133, v149
	v_mul_f32_e32 v134, v86, v133
	v_mul_f32_e32 v135, 0xbfb8aa3b, v134
	v_exp_f32_e32 v135, v135
	s_nop 0
	v_add_f32_e32 v135, 1.0, v135
	v_rcp_f32_e32 v135, v135
	s_nop 0
	v_mul_f32_e32 v134, v134, v135
	v_mul_f32_e32 v135, v87, v133
	v_mul_f32_e32 v136, 0xbfb8aa3b, v135
	v_exp_f32_e32 v136, v136
	s_nop 0
	v_add_f32_e32 v136, 1.0, v136
	v_rcp_f32_e32 v136, v136
	s_nop 0
	v_mul_f32_e32 v135, v135, v136
	v_mul_f32_e32 v136, v88, v133
	v_mul_f32_e32 v138, 0xbfb8aa3b, v136
	v_exp_f32_e32 v138, v138
	v_mul_f32_e32 v133, v89, v133
	v_cvt_pk_bf16_f32 v134, v134, v135
	v_add_f32_e32 v138, 1.0, v138
	v_rcp_f32_e32 v138, v138
	s_nop 0
	v_mul_f32_e32 v136, v136, v138
	v_mul_f32_e32 v138, 0xbfb8aa3b, v133
	v_exp_f32_e32 v138, v138
	s_nop 0
	v_add_f32_e32 v138, 1.0, v138
	v_rcp_f32_e32 v138, v138
	s_nop 0
	v_mul_f32_e32 v133, v133, v138
	v_cvt_pk_bf16_f32 v135, v136, v133
	ds_write_b64 v131, v[134:135] offset:8768
	v_mov_b32_e32 v133, v150
	v_mul_f32_e32 v134, v90, v133
	v_mul_f32_e32 v135, 0xbfb8aa3b, v134
	v_exp_f32_e32 v135, v135
	s_nop 0
	v_add_f32_e32 v135, 1.0, v135
	v_rcp_f32_e32 v135, v135
	s_nop 0
	v_mul_f32_e32 v134, v134, v135
	v_mul_f32_e32 v135, v91, v133
	v_mul_f32_e32 v136, 0xbfb8aa3b, v135
	v_exp_f32_e32 v136, v136
	s_nop 0
	v_add_f32_e32 v136, 1.0, v136
	v_rcp_f32_e32 v136, v136
	s_nop 0
	v_mul_f32_e32 v135, v135, v136
	v_mul_f32_e32 v136, v92, v133
	v_mul_f32_e32 v138, 0xbfb8aa3b, v136
	v_exp_f32_e32 v138, v138
	v_mul_f32_e32 v133, v93, v133
	v_cvt_pk_bf16_f32 v134, v134, v135
	v_add_f32_e32 v138, 1.0, v138
	v_rcp_f32_e32 v138, v138
	s_nop 0
	v_mul_f32_e32 v136, v136, v138
	v_mul_f32_e32 v138, 0xbfb8aa3b, v133
	v_exp_f32_e32 v138, v138
	s_nop 0
	v_add_f32_e32 v138, 1.0, v138
	v_rcp_f32_e32 v138, v138
	s_nop 0
	v_mul_f32_e32 v133, v133, v138
	v_cvt_pk_bf16_f32 v135, v136, v133
	ds_write_b64 v130, v[134:135] offset:60992
	v_mov_b32_e32 v133, v151
	v_mul_f32_e32 v134, v82, v133
	v_mul_f32_e32 v135, 0xbfb8aa3b, v134
	v_exp_f32_e32 v135, v135
	s_nop 0
	v_add_f32_e32 v135, 1.0, v135
	v_rcp_f32_e32 v135, v135
	s_nop 0
	v_mul_f32_e32 v134, v134, v135
	v_mul_f32_e32 v135, v83, v133
	v_mul_f32_e32 v136, 0xbfb8aa3b, v135
	v_exp_f32_e32 v136, v136
	s_nop 0
	v_add_f32_e32 v136, 1.0, v136
	v_rcp_f32_e32 v136, v136
; __device__ __forceinline__ float siluf(float x) { return x * __builtin_amdgcn_rcpf(1.f + __expf(-x)); }
; #define STAGE_TILE_F(XFORM) do { SW_BEGIN f32x4 v = acc[ai][bj][m][n2]; XFORM; \
;     *(u32x2*)(smem + mrow * SPITCH + nc0 * 2) = u32x2{cvtpk_t(v[0], v[1]), cvtpk_t(v[2], v[3])}; LOOP_END __syncthreads(); } while (0)
; template <int kind> __device__ __forceinline__ void gemm_phase_n(const Params& P, int layer, int b, const int wv) {
;     ...
;                 } else if (pn < 12) {
;                     STAGE_TILE_F(const float r = rs_lds[mrow]; v[0] = siluf(v[0] * r); v[1] = siluf(v[1] * r); v[2] = siluf(v[2] * r); v[3] = siluf(v[3] * r));
;                     u16* dst = (u16*)(ws + O_SG) + (size_t)t0 * 2048 + (pn - 4) * 256;
	s_nop 0
	v_mul_f32_e32 v135, v135, v136
	v_mul_f32_e32 v136, v84, v133
	v_mul_f32_e32 v138, 0xbfb8aa3b, v136
	v_exp_f32_e32 v138, v138
	v_mul_f32_e32 v133, v85, v133
	v_cvt_pk_bf16_f32 v134, v134, v135
	v_add_f32_e32 v138, 1.0, v138
	v_rcp_f32_e32 v138, v138
	s_nop 0
	v_mul_f32_e32 v136, v136, v138
	v_mul_f32_e32 v138, 0xbfb8aa3b, v133
	v_exp_f32_e32 v138, v138
	s_nop 0
	v_add_f32_e32 v138, 1.0, v138
	v_rcp_f32_e32 v138, v138
	s_nop 0
	v_mul_f32_e32 v133, v133, v138
	v_cvt_pk_bf16_f32 v135, v136, v133
	ds_write_b64 v132, v[134:135] offset:8768
	v_mov_b32_e32 v133, v148
	v_mul_f32_e32 v134, v78, v133
	v_mul_f32_e32 v135, 0xbfb8aa3b, v134
	v_exp_f32_e32 v135, v135
	s_nop 0
	v_add_f32_e32 v135, 1.0, v135
	v_rcp_f32_e32 v135, v135
	s_nop 0
	v_mul_f32_e32 v134, v134, v135
	v_mul_f32_e32 v135, v79, v133
	v_mul_f32_e32 v136, 0xbfb8aa3b, v135
	v_exp_f32_e32 v136, v136
	s_nop 0
	v_add_f32_e32 v136, 1.0, v136
	v_rcp_f32_e32 v136, v136
	s_nop 0
	v_mul_f32_e32 v135, v135, v136
	v_mul_f32_e32 v136, v80, v133
	v_mul_f32_e32 v138, 0xbfb8aa3b, v136
	v_exp_f32_e32 v138, v138
	v_mul_f32_e32 v133, v81, v133
	v_cvt_pk_bf16_f32 v134, v134, v135
	v_add_f32_e32 v138, 1.0, v138
	v_rcp_f32_e32 v138, v138
	s_nop 0
	v_mul_f32_e32 v136, v136, v138
	v_mul_f32_e32 v138, 0xbfb8aa3b, v133
	v_exp_f32_e32 v138, v138
	s_nop 0
	v_add_f32_e32 v138, 1.0, v138
	v_rcp_f32_e32 v138, v138
	s_nop 0
	v_mul_f32_e32 v133, v133, v138
	v_cvt_pk_bf16_f32 v135, v136, v133
	ds_write_b64 v131, v[134:135] offset:96
	v_mov_b32_e32 v133, v149
	v_mul_f32_e32 v134, v70, v133
	v_mul_f32_e32 v135, 0xbfb8aa3b, v134
	v_exp_f32_e32 v135, v135
	s_nop 0
	v_add_f32_e32 v135, 1.0, v135
	v_rcp_f32_e32 v135, v135
	s_nop 0
	v_mul_f32_e32 v134, v134, v135
	v_mul_f32_e32 v135, v71, v133
	v_mul_f32_e32 v136, 0xbfb8aa3b, v135
	v_exp_f32_e32 v136, v136
	s_nop 0
	v_add_f32_e32 v136, 1.0, v136
	v_rcp_f32_e32 v136, v136
	s_nop 0
	v_mul_f32_e32 v135, v135, v136
	v_mul_f32_e32 v136, v72, v133
	v_mul_f32_e32 v138, 0xbfb8aa3b, v136
	v_exp_f32_e32 v138, v138
	v_mul_f32_e32 v133, v73, v133
	v_cvt_pk_bf16_f32 v134, v134, v135
	v_add_f32_e32 v138, 1.0, v138
	v_rcp_f32_e32 v138, v138
	s_nop 0
	v_mul_f32_e32 v136, v136, v138
	v_mul_f32_e32 v138, 0xbfb8aa3b, v133
	v_exp_f32_e32 v138, v138
	s_nop 0
	v_add_f32_e32 v138, 1.0, v138
	v_rcp_f32_e32 v138, v138
	s_nop 0
	v_mul_f32_e32 v133, v133, v138
	v_cvt_pk_bf16_f32 v135, v136, v133
	ds_write_b64 v131, v[134:135] offset:8800
	v_mov_b32_e32 v133, v150
	v_mul_f32_e32 v134, v74, v133
	v_mul_f32_e32 v135, 0xbfb8aa3b, v134
	v_exp_f32_e32 v135, v135
	s_nop 0
	v_add_f32_e32 v135, 1.0, v135
	v_rcp_f32_e32 v135, v135
	s_nop 0
	v_mul_f32_e32 v134, v134, v135
	v_mul_f32_e32 v135, v75, v133
	v_mul_f32_e32 v136, 0xbfb8aa3b, v135
	v_exp_f32_e32 v136, v136
	s_nop 0
	v_add_f32_e32 v136, 1.0, v136
	v_rcp_f32_e32 v136, v136
	s_nop 0
	v_mul_f32_e32 v135, v135, v136
	v_mul_f32_e32 v136, v76, v133
	v_mul_f32_e32 v138, 0xbfb8aa3b, v136
	v_exp_f32_e32 v138, v138
	v_mul_f32_e32 v133, v77, v133
	v_cvt_pk_bf16_f32 v134, v134, v135
	v_add_f32_e32 v138, 1.0, v138
	v_rcp_f32_e32 v138, v138
	s_nop 0
	v_mul_f32_e32 v136, v136, v138
	v_mul_f32_e32 v138, 0xbfb8aa3b, v133
	v_exp_f32_e32 v138, v138
	s_nop 0
	v_add_f32_e32 v138, 1.0, v138
	v_rcp_f32_e32 v138, v138
	s_nop 0
	v_mul_f32_e32 v133, v133, v138
	v_cvt_pk_bf16_f32 v135, v136, v133
	ds_write_b64 v130, v[134:135] offset:61024
	v_mov_b32_e32 v133, v151
	v_mul_f32_e32 v134, v62, v133
	v_mul_f32_e32 v135, 0xbfb8aa3b, v134
	v_exp_f32_e32 v135, v135
	s_nop 0
	v_add_f32_e32 v135, 1.0, v135
	v_rcp_f32_e32 v135, v135
	s_nop 0
	v_mul_f32_e32 v134, v134, v135
	v_mul_f32_e32 v135, v63, v133
	v_mul_f32_e32 v136, 0xbfb8aa3b, v135
	v_exp_f32_e32 v136, v136
	s_nop 0
	v_add_f32_e32 v136, 1.0, v136
	v_rcp_f32_e32 v136, v136
	s_nop 0
	v_mul_f32_e32 v135, v135, v136
	v_mul_f32_e32 v136, v64, v133
	v_mul_f32_e32 v138, 0xbfb8aa3b, v136
	v_exp_f32_e32 v138, v138
	v_mul_f32_e32 v133, v65, v133
	v_cvt_pk_bf16_f32 v134, v134, v135
	v_add_f32_e32 v138, 1.0, v138
	v_rcp_f32_e32 v138, v138
	s_nop 0
	v_mul_f32_e32 v136, v136, v138
	v_mul_f32_e32 v138, 0xbfb8aa3b, v133
	v_exp_f32_e32 v138, v138
	s_nop 0
	v_add_f32_e32 v138, 1.0, v138
	v_rcp_f32_e32 v138, v138
	s_nop 0
	v_mul_f32_e32 v133, v133, v138
	v_cvt_pk_bf16_f32 v135, v136, v133
	ds_write_b64 v132, v[134:135] offset:8800
	v_mov_b32_e32 v133, v148
	v_mul_f32_e32 v134, v66, v133
	v_mul_f32_e32 v135, 0xbfb8aa3b, v134
	v_exp_f32_e32 v135, v135
	s_nop 0
	v_add_f32_e32 v135, 1.0, v135
	v_rcp_f32_e32 v135, v135
	s_nop 0
	v_mul_f32_e32 v134, v134, v135
	v_mul_f32_e32 v135, v67, v133
	v_mul_f32_e32 v136, 0xbfb8aa3b, v135
	v_exp_f32_e32 v136, v136
	s_nop 0
	v_add_f32_e32 v136, 1.0, v136
	v_rcp_f32_e32 v136, v136
	s_nop 0
	v_mul_f32_e32 v135, v135, v136
	v_mul_f32_e32 v136, v68, v133
	v_mul_f32_e32 v138, 0xbfb8aa3b, v136
	v_exp_f32_e32 v138, v138
	v_mul_f32_e32 v133, v69, v133
	v_cvt_pk_bf16_f32 v134, v134, v135
	v_add_f32_e32 v138, 1.0, v138
	v_rcp_f32_e32 v138, v138
	s_nop 0
	v_mul_f32_e32 v136, v136, v138
	v_mul_f32_e32 v138, 0xbfb8aa3b, v133
	v_exp_f32_e32 v138, v138
	s_nop 0
	v_add_f32_e32 v138, 1.0, v138
	v_rcp_f32_e32 v138, v138
	s_nop 0
	v_mul_f32_e32 v133, v133, v138
	v_cvt_pk_bf16_f32 v135, v136, v133
	ds_write_b64 v131, v[134:135] offset:256
	v_mov_b32_e32 v133, v149
	v_mul_f32_e32 v134, v54, v133
	v_mul_f32_e32 v135, 0xbfb8aa3b, v134
	v_exp_f32_e32 v135, v135
	s_nop 0
	v_add_f32_e32 v135, 1.0, v135
	v_rcp_f32_e32 v135, v135
	s_nop 0
	v_mul_f32_e32 v134, v134, v135
	v_mul_f32_e32 v135, v55, v133
	v_mul_f32_e32 v136, 0xbfb8aa3b, v135
	v_exp_f32_e32 v136, v136
	s_nop 0
	v_add_f32_e32 v136, 1.0, v136
	v_rcp_f32_e32 v136, v136
; __device__ __forceinline__ float siluf(float x) { return x * __builtin_amdgcn_rcpf(1.f + __expf(-x)); }
; #define STAGE_TILE_F(XFORM) do { SW_BEGIN f32x4 v = acc[ai][bj][m][n2]; XFORM; \
;     *(u32x2*)(smem + mrow * SPITCH + nc0 * 2) = u32x2{cvtpk_t(v[0], v[1]), cvtpk_t(v[2], v[3])}; LOOP_END __syncthreads(); } while (0)
; template <int kind> __device__ __forceinline__ void gemm_phase_n(const Params& P, int layer, int b, const int wv) {
;     ...
;                 } else if (pn < 12) {
;                     STAGE_TILE_F(const float r = rs_lds[mrow]; v[0] = siluf(v[0] * r); v[1] = siluf(v[1] * r); v[2] = siluf(v[2] * r); v[3] = siluf(v[3] * r));
;                     u16* dst = (u16*)(ws + O_SG) + (size_t)t0 * 2048 + (pn - 4) * 256;
	s_nop 0
	v_mul_f32_e32 v135, v135, v136
	v_mul_f32_e32 v136, v56, v133
	v_mul_f32_e32 v138, 0xbfb8aa3b, v136
	v_exp_f32_e32 v138, v138
	v_mul_f32_e32 v133, v57, v133
	v_cvt_pk_bf16_f32 v134, v134, v135
	v_add_f32_e32 v138, 1.0, v138
	v_rcp_f32_e32 v138, v138
	s_nop 0
	v_mul_f32_e32 v136, v136, v138
	v_mul_f32_e32 v138, 0xbfb8aa3b, v133
	v_exp_f32_e32 v138, v138
	s_nop 0
	v_add_f32_e32 v138, 1.0, v138
	v_rcp_f32_e32 v138, v138
	s_nop 0
	v_mul_f32_e32 v133, v133, v138
	v_cvt_pk_bf16_f32 v135, v136, v133
	ds_write_b64 v131, v[134:135] offset:8960
	v_mov_b32_e32 v133, v150
	v_mul_f32_e32 v134, v58, v133
	v_mul_f32_e32 v135, 0xbfb8aa3b, v134
	v_exp_f32_e32 v135, v135
	s_nop 0
	v_add_f32_e32 v135, 1.0, v135
	v_rcp_f32_e32 v135, v135
	s_nop 0
	v_mul_f32_e32 v134, v134, v135
	v_mul_f32_e32 v135, v59, v133
	v_mul_f32_e32 v136, 0xbfb8aa3b, v135
	v_exp_f32_e32 v136, v136
	s_nop 0
	v_add_f32_e32 v136, 1.0, v136
	v_rcp_f32_e32 v136, v136
	s_nop 0
	v_mul_f32_e32 v135, v135, v136
	v_mul_f32_e32 v136, v60, v133
	v_mul_f32_e32 v138, 0xbfb8aa3b, v136
	v_exp_f32_e32 v138, v138
	v_mul_f32_e32 v133, v61, v133
	v_cvt_pk_bf16_f32 v134, v134, v135
	v_add_f32_e32 v138, 1.0, v138
	v_rcp_f32_e32 v138, v138
	s_nop 0
	v_mul_f32_e32 v136, v136, v138
	v_mul_f32_e32 v138, 0xbfb8aa3b, v133
	v_exp_f32_e32 v138, v138
	s_nop 0
	v_add_f32_e32 v138, 1.0, v138
	v_rcp_f32_e32 v138, v138
	s_nop 0
	v_mul_f32_e32 v133, v133, v138
	v_cvt_pk_bf16_f32 v135, v136, v133
	ds_write_b64 v130, v[134:135] offset:61184
	v_mov_b32_e32 v133, v151
	v_mul_f32_e32 v134, v50, v133
	v_mul_f32_e32 v135, 0xbfb8aa3b, v134
	v_exp_f32_e32 v135, v135
	s_nop 0
	v_add_f32_e32 v135, 1.0, v135
	v_rcp_f32_e32 v135, v135
	s_nop 0
	v_mul_f32_e32 v134, v134, v135
	v_mul_f32_e32 v135, v51, v133
	v_mul_f32_e32 v136, 0xbfb8aa3b, v135
	v_exp_f32_e32 v136, v136
	s_nop 0
	v_add_f32_e32 v136, 1.0, v136
	v_rcp_f32_e32 v136, v136
	s_nop 0
	v_mul_f32_e32 v135, v135, v136
	v_mul_f32_e32 v136, v52, v133
	v_mul_f32_e32 v138, 0xbfb8aa3b, v136
	v_exp_f32_e32 v138, v138
	v_mul_f32_e32 v133, v53, v133
	v_cvt_pk_bf16_f32 v134, v134, v135
	v_add_f32_e32 v138, 1.0, v138
	v_rcp_f32_e32 v138, v138
	s_nop 0
	v_mul_f32_e32 v136, v136, v138
	v_mul_f32_e32 v138, 0xbfb8aa3b, v133
	v_exp_f32_e32 v138, v138
	s_nop 0
	v_add_f32_e32 v138, 1.0, v138
	v_rcp_f32_e32 v138, v138
	s_nop 0
	v_mul_f32_e32 v133, v133, v138
	v_cvt_pk_bf16_f32 v135, v136, v133
	ds_write_b64 v132, v[134:135] offset:8960
	v_mov_b32_e32 v133, v148
	v_mul_f32_e32 v134, v46, v133
	v_mul_f32_e32 v135, 0xbfb8aa3b, v134
	v_exp_f32_e32 v135, v135
	s_nop 0
	v_add_f32_e32 v135, 1.0, v135
	v_rcp_f32_e32 v135, v135
	s_nop 0
	v_mul_f32_e32 v134, v134, v135
	v_mul_f32_e32 v135, v47, v133
	v_mul_f32_e32 v136, 0xbfb8aa3b, v135
	v_exp_f32_e32 v136, v136
	s_nop 0
	v_add_f32_e32 v136, 1.0, v136
	v_rcp_f32_e32 v136, v136
	s_nop 0
	v_mul_f32_e32 v135, v135, v136
	v_mul_f32_e32 v136, v48, v133
	v_mul_f32_e32 v138, 0xbfb8aa3b, v136
	v_exp_f32_e32 v138, v138
	v_mul_f32_e32 v133, v49, v133
	v_cvt_pk_bf16_f32 v134, v134, v135
	v_add_f32_e32 v138, 1.0, v138
	v_rcp_f32_e32 v138, v138
	s_nop 0
	v_mul_f32_e32 v136, v136, v138
	v_mul_f32_e32 v138, 0xbfb8aa3b, v133
	v_exp_f32_e32 v138, v138
	s_nop 0
	v_add_f32_e32 v138, 1.0, v138
	v_rcp_f32_e32 v138, v138
	s_nop 0
	v_mul_f32_e32 v133, v133, v138
	v_cvt_pk_bf16_f32 v135, v136, v133
	ds_write_b64 v131, v[134:135] offset:288
	v_mov_b32_e32 v133, v149
	v_mul_f32_e32 v134, v38, v133
	v_mul_f32_e32 v135, 0xbfb8aa3b, v134
	v_exp_f32_e32 v135, v135
	s_nop 0
	v_add_f32_e32 v135, 1.0, v135
	v_rcp_f32_e32 v135, v135
	s_nop 0
	v_mul_f32_e32 v134, v134, v135
	v_mul_f32_e32 v135, v39, v133
	v_mul_f32_e32 v136, 0xbfb8aa3b, v135
	v_exp_f32_e32 v136, v136
	s_nop 0
	v_add_f32_e32 v136, 1.0, v136
	v_rcp_f32_e32 v136, v136
	s_nop 0
	v_mul_f32_e32 v135, v135, v136
	v_mul_f32_e32 v136, v40, v133
	v_mul_f32_e32 v138, 0xbfb8aa3b, v136
	v_exp_f32_e32 v138, v138
	v_mul_f32_e32 v133, v41, v133
	v_cvt_pk_bf16_f32 v134, v134, v135
	v_add_f32_e32 v138, 1.0, v138
	v_rcp_f32_e32 v138, v138
	s_nop 0
	v_mul_f32_e32 v136, v136, v138
	v_mul_f32_e32 v138, 0xbfb8aa3b, v133
	v_exp_f32_e32 v138, v138
	s_nop 0
	v_add_f32_e32 v138, 1.0, v138
	v_rcp_f32_e32 v138, v138
	s_nop 0
	v_mul_f32_e32 v133, v133, v138
	v_cvt_pk_bf16_f32 v135, v136, v133
	ds_write_b64 v131, v[134:135] offset:8992
	v_mov_b32_e32 v133, v150
	v_mul_f32_e32 v134, v42, v133
	v_mul_f32_e32 v135, 0xbfb8aa3b, v134
	v_exp_f32_e32 v135, v135
	s_nop 0
	v_add_f32_e32 v135, 1.0, v135
	v_rcp_f32_e32 v135, v135
	s_nop 0
	v_mul_f32_e32 v134, v134, v135
	v_mul_f32_e32 v135, v43, v133
	v_mul_f32_e32 v136, 0xbfb8aa3b, v135
	v_exp_f32_e32 v136, v136
	s_nop 0
	v_add_f32_e32 v136, 1.0, v136
	v_rcp_f32_e32 v136, v136
	s_nop 0
	v_mul_f32_e32 v135, v135, v136
	v_mul_f32_e32 v136, v44, v133
	v_mul_f32_e32 v138, 0xbfb8aa3b, v136
	v_exp_f32_e32 v138, v138
	v_mul_f32_e32 v133, v45, v133
	v_cvt_pk_bf16_f32 v134, v134, v135
	v_add_f32_e32 v138, 1.0, v138
	v_rcp_f32_e32 v138, v138
	s_nop 0
	v_mul_f32_e32 v136, v136, v138
	v_mul_f32_e32 v138, 0xbfb8aa3b, v133
	v_exp_f32_e32 v138, v138
	s_nop 0
	v_add_f32_e32 v138, 1.0, v138
	v_rcp_f32_e32 v138, v138
	s_nop 0
	v_mul_f32_e32 v133, v133, v138
	v_cvt_pk_bf16_f32 v135, v136, v133
	ds_write_b64 v130, v[134:135] offset:61216
	v_mov_b32_e32 v133, v151
	v_mul_f32_e32 v134, v34, v133
	v_mul_f32_e32 v135, 0xbfb8aa3b, v134
	v_exp_f32_e32 v135, v135
	s_nop 0
	v_add_f32_e32 v135, 1.0, v135
	v_rcp_f32_e32 v135, v135
	s_nop 0
	v_mul_f32_e32 v134, v134, v135
	v_mul_f32_e32 v135, v35, v133
	v_mul_f32_e32 v136, 0xbfb8aa3b, v135
	v_exp_f32_e32 v136, v136
	s_nop 0
	v_add_f32_e32 v136, 1.0, v136
	v_rcp_f32_e32 v136, v136
; __device__ __forceinline__ float siluf(float x) { return x * __builtin_amdgcn_rcpf(1.f + __expf(-x)); }
; #define STAGE_TILE_F(XFORM) do { SW_BEGIN f32x4 v = acc[ai][bj][m][n2]; XFORM; \
;     *(u32x2*)(smem + mrow * SPITCH + nc0 * 2) = u32x2{cvtpk_t(v[0], v[1]), cvtpk_t(v[2], v[3])}; LOOP_END __syncthreads(); } while (0)
; template <int kind> __device__ __forceinline__ void gemm_phase_n(const Params& P, int layer, int b, const int wv) {
;     ...
;                 } else if (pn < 12) {
;                     STAGE_TILE_F(const float r = rs_lds[mrow]; v[0] = siluf(v[0] * r); v[1] = siluf(v[1] * r); v[2] = siluf(v[2] * r); v[3] = siluf(v[3] * r));
;                     u16* dst = (u16*)(ws + O_SG) + (size_t)t0 * 2048 + (pn - 4) * 256;
	s_nop 0
	v_mul_f32_e32 v135, v135, v136
	v_mul_f32_e32 v136, v36, v133
	v_mul_f32_e32 v138, 0xbfb8aa3b, v136
	v_exp_f32_e32 v138, v138
	v_mul_f32_e32 v133, v37, v133
	v_cvt_pk_bf16_f32 v134, v134, v135
	v_add_f32_e32 v138, 1.0, v138
	v_rcp_f32_e32 v138, v138
	s_nop 0
	v_mul_f32_e32 v136, v136, v138
	v_mul_f32_e32 v138, 0xbfb8aa3b, v133
	v_exp_f32_e32 v138, v138
	s_nop 0
	v_add_f32_e32 v138, 1.0, v138
	v_rcp_f32_e32 v138, v138
	s_nop 0
	v_mul_f32_e32 v133, v133, v138
	v_cvt_pk_bf16_f32 v135, v136, v133
	ds_write_b64 v132, v[134:135] offset:8992
	v_mov_b32_e32 v133, v148
	v_mul_f32_e32 v134, v30, v133
	v_mul_f32_e32 v135, 0xbfb8aa3b, v134
	v_exp_f32_e32 v135, v135
	s_nop 0
	v_add_f32_e32 v135, 1.0, v135
	v_rcp_f32_e32 v135, v135
	s_nop 0
	v_mul_f32_e32 v134, v134, v135
	v_mul_f32_e32 v135, v31, v133
	v_mul_f32_e32 v136, 0xbfb8aa3b, v135
	v_exp_f32_e32 v136, v136
	s_nop 0
	v_add_f32_e32 v136, 1.0, v136
	v_rcp_f32_e32 v136, v136
	s_nop 0
	v_mul_f32_e32 v135, v135, v136
	v_mul_f32_e32 v136, v32, v133
	v_mul_f32_e32 v138, 0xbfb8aa3b, v136
	v_exp_f32_e32 v138, v138
	v_mul_f32_e32 v133, v33, v133
	v_cvt_pk_bf16_f32 v134, v134, v135
	v_add_f32_e32 v138, 1.0, v138
	v_rcp_f32_e32 v138, v138
	s_nop 0
	v_mul_f32_e32 v136, v136, v138
	v_mul_f32_e32 v138, 0xbfb8aa3b, v133
	v_exp_f32_e32 v138, v138
	s_nop 0
	v_add_f32_e32 v138, 1.0, v138
	v_rcp_f32_e32 v138, v138
	s_nop 0
	v_mul_f32_e32 v133, v133, v138
	v_cvt_pk_bf16_f32 v135, v136, v133
	ds_write_b64 v131, v[134:135] offset:320
	v_mov_b32_e32 v133, v149
	v_mul_f32_e32 v134, v22, v133
	v_mul_f32_e32 v135, 0xbfb8aa3b, v134
	v_exp_f32_e32 v135, v135
	s_nop 0
	v_add_f32_e32 v135, 1.0, v135
	v_rcp_f32_e32 v135, v135
	s_nop 0
	v_mul_f32_e32 v134, v134, v135
	v_mul_f32_e32 v135, v23, v133
	v_mul_f32_e32 v136, 0xbfb8aa3b, v135
	v_exp_f32_e32 v136, v136
	s_nop 0
	v_add_f32_e32 v136, 1.0, v136
	v_rcp_f32_e32 v136, v136
	s_nop 0
	v_mul_f32_e32 v135, v135, v136
	v_mul_f32_e32 v136, v24, v133
	v_mul_f32_e32 v138, 0xbfb8aa3b, v136
	v_exp_f32_e32 v138, v138
	v_mul_f32_e32 v133, v25, v133
	v_cvt_pk_bf16_f32 v134, v134, v135
	v_add_f32_e32 v138, 1.0, v138
	v_rcp_f32_e32 v138, v138
	s_nop 0
	v_mul_f32_e32 v136, v136, v138
	v_mul_f32_e32 v138, 0xbfb8aa3b, v133
	v_exp_f32_e32 v138, v138
	s_nop 0
	v_add_f32_e32 v138, 1.0, v138
	v_rcp_f32_e32 v138, v138
	s_nop 0
	v_mul_f32_e32 v133, v133, v138
	v_cvt_pk_bf16_f32 v135, v136, v133
	ds_write_b64 v131, v[134:135] offset:9024
	v_mov_b32_e32 v133, v150
	v_mul_f32_e32 v134, v26, v133
	v_mul_f32_e32 v135, 0xbfb8aa3b, v134
	v_exp_f32_e32 v135, v135
	s_nop 0
	v_add_f32_e32 v135, 1.0, v135
	v_rcp_f32_e32 v135, v135
	s_nop 0
	v_mul_f32_e32 v134, v134, v135
	v_mul_f32_e32 v135, v27, v133
	v_mul_f32_e32 v136, 0xbfb8aa3b, v135
	v_exp_f32_e32 v136, v136
	s_nop 0
	v_add_f32_e32 v136, 1.0, v136
	v_rcp_f32_e32 v136, v136
	s_nop 0
	v_mul_f32_e32 v135, v135, v136
	v_mul_f32_e32 v136, v28, v133
	v_mul_f32_e32 v138, 0xbfb8aa3b, v136
	v_exp_f32_e32 v138, v138
	v_mul_f32_e32 v133, v29, v133
	v_cvt_pk_bf16_f32 v134, v134, v135
	v_add_f32_e32 v138, 1.0, v138
	v_rcp_f32_e32 v138, v138
	s_nop 0
	v_mul_f32_e32 v136, v136, v138
	v_mul_f32_e32 v138, 0xbfb8aa3b, v133
	v_exp_f32_e32 v138, v138
	s_nop 0
	v_add_f32_e32 v138, 1.0, v138
	v_rcp_f32_e32 v138, v138
	s_nop 0
	v_mul_f32_e32 v133, v133, v138
	v_cvt_pk_bf16_f32 v135, v136, v133
	ds_write_b64 v130, v[134:135] offset:61248
	v_mov_b32_e32 v133, v151
	v_mul_f32_e32 v134, v18, v133
	v_mul_f32_e32 v135, 0xbfb8aa3b, v134
	v_exp_f32_e32 v135, v135
	s_nop 0
	v_add_f32_e32 v135, 1.0, v135
	v_rcp_f32_e32 v135, v135
	s_nop 0
	v_mul_f32_e32 v134, v134, v135
	v_mul_f32_e32 v135, v19, v133
	v_mul_f32_e32 v136, 0xbfb8aa3b, v135
	v_exp_f32_e32 v136, v136
	s_nop 0
	v_add_f32_e32 v136, 1.0, v136
	v_rcp_f32_e32 v136, v136
	s_nop 0
	v_mul_f32_e32 v135, v135, v136
	v_mul_f32_e32 v136, v20, v133
	v_mul_f32_e32 v138, 0xbfb8aa3b, v136
	v_exp_f32_e32 v138, v138
	v_mul_f32_e32 v133, v21, v133
	v_cvt_pk_bf16_f32 v134, v134, v135
	v_add_f32_e32 v138, 1.0, v138
	v_rcp_f32_e32 v138, v138
	s_nop 0
	v_mul_f32_e32 v136, v136, v138
	v_mul_f32_e32 v138, 0xbfb8aa3b, v133
	v_exp_f32_e32 v138, v138
	s_nop 0
	v_add_f32_e32 v138, 1.0, v138
	v_rcp_f32_e32 v138, v138
	s_nop 0
	v_mul_f32_e32 v133, v133, v138
	v_cvt_pk_bf16_f32 v135, v136, v133
; __device__ __forceinline__ float siluf(float x) { return x * __builtin_amdgcn_rcpf(1.f + __expf(-x)); }
; #define STAGE_TILE_F(XFORM) do { SW_BEGIN f32x4 v = acc[ai][bj][m][n2]; XFORM; \
;     *(u32x2*)(smem + mrow * SPITCH + nc0 * 2) = u32x2{cvtpk_t(v[0], v[1]), cvtpk_t(v[2], v[3])}; LOOP_END __syncthreads(); } while (0)
; template <int kind> __device__ __forceinline__ void gemm_phase_n(const Params& P, int layer, int b, const int wv) {
;     ...
;                 } else if (pn < 12) {
;                     STAGE_TILE_F(const float r = rs_lds[mrow]; v[0] = siluf(v[0] * r); v[1] = siluf(v[1] * r); v[2] = siluf(v[2] * r); v[3] = siluf(v[3] * r));
;                     u16* dst = (u16*)(ws + O_SG) + (size_t)t0 * 2048 + (pn - 4) * 256;
;                     DRAIN_BEGIN *(u32x4*)(dst + (size_t)row * 2048 + chunk * 8) = w; LOOP_END
	ds_write_b64 v132, v[134:135] offset:9024
	v_mov_b32_e32 v133, v148
	v_mul_f32_e32 v134, v14, v133
	v_mul_f32_e32 v135, 0xbfb8aa3b, v134
	v_exp_f32_e32 v135, v135
	s_nop 0
	v_add_f32_e32 v135, 1.0, v135
	v_rcp_f32_e32 v135, v135
	s_nop 0
	v_mul_f32_e32 v134, v134, v135
	v_mul_f32_e32 v135, v15, v133
	v_mul_f32_e32 v136, 0xbfb8aa3b, v135
	v_exp_f32_e32 v136, v136
	s_nop 0
	v_add_f32_e32 v136, 1.0, v136
	v_rcp_f32_e32 v136, v136
	s_nop 0
	v_mul_f32_e32 v135, v135, v136
	v_mul_f32_e32 v136, v16, v133
	v_mul_f32_e32 v138, 0xbfb8aa3b, v136
	v_exp_f32_e32 v138, v138
	v_mul_f32_e32 v133, v17, v133
	v_cvt_pk_bf16_f32 v134, v134, v135
	v_add_f32_e32 v138, 1.0, v138
	v_rcp_f32_e32 v138, v138
	s_nop 0
	v_mul_f32_e32 v136, v136, v138
	v_mul_f32_e32 v138, 0xbfb8aa3b, v133
	v_exp_f32_e32 v138, v138
	s_nop 0
	v_add_f32_e32 v138, 1.0, v138
	v_rcp_f32_e32 v138, v138
	s_nop 0
	v_mul_f32_e32 v133, v133, v138
	v_cvt_pk_bf16_f32 v135, v136, v133
	ds_write_b64 v131, v[134:135] offset:352
	v_mov_b32_e32 v133, v149
	v_mul_f32_e32 v134, v2, v133
	v_mul_f32_e32 v135, 0xbfb8aa3b, v134
	v_exp_f32_e32 v135, v135
	s_nop 0
	v_add_f32_e32 v135, 1.0, v135
	v_rcp_f32_e32 v135, v135
	s_nop 0
	v_mul_f32_e32 v134, v134, v135
	v_mul_f32_e32 v135, v3, v133
	v_mul_f32_e32 v136, 0xbfb8aa3b, v135
	v_exp_f32_e32 v136, v136
	s_nop 0
	v_add_f32_e32 v136, 1.0, v136
	v_rcp_f32_e32 v136, v136
	s_nop 0
	v_mul_f32_e32 v135, v135, v136
	v_mul_f32_e32 v136, v4, v133
	v_mul_f32_e32 v138, 0xbfb8aa3b, v136
	v_exp_f32_e32 v138, v138
	v_mul_f32_e32 v133, v5, v133
	v_cvt_pk_bf16_f32 v134, v134, v135
	v_add_f32_e32 v138, 1.0, v138
	v_rcp_f32_e32 v138, v138
	s_nop 0
	v_mul_f32_e32 v136, v136, v138
	v_mul_f32_e32 v138, 0xbfb8aa3b, v133
	v_exp_f32_e32 v138, v138
	s_nop 0
	v_add_f32_e32 v138, 1.0, v138
	v_rcp_f32_e32 v138, v138
	s_nop 0
	v_mul_f32_e32 v133, v133, v138
	v_cvt_pk_bf16_f32 v135, v136, v133
	ds_write_b64 v131, v[134:135] offset:9056
	v_mov_b32_e32 v131, v150
	v_mul_f32_e32 v133, v10, v131
	v_mul_f32_e32 v134, 0xbfb8aa3b, v133
	v_exp_f32_e32 v134, v134
	s_nop 0
	v_add_f32_e32 v134, 1.0, v134
	v_rcp_f32_e32 v134, v134
	s_nop 0
	v_mul_f32_e32 v133, v133, v134
	v_mul_f32_e32 v134, v11, v131
	v_mul_f32_e32 v135, 0xbfb8aa3b, v134
	v_exp_f32_e32 v135, v135
	s_nop 0
	v_add_f32_e32 v135, 1.0, v135
	v_rcp_f32_e32 v135, v135
	s_nop 0
	v_mul_f32_e32 v134, v134, v135
	v_mul_f32_e32 v135, v12, v131
	v_mul_f32_e32 v136, 0xbfb8aa3b, v135
	v_exp_f32_e32 v136, v136
	v_mul_f32_e32 v131, v13, v131
	v_cvt_pk_bf16_f32 v134, v133, v134
	v_add_f32_e32 v136, 1.0, v136
	v_rcp_f32_e32 v136, v136
	s_nop 0
	v_mul_f32_e32 v135, v135, v136
	v_mul_f32_e32 v136, 0xbfb8aa3b, v131
	v_exp_f32_e32 v136, v136
	s_nop 0
	v_add_f32_e32 v136, 1.0, v136
	v_rcp_f32_e32 v136, v136
	s_nop 0
	v_mul_f32_e32 v131, v131, v136
	v_cvt_pk_bf16_f32 v135, v135, v131
	ds_write_b64 v130, v[134:135] offset:61280
	v_mov_b32_e32 v0, v151
	v_mul_f32_e32 v130, v6, v0
	v_mul_f32_e32 v131, 0xbfb8aa3b, v130
	v_exp_f32_e32 v131, v131
	s_nop 0
	v_add_f32_e32 v131, 1.0, v131
	v_rcp_f32_e32 v131, v131
	s_nop 0
	v_mul_f32_e32 v130, v130, v131
	v_mul_f32_e32 v131, v7, v0
	v_mul_f32_e32 v133, 0xbfb8aa3b, v131
	v_exp_f32_e32 v133, v133
	s_nop 0
	v_add_f32_e32 v133, 1.0, v133
	v_rcp_f32_e32 v133, v133
	s_nop 0
	v_mul_f32_e32 v131, v131, v133
	v_mul_f32_e32 v133, v8, v0
	v_mul_f32_e32 v134, 0xbfb8aa3b, v133
	v_exp_f32_e32 v134, v134
	v_mul_f32_e32 v0, v9, v0
	v_cvt_pk_bf16_f32 v130, v130, v131
	v_add_f32_e32 v134, 1.0, v134
	v_rcp_f32_e32 v134, v134
	s_nop 0
	v_mul_f32_e32 v133, v133, v134
	v_mul_f32_e32 v134, 0xbfb8aa3b, v0
	v_exp_f32_e32 v134, v134
	s_nop 0
	v_add_f32_e32 v134, 1.0, v134
	v_rcp_f32_e32 v134, v134
	s_nop 0
	v_mul_f32_e32 v0, v0, v134
	v_cvt_pk_bf16_f32 v131, v133, v0
	ds_write_b64 v132, v[130:131] offset:9056
	v_ashrrev_i32_e32 v132, 5, v137
	v_ashrrev_i32_e32 v133, 31, v132
	v_lshlrev_b64 v[130:131], 12, v[132:133]
	v_lshlrev_b32_e32 v0, 4, v137
	v_lshl_add_u64 v[130:131], v[130:131], 0, s[2:3]
	s_lshl_b64 s[2:3], s[14:15], 1
	v_and_b32_e32 v0, 0x1f0, v0
	s_add_u32 s2, s21, s2
	v_or_b32_e32 v130, v130, v0
	s_addc_u32 s3, s22, s3
	v_lshl_add_u64 v[130:131], s[2:3], 0, v[130:131]
	s_movk_i32 s2, 0x220
	v_mul_lo_u32 v132, v132, s2
	v_add3_u32 v0, v132, v0, 0
	s_mov_b64 s[2:3], 0
	s_waitcnt vmcnt(0) lgkmcnt(0)
	s_barrier

; #define STAGE_TILE_F(XFORM) do { SW_BEGIN f32x4 v = acc[ai][bj][m][n2]; XFORM; \
;     *(u32x2*)(smem + mrow * SPITCH + nc0 * 2) = u32x2{cvtpk_t(v[0], v[1]), cvtpk_t(v[2], v[3])}; LOOP_END __syncthreads(); } while (0)
; template <int kind> __device__ __forceinline__ void gemm_phase_n(const Params& P, int layer, int b, const int wv) {
;     ...
;                 if (pn < 4) {
;                     STAGE_TILE_F(v *= rs_lds[mrow]);
;                     u16* dst = (pn < 3) ? (u16*)(ws + O_CQ) + (size_t)s0 * 768 + pn * 256 : (u16*)(ws + O_CKV) + (size_t)s0 * 256; const int ldd = pn < 3 ? 768 : 256;
.LBB0_686:
	s_andn2_b64 vcc, exec, s[2:3]
	s_cbranch_vccnz .LBB0_666
	v_lshl_or_b32 v132, v140, 5, v141
	v_lshl_add_u32 v0, v132, 2, 0
	v_add_u32_e32 v133, 0x22000, v0
	ds_read_b32 v134, v133
	ds_read_b32 v135, v133 offset:64
	ds_read_b32 v136, v133 offset:512
	ds_read_b32 v138, v133 offset:576
	s_waitcnt lgkmcnt(0)
	v_mov_b32_e32 v0, v134
	v_lshlrev_b32_e32 v130, 7, v142
	v_lshl_add_u32 v131, v143, 3, 0
	s_lshr_b32 s2, s13, 24
	s_cmp_lg_u32 s2, 3
	v_pk_mul_f32 v[128:129], v[128:129], v[0:1] op_sel_hi:[1,0]
	v_pk_mul_f32 v[126:127], v[126:127], v[0:1] op_sel_hi:[1,0]
	v_mul_u32_u24_e32 v0, 0x220, v132
	v_cvt_pk_bf16_f32 v126, v126, v127
	v_cvt_pk_bf16_f32 v127, v128, v129
	v_add3_u32 v128, v131, v130, v0
	ds_write_b64 v128, v[126:127]
	v_mov_b32_e32 v0, v135
	v_add_u32_e32 v126, 0x2200, v128
	s_cselect_b64 s[2:3], -1, 0
	s_ashr_i32 s13, s12, 31
	s_mov_b64 s[18:19], -1
	v_pk_mul_f32 v[118:119], v[118:119], v[0:1] op_sel_hi:[1,0]
	v_pk_mul_f32 v[120:121], v[120:121], v[0:1] op_sel_hi:[1,0]
	v_cvt_pk_bf16_f32 v118, v118, v119
	s_and_b64 vcc, exec, s[2:3]
	v_cvt_pk_bf16_f32 v119, v120, v121
	ds_write_b64 v128, v[118:119] offset:8704
	v_mov_b32_e32 v0, v136
	v_pk_mul_f32 v[120:121], v[122:123], v[0:1] op_sel_hi:[1,0]
	v_pk_mul_f32 v[118:119], v[124:125], v[0:1] op_sel_hi:[1,0]
	v_cvt_pk_bf16_f32 v120, v120, v121
	s_nop 0
	v_cvt_pk_bf16_f32 v121, v118, v119
	ds_write_b64 v126, v[120:121] offset:60928
	v_mov_b32_e32 v0, v138
	v_add_u32_e32 v118, 0xee00, v126
	v_pk_mul_f32 v[114:115], v[114:115], v[0:1] op_sel_hi:[1,0]
	v_pk_mul_f32 v[116:117], v[116:117], v[0:1] op_sel_hi:[1,0]
	v_cvt_pk_bf16_f32 v114, v114, v115
	s_nop 0
	v_cvt_pk_bf16_f32 v115, v116, v117
	ds_write_b64 v118, v[114:115] offset:8704
	s_waitcnt vmcnt(0)
	v_mov_b32_e32 v0, v134
	v_pk_mul_f32 v[110:111], v[110:111], v[0:1] op_sel_hi:[1,0]
	v_pk_mul_f32 v[112:113], v[112:113], v[0:1] op_sel_hi:[1,0]
	v_cvt_pk_bf16_f32 v110, v110, v111
	s_nop 0
	v_cvt_pk_bf16_f32 v111, v112, v113
	ds_write_b64 v128, v[110:111] offset:32
	v_mov_b32_e32 v0, v135
	v_pk_mul_f32 v[102:103], v[102:103], v[0:1] op_sel_hi:[1,0]
	v_pk_mul_f32 v[104:105], v[104:105], v[0:1] op_sel_hi:[1,0]
	v_cvt_pk_bf16_f32 v102, v102, v103
	s_nop 0
	v_cvt_pk_bf16_f32 v103, v104, v105
	ds_write_b64 v128, v[102:103] offset:8736
	v_mov_b32_e32 v0, v136
	v_pk_mul_f32 v[104:105], v[106:107], v[0:1] op_sel_hi:[1,0]
	v_pk_mul_f32 v[102:103], v[108:109], v[0:1] op_sel_hi:[1,0]
	v_cvt_pk_bf16_f32 v104, v104, v105
	s_nop 0
	v_cvt_pk_bf16_f32 v105, v102, v103
	ds_write_b64 v126, v[104:105] offset:60960
	v_mov_b32_e32 v0, v138
	v_pk_mul_f32 v[98:99], v[98:99], v[0:1] op_sel_hi:[1,0]
	v_pk_mul_f32 v[100:101], v[100:101], v[0:1] op_sel_hi:[1,0]
	v_cvt_pk_bf16_f32 v98, v98, v99
	s_nop 0
	v_cvt_pk_bf16_f32 v99, v100, v101
	ds_write_b64 v118, v[98:99] offset:8736
	v_mov_b32_e32 v0, v134
	v_pk_mul_f32 v[94:95], v[94:95], v[0:1] op_sel_hi:[1,0]
	v_pk_mul_f32 v[96:97], v[96:97], v[0:1] op_sel_hi:[1,0]
	v_cvt_pk_bf16_f32 v94, v94, v95
	s_nop 0
	v_cvt_pk_bf16_f32 v95, v96, v97
	ds_write_b64 v128, v[94:95] offset:64
	v_mov_b32_e32 v0, v135
	v_pk_mul_f32 v[86:87], v[86:87], v[0:1] op_sel_hi:[1,0]
	v_pk_mul_f32 v[88:89], v[88:89], v[0:1] op_sel_hi:[1,0]
	v_cvt_pk_bf16_f32 v86, v86, v87
	s_nop 0
	v_cvt_pk_bf16_f32 v87, v88, v89
	ds_write_b64 v128, v[86:87] offset:8768
	v_mov_b32_e32 v0, v136
	v_pk_mul_f32 v[88:89], v[90:91], v[0:1] op_sel_hi:[1,0]
	v_pk_mul_f32 v[86:87], v[92:93], v[0:1] op_sel_hi:[1,0]
	v_cvt_pk_bf16_f32 v88, v88, v89
	s_nop 0
	v_cvt_pk_bf16_f32 v89, v86, v87
	ds_write_b64 v126, v[88:89] offset:60992
	v_mov_b32_e32 v0, v138
	v_pk_mul_f32 v[82:83], v[82:83], v[0:1] op_sel_hi:[1,0]
	v_pk_mul_f32 v[84:85], v[84:85], v[0:1] op_sel_hi:[1,0]
	v_cvt_pk_bf16_f32 v82, v82, v83
	s_nop 0
	v_cvt_pk_bf16_f32 v83, v84, v85
	ds_write_b64 v118, v[82:83] offset:8768
	v_mov_b32_e32 v0, v134
	v_pk_mul_f32 v[78:79], v[78:79], v[0:1] op_sel_hi:[1,0]
	v_pk_mul_f32 v[80:81], v[80:81], v[0:1] op_sel_hi:[1,0]
	v_cvt_pk_bf16_f32 v78, v78, v79
	s_nop 0
	v_cvt_pk_bf16_f32 v79, v80, v81
	ds_write_b64 v128, v[78:79] offset:96
	v_mov_b32_e32 v0, v135
	v_pk_mul_f32 v[70:71], v[70:71], v[0:1] op_sel_hi:[1,0]
	v_pk_mul_f32 v[72:73], v[72:73], v[0:1] op_sel_hi:[1,0]
	v_cvt_pk_bf16_f32 v70, v70, v71
	s_nop 0
	v_cvt_pk_bf16_f32 v71, v72, v73
	ds_write_b64 v128, v[70:71] offset:8800
	v_mov_b32_e32 v0, v136
	v_pk_mul_f32 v[72:73], v[74:75], v[0:1] op_sel_hi:[1,0]
	v_pk_mul_f32 v[70:71], v[76:77], v[0:1] op_sel_hi:[1,0]
	v_cvt_pk_bf16_f32 v72, v72, v73
; #define STAGE_TILE_F(XFORM) do { SW_BEGIN f32x4 v = acc[ai][bj][m][n2]; XFORM; \
;     *(u32x2*)(smem + mrow * SPITCH + nc0 * 2) = u32x2{cvtpk_t(v[0], v[1]), cvtpk_t(v[2], v[3])}; LOOP_END __syncthreads(); } while (0)
; template <int kind> __device__ __forceinline__ void gemm_phase_n(const Params& P, int layer, int b, const int wv) {
;     ...
;                 if (pn < 4) {
;                     STAGE_TILE_F(v *= rs_lds[mrow]);
;                     u16* dst = (pn < 3) ? (u16*)(ws + O_CQ) + (size_t)s0 * 768 + pn * 256 : (u16*)(ws + O_CKV) + (size_t)s0 * 256; const int ldd = pn < 3 ? 768 : 256;
	s_nop 0
	v_cvt_pk_bf16_f32 v73, v70, v71
	ds_write_b64 v126, v[72:73] offset:61024
	v_mov_b32_e32 v0, v138
	v_pk_mul_f32 v[62:63], v[62:63], v[0:1] op_sel_hi:[1,0]
	v_pk_mul_f32 v[64:65], v[64:65], v[0:1] op_sel_hi:[1,0]
	v_cvt_pk_bf16_f32 v62, v62, v63
	s_nop 0
	v_cvt_pk_bf16_f32 v63, v64, v65
	ds_write_b64 v118, v[62:63] offset:8800
	v_mov_b32_e32 v0, v134
	v_pk_mul_f32 v[64:65], v[66:67], v[0:1] op_sel_hi:[1,0]
	v_pk_mul_f32 v[62:63], v[68:69], v[0:1] op_sel_hi:[1,0]
	v_cvt_pk_bf16_f32 v64, v64, v65
	s_nop 0
	v_cvt_pk_bf16_f32 v65, v62, v63
	ds_write_b64 v128, v[64:65] offset:256
	v_mov_b32_e32 v0, v135
	v_pk_mul_f32 v[54:55], v[54:55], v[0:1] op_sel_hi:[1,0]
	v_pk_mul_f32 v[56:57], v[56:57], v[0:1] op_sel_hi:[1,0]
	v_cvt_pk_bf16_f32 v54, v54, v55
	s_nop 0
	v_cvt_pk_bf16_f32 v55, v56, v57
	ds_write_b64 v128, v[54:55] offset:8960
	v_mov_b32_e32 v0, v136
	v_pk_mul_f32 v[56:57], v[58:59], v[0:1] op_sel_hi:[1,0]
	v_pk_mul_f32 v[54:55], v[60:61], v[0:1] op_sel_hi:[1,0]
	v_cvt_pk_bf16_f32 v56, v56, v57
	s_nop 0
	v_cvt_pk_bf16_f32 v57, v54, v55
	ds_write_b64 v126, v[56:57] offset:61184
	v_mov_b32_e32 v0, v138
	v_pk_mul_f32 v[50:51], v[50:51], v[0:1] op_sel_hi:[1,0]
	v_pk_mul_f32 v[52:53], v[52:53], v[0:1] op_sel_hi:[1,0]
	v_cvt_pk_bf16_f32 v50, v50, v51
	s_nop 0
	v_cvt_pk_bf16_f32 v51, v52, v53
	ds_write_b64 v118, v[50:51] offset:8960
	v_mov_b32_e32 v0, v134
	v_pk_mul_f32 v[46:47], v[46:47], v[0:1] op_sel_hi:[1,0]
	v_pk_mul_f32 v[48:49], v[48:49], v[0:1] op_sel_hi:[1,0]
	v_cvt_pk_bf16_f32 v46, v46, v47
	s_nop 0
	v_cvt_pk_bf16_f32 v47, v48, v49
	ds_write_b64 v128, v[46:47] offset:288
	v_mov_b32_e32 v0, v135
	v_pk_mul_f32 v[38:39], v[38:39], v[0:1] op_sel_hi:[1,0]
	v_pk_mul_f32 v[40:41], v[40:41], v[0:1] op_sel_hi:[1,0]
	v_cvt_pk_bf16_f32 v38, v38, v39
	s_nop 0
	v_cvt_pk_bf16_f32 v39, v40, v41
	ds_write_b64 v128, v[38:39] offset:8992
	v_mov_b32_e32 v0, v136
	v_pk_mul_f32 v[40:41], v[42:43], v[0:1] op_sel_hi:[1,0]
	v_pk_mul_f32 v[38:39], v[44:45], v[0:1] op_sel_hi:[1,0]
	v_cvt_pk_bf16_f32 v40, v40, v41
	s_nop 0
	v_cvt_pk_bf16_f32 v41, v38, v39
	ds_write_b64 v126, v[40:41] offset:61216
	v_mov_b32_e32 v0, v138
	v_pk_mul_f32 v[34:35], v[34:35], v[0:1] op_sel_hi:[1,0]
	v_pk_mul_f32 v[36:37], v[36:37], v[0:1] op_sel_hi:[1,0]
	v_cvt_pk_bf16_f32 v34, v34, v35
	s_nop 0
	v_cvt_pk_bf16_f32 v35, v36, v37
	ds_write_b64 v118, v[34:35] offset:8992
	v_mov_b32_e32 v0, v134
	v_pk_mul_f32 v[30:31], v[30:31], v[0:1] op_sel_hi:[1,0]
	v_pk_mul_f32 v[32:33], v[32:33], v[0:1] op_sel_hi:[1,0]
	v_cvt_pk_bf16_f32 v30, v30, v31
	s_nop 0
	v_cvt_pk_bf16_f32 v31, v32, v33
	ds_write_b64 v128, v[30:31] offset:320
	v_mov_b32_e32 v0, v135
	v_pk_mul_f32 v[22:23], v[22:23], v[0:1] op_sel_hi:[1,0]
	v_pk_mul_f32 v[24:25], v[24:25], v[0:1] op_sel_hi:[1,0]
	v_cvt_pk_bf16_f32 v22, v22, v23
	s_nop 0
	v_cvt_pk_bf16_f32 v23, v24, v25
	ds_write_b64 v128, v[22:23] offset:9024
	v_mov_b32_e32 v0, v136
	v_pk_mul_f32 v[24:25], v[26:27], v[0:1] op_sel_hi:[1,0]
	v_pk_mul_f32 v[22:23], v[28:29], v[0:1] op_sel_hi:[1,0]
	v_cvt_pk_bf16_f32 v24, v24, v25
	s_nop 0
	v_cvt_pk_bf16_f32 v25, v22, v23
	ds_write_b64 v126, v[24:25] offset:61248
	v_mov_b32_e32 v0, v138
	v_pk_mul_f32 v[18:19], v[18:19], v[0:1] op_sel_hi:[1,0]
	v_pk_mul_f32 v[20:21], v[20:21], v[0:1] op_sel_hi:[1,0]
	v_cvt_pk_bf16_f32 v18, v18, v19
	s_nop 0
	v_cvt_pk_bf16_f32 v19, v20, v21
	ds_write_b64 v118, v[18:19] offset:9024
	v_mov_b32_e32 v0, v134
	v_pk_mul_f32 v[14:15], v[14:15], v[0:1] op_sel_hi:[1,0]
	v_pk_mul_f32 v[16:17], v[16:17], v[0:1] op_sel_hi:[1,0]
	v_cvt_pk_bf16_f32 v14, v14, v15
	s_nop 0
	v_cvt_pk_bf16_f32 v15, v16, v17
	ds_write_b64 v128, v[14:15] offset:352
	v_mov_b32_e32 v0, v135
	v_pk_mul_f32 v[2:3], v[2:3], v[0:1] op_sel_hi:[1,0]
	v_pk_mul_f32 v[4:5], v[4:5], v[0:1] op_sel_hi:[1,0]
	v_cvt_pk_bf16_f32 v2, v2, v3
	s_nop 0
	v_cvt_pk_bf16_f32 v3, v4, v5
	ds_write_b64 v128, v[2:3] offset:9056
	v_mov_b32_e32 v0, v136
	v_pk_mul_f32 v[4:5], v[10:11], v[0:1] op_sel_hi:[1,0]
	v_pk_mul_f32 v[2:3], v[12:13], v[0:1] op_sel_hi:[1,0]
	v_cvt_pk_bf16_f32 v4, v4, v5
	s_nop 0
	v_cvt_pk_bf16_f32 v5, v2, v3
	ds_write_b64 v126, v[4:5] offset:61280
	v_mov_b32_e32 v0, v138
	v_pk_mul_f32 v[4:5], v[6:7], v[0:1] op_sel_hi:[1,0]
	v_pk_mul_f32 v[2:3], v[8:9], v[0:1] op_sel_hi:[1,0]
	v_cvt_pk_bf16_f32 v4, v4, v5
	s_nop 0
	v_cvt_pk_bf16_f32 v5, v2, v3
	ds_write_b64 v118, v[4:5] offset:9056
	s_waitcnt lgkmcnt(0)
	s_barrier
	s_cbranch_vccnz .LBB0_702
	s_andn2_b64 vcc, exec, s[18:19]
	s_mov_b64 s[14:15], 0x300
	s_cbranch_vccz .LBB0_703

; __device__ __forceinline__ float siluf(float x) { return x * __builtin_amdgcn_rcpf(1.f + __expf(-x)); }
; __device__ __forceinline__ float log2gamma(int h) { return log2f(1.f - exp2f(-5.f - (float)h)); }
; #define STAGE_TILE() do { SW_BEGIN const f32x4 v_ = acc[ai][bj][m][n2]; \
;     *(u32x2*)(smem + mrow * SPITCH + nc0 * 2) = u32x2{cvtpk(v_[0], v_[1]), cvtpk(v_[2], v_[3])}; LOOP_END __syncthreads(); } while (0)
; #define STAGE_TILE_F(XFORM) do { SW_BEGIN f32x4 v = acc[ai][bj][m][n2]; XFORM; \
;     *(u32x2*)(smem + mrow * SPITCH + nc0 * 2) = u32x2{cvtpk_t(v[0], v[1]), cvtpk_t(v[2], v[3])}; LOOP_END __syncthreads(); } while (0)
; template <int kind> __device__ __forceinline__ void gemm_phase_n(const Params& P, int layer, int b, const int wv) {
;     ...
;             case G_RETIN: {
;                 const int t0 = tb0 + pm * 256;
;                 if (pn < 8) {
;                     const bool isk = pn >= 4; const int h = pn & 3, item = h * 32 + pm; const float l2g = isk ? -log2gamma(h) : log2gamma(h); const float mul = isk ? 0.0625f : 1.f;
;                     ROPE_RET(rs_lds[mrow] * mul * exp2f((float)(mrow + 1) * l2g));
;                     STAGE_TILE();
;                     u16* dst = isk ? (u16*)(ws + O_KINV) + (size_t)item * 256 * 256 : (u16*)(ws + O_AQ) + (size_t)item * 256 * 512 + 256; const int ldd = isk ? 256 : 512;
;                     DRAIN_BEGIN *(u32x4*)(dst + (size_t)row * ldd + chunk * 8) = w; LOOP_END
;                     if (isk) { u16* Kdt = (u16*)(ws + O_KDT) + (size_t)item * 256 * 256; TDRAIN(Kdt, 256); }
;                 } else if (pn < 16) {
;                     const int h = (pn - 8) >> 1, half = (pn - 8) & 1, item = h * 32 + pm;
;                     STAGE_TILE_F(v *= rs_lds[mrow]);
;                     u16* VS = (u16*)(ws + O_VS) + ((size_t)item * 512 + half * 256) * 512; TDRAIN(VS, 512);
;                 } else {
;                     STAGE_TILE_F(const float r = rs_lds[mrow]; v[0] = siluf(v[0] * r); v[1] = siluf(v[1] * r); v[2] = siluf(v[2] * r); v[3] = siluf(v[3] * r));
.LBB0_719:
	s_or_b64 exec, exec, s[2:3]
	v_mov_b32_e32 v0, v1
	s_cmp_gt_i32 s34, 7
	v_mbcnt_lo_u32_b32 v0, -1, v0
	v_mbcnt_hi_u32_b32 v0, -1, v0
	v_or_b32_e32 v132, s57, v0
	s_mov_b64 s[2:3], -1
	v_ashrrev_i32_e32 v133, 8, v132
	v_bfe_u32 v136, v132, 6, 2
	v_and_b32_e32 v135, 15, v132
	v_bfe_u32 v134, v132, 4, 2
	s_cbranch_scc0 .LBB0_728
	s_and_b32 s2, s34, 0xffff
	s_cmp_lt_u32 s2, 16
	s_mov_b64 s[2:3], -1
	s_cbranch_scc1 .LBB0_724
	v_lshl_or_b32 v137, v136, 5, v135
	v_lshl_add_u32 v0, v137, 2, 0
	v_add_u32_e32 v0, 0x22000, v0
	ds_read_b32 v148, v0
	ds_read_b32 v149, v0 offset:64
	ds_read_b32 v150, v0 offset:512
	ds_read_b32 v151, v0 offset:576
	s_waitcnt lgkmcnt(0)
	v_mov_b32_e32 v138, v148
	v_lshlrev_b32_e32 v130, 7, v133
	v_lshl_add_u32 v131, v134, 3, 0
	v_mul_u32_u24_e32 v137, 0x220, v137
	v_add3_u32 v131, v131, v130, v137
	v_mul_f32_e32 v139, v122, v138
	v_mul_f32_e32 v140, 0xbfb8aa3b, v139
	v_exp_f32_e32 v140, v140
	s_lshl_b64 s[2:3], s[4:5], 12
	s_mov_b32 s15, s73
	v_add_f32_e32 v140, 1.0, v140
	v_rcp_f32_e32 v140, v140
	s_nop 0
	v_mul_f32_e32 v139, v139, v140
	v_mul_f32_e32 v140, v123, v138
	v_mul_f32_e32 v141, 0xbfb8aa3b, v140
	v_exp_f32_e32 v141, v141
	s_nop 0
	v_add_f32_e32 v141, 1.0, v141
	v_rcp_f32_e32 v141, v141
	s_nop 0
	v_mul_f32_e32 v140, v140, v141
	v_mul_f32_e32 v141, v124, v138
	v_mul_f32_e32 v142, 0xbfb8aa3b, v141
	v_exp_f32_e32 v142, v142
	v_mul_f32_e32 v138, v125, v138
	v_add_f32_e32 v142, 1.0, v142
	v_rcp_f32_e32 v142, v142
	s_nop 0
	v_mul_f32_e32 v141, v141, v142
	v_mul_f32_e32 v142, 0xbfb8aa3b, v138
	v_exp_f32_e32 v142, v142
	s_nop 0
	v_add_f32_e32 v142, 1.0, v142
	v_rcp_f32_e32 v142, v142
	s_nop 0
	v_mul_f32_e32 v142, v138, v142
	v_cvt_pk_bf16_f32 v138, v139, v140
	v_cvt_pk_bf16_f32 v139, v141, v142
	ds_write_b64 v131, v[138:139]
	v_mov_b32_e32 v130, v149
	v_mul_f32_e32 v137, v90, v130
	v_mul_f32_e32 v138, 0xbfb8aa3b, v137
	v_exp_f32_e32 v138, v138
	s_nop 0
	v_add_f32_e32 v138, 1.0, v138
	v_rcp_f32_e32 v138, v138
	s_nop 0
	v_mul_f32_e32 v137, v137, v138
	v_mul_f32_e32 v138, v91, v130
	v_mul_f32_e32 v139, 0xbfb8aa3b, v138
	v_exp_f32_e32 v139, v139
	s_nop 0
	v_add_f32_e32 v139, 1.0, v139
	v_rcp_f32_e32 v139, v139
	s_nop 0
	v_mul_f32_e32 v138, v138, v139
	v_mul_f32_e32 v139, v92, v130
	v_mul_f32_e32 v140, 0xbfb8aa3b, v139
	v_exp_f32_e32 v140, v140
	v_mul_f32_e32 v130, v93, v130
	v_cvt_pk_bf16_f32 v138, v137, v138
	v_add_f32_e32 v140, 1.0, v140
	v_rcp_f32_e32 v140, v140
	s_nop 0
	v_mul_f32_e32 v139, v139, v140
	v_mul_f32_e32 v140, 0xbfb8aa3b, v130
	v_exp_f32_e32 v140, v140
	s_nop 0
	v_add_f32_e32 v140, 1.0, v140
	v_rcp_f32_e32 v140, v140
	s_nop 0
	v_mul_f32_e32 v130, v130, v140
	v_cvt_pk_bf16_f32 v139, v139, v130
	ds_write_b64 v131, v[138:139] offset:8704
	v_mov_b32_e32 v137, v150
	v_add_u32_e32 v130, 0x2200, v131
	v_mul_f32_e32 v138, v58, v137
	v_mul_f32_e32 v139, 0xbfb8aa3b, v138
	v_exp_f32_e32 v139, v139
	s_nop 0
	v_add_f32_e32 v139, 1.0, v139
	v_rcp_f32_e32 v139, v139
	s_nop 0
	v_mul_f32_e32 v138, v138, v139
	v_mul_f32_e32 v139, v59, v137
	v_mul_f32_e32 v140, 0xbfb8aa3b, v139
	v_exp_f32_e32 v140, v140
	s_nop 0
	v_add_f32_e32 v140, 1.0, v140
	v_rcp_f32_e32 v140, v140
	s_nop 0
	v_mul_f32_e32 v139, v139, v140
	v_mul_f32_e32 v140, v60, v137
	v_mul_f32_e32 v141, 0xbfb8aa3b, v140
	v_exp_f32_e32 v141, v141
	v_mul_f32_e32 v137, v61, v137
	v_cvt_pk_bf16_f32 v138, v138, v139
	v_add_f32_e32 v141, 1.0, v141
	v_rcp_f32_e32 v141, v141
	s_nop 0
	v_mul_f32_e32 v140, v140, v141
	v_mul_f32_e32 v141, 0xbfb8aa3b, v137
	v_exp_f32_e32 v141, v141
	s_nop 0
	v_add_f32_e32 v141, 1.0, v141
	v_rcp_f32_e32 v141, v141
	s_nop 0
	v_mul_f32_e32 v137, v137, v141
	v_cvt_pk_bf16_f32 v139, v140, v137
	ds_write_b64 v130, v[138:139] offset:60928
	v_mov_b32_e32 v138, v151
	v_add_u32_e32 v137, 0xee00, v130
	v_mul_f32_e32 v139, v26, v138
	v_mul_f32_e32 v140, 0xbfb8aa3b, v139
	v_exp_f32_e32 v140, v140
	s_nop 0
	v_add_f32_e32 v140, 1.0, v140
	v_rcp_f32_e32 v140, v140
	s_nop 0
	v_mul_f32_e32 v139, v139, v140
	v_mul_f32_e32 v140, v27, v138
	v_mul_f32_e32 v141, 0xbfb8aa3b, v140
	v_exp_f32_e32 v141, v141
	s_nop 0
	v_add_f32_e32 v141, 1.0, v141
	v_rcp_f32_e32 v141, v141
	s_nop 0
	v_mul_f32_e32 v140, v140, v141
	v_mul_f32_e32 v141, v28, v138
	v_mul_f32_e32 v142, 0xbfb8aa3b, v141
	v_exp_f32_e32 v142, v142
	v_mul_f32_e32 v138, v29, v138
	v_add_f32_e32 v142, 1.0, v142
	v_rcp_f32_e32 v142, v142
	s_nop 0
	v_mul_f32_e32 v141, v141, v142
	v_mul_f32_e32 v142, 0xbfb8aa3b, v138
	v_exp_f32_e32 v142, v142
	s_nop 0
	v_add_f32_e32 v142, 1.0, v142
	v_rcp_f32_e32 v142, v142
	s_nop 0
	v_mul_f32_e32 v142, v138, v142
	v_cvt_pk_bf16_f32 v138, v139, v140
	v_cvt_pk_bf16_f32 v139, v141, v142
	ds_write_b64 v137, v[138:139] offset:8704
	v_mov_b32_e32 v138, v148
	v_mul_f32_e32 v139, v114, v138
	v_mul_f32_e32 v140, 0xbfb8aa3b, v139
	v_exp_f32_e32 v140, v140
	s_nop 0
	v_add_f32_e32 v140, 1.0, v140
	v_rcp_f32_e32 v140, v140
	s_nop 0
	v_mul_f32_e32 v139, v139, v140
	v_mul_f32_e32 v140, v115, v138
	v_mul_f32_e32 v141, 0xbfb8aa3b, v140
	v_exp_f32_e32 v141, v141
	s_nop 0
	v_add_f32_e32 v141, 1.0, v141
	v_rcp_f32_e32 v141, v141
	s_nop 0
	v_mul_f32_e32 v140, v140, v141
	v_mul_f32_e32 v141, v116, v138
	v_mul_f32_e32 v142, 0xbfb8aa3b, v141
	v_exp_f32_e32 v142, v142
	v_mul_f32_e32 v138, v117, v138
	v_add_f32_e32 v142, 1.0, v142
	v_rcp_f32_e32 v142, v142
	s_nop 0
	v_mul_f32_e32 v141, v141, v142
	v_mul_f32_e32 v142, 0xbfb8aa3b, v138
	v_exp_f32_e32 v142, v142
	s_nop 0
	v_add_f32_e32 v142, 1.0, v142
	v_rcp_f32_e32 v142, v142
	s_nop 0
	v_mul_f32_e32 v142, v138, v142
	v_cvt_pk_bf16_f32 v138, v139, v140
	v_cvt_pk_bf16_f32 v139, v141, v142
	ds_write_b64 v131, v[138:139] offset:32
	v_mov_b32_e32 v138, v149
; __device__ __forceinline__ float siluf(float x) { return x * __builtin_amdgcn_rcpf(1.f + __expf(-x)); }
; #define STAGE_TILE_F(XFORM) do { SW_BEGIN f32x4 v = acc[ai][bj][m][n2]; XFORM; \
;     *(u32x2*)(smem + mrow * SPITCH + nc0 * 2) = u32x2{cvtpk_t(v[0], v[1]), cvtpk_t(v[2], v[3])}; LOOP_END __syncthreads(); } while (0)
; template <int kind> __device__ __forceinline__ void gemm_phase_n(const Params& P, int layer, int b, const int wv) {
;     ...
;                 } else {
;                     STAGE_TILE_F(const float r = rs_lds[mrow]; v[0] = siluf(v[0] * r); v[1] = siluf(v[1] * r); v[2] = siluf(v[2] * r); v[3] = siluf(v[3] * r));
	v_mul_f32_e32 v139, v82, v138
	v_mul_f32_e32 v140, 0xbfb8aa3b, v139
	v_exp_f32_e32 v140, v140
	s_nop 0
	v_add_f32_e32 v140, 1.0, v140
	v_rcp_f32_e32 v140, v140
	s_nop 0
	v_mul_f32_e32 v139, v139, v140
	v_mul_f32_e32 v140, v83, v138
	v_mul_f32_e32 v141, 0xbfb8aa3b, v140
	v_exp_f32_e32 v141, v141
	s_nop 0
	v_add_f32_e32 v141, 1.0, v141
	v_rcp_f32_e32 v141, v141
	s_nop 0
	v_mul_f32_e32 v140, v140, v141
	v_mul_f32_e32 v141, v84, v138
	v_mul_f32_e32 v142, 0xbfb8aa3b, v141
	v_exp_f32_e32 v142, v142
	v_mul_f32_e32 v138, v85, v138
	v_add_f32_e32 v142, 1.0, v142
	v_rcp_f32_e32 v142, v142
	s_nop 0
	v_mul_f32_e32 v141, v141, v142
	v_mul_f32_e32 v142, 0xbfb8aa3b, v138
	v_exp_f32_e32 v142, v142
	s_nop 0
	v_add_f32_e32 v142, 1.0, v142
	v_rcp_f32_e32 v142, v142
	s_nop 0
	v_mul_f32_e32 v142, v138, v142
	v_cvt_pk_bf16_f32 v138, v139, v140
	v_cvt_pk_bf16_f32 v139, v141, v142
	ds_write_b64 v131, v[138:139] offset:8736
	v_mov_b32_e32 v138, v150
	v_mul_f32_e32 v139, v50, v138
	v_mul_f32_e32 v140, 0xbfb8aa3b, v139
	v_exp_f32_e32 v140, v140
	s_nop 0
	v_add_f32_e32 v140, 1.0, v140
	v_rcp_f32_e32 v140, v140
	s_nop 0
	v_mul_f32_e32 v139, v139, v140
	v_mul_f32_e32 v140, v51, v138
	v_mul_f32_e32 v141, 0xbfb8aa3b, v140
	v_exp_f32_e32 v141, v141
	s_nop 0
	v_add_f32_e32 v141, 1.0, v141
	v_rcp_f32_e32 v141, v141
	s_nop 0
	v_mul_f32_e32 v140, v140, v141
	v_mul_f32_e32 v141, v52, v138
	v_mul_f32_e32 v142, 0xbfb8aa3b, v141
	v_exp_f32_e32 v142, v142
	v_mul_f32_e32 v138, v53, v138
	v_add_f32_e32 v142, 1.0, v142
	v_rcp_f32_e32 v142, v142
	s_nop 0
	v_mul_f32_e32 v141, v141, v142
	v_mul_f32_e32 v142, 0xbfb8aa3b, v138
	v_exp_f32_e32 v142, v142
	s_nop 0
	v_add_f32_e32 v142, 1.0, v142
	v_rcp_f32_e32 v142, v142
	s_nop 0
	v_mul_f32_e32 v142, v138, v142
	v_cvt_pk_bf16_f32 v138, v139, v140
	v_cvt_pk_bf16_f32 v139, v141, v142
	ds_write_b64 v130, v[138:139] offset:60960
	v_mov_b32_e32 v138, v151
	v_mul_f32_e32 v139, v18, v138
	v_mul_f32_e32 v140, 0xbfb8aa3b, v139
	v_exp_f32_e32 v140, v140
	s_nop 0
	v_add_f32_e32 v140, 1.0, v140
	v_rcp_f32_e32 v140, v140
	s_nop 0
	v_mul_f32_e32 v139, v139, v140
	v_mul_f32_e32 v140, v19, v138
	v_mul_f32_e32 v141, 0xbfb8aa3b, v140
	v_exp_f32_e32 v141, v141
	s_nop 0
	v_add_f32_e32 v141, 1.0, v141
	v_rcp_f32_e32 v141, v141
	s_nop 0
	v_mul_f32_e32 v140, v140, v141
	v_mul_f32_e32 v141, v20, v138
	v_mul_f32_e32 v142, 0xbfb8aa3b, v141
	v_exp_f32_e32 v142, v142
	v_mul_f32_e32 v138, v21, v138
	v_add_f32_e32 v142, 1.0, v142
	v_rcp_f32_e32 v142, v142
	s_nop 0
	v_mul_f32_e32 v141, v141, v142
	v_mul_f32_e32 v142, 0xbfb8aa3b, v138
	v_exp_f32_e32 v142, v142
	s_nop 0
	v_add_f32_e32 v142, 1.0, v142
	v_rcp_f32_e32 v142, v142
	s_nop 0
	v_mul_f32_e32 v142, v138, v142
	v_cvt_pk_bf16_f32 v138, v139, v140
	v_cvt_pk_bf16_f32 v139, v141, v142
	ds_write_b64 v137, v[138:139] offset:8736
	v_mov_b32_e32 v138, v148
	v_mul_f32_e32 v139, v102, v138
	v_mul_f32_e32 v140, 0xbfb8aa3b, v139
	v_exp_f32_e32 v140, v140
	s_nop 0
	v_add_f32_e32 v140, 1.0, v140
	v_rcp_f32_e32 v140, v140
	s_nop 0
	v_mul_f32_e32 v139, v139, v140
	v_mul_f32_e32 v140, v103, v138
	v_mul_f32_e32 v141, 0xbfb8aa3b, v140
	v_exp_f32_e32 v141, v141
	s_nop 0
	v_add_f32_e32 v141, 1.0, v141
	v_rcp_f32_e32 v141, v141
	s_nop 0
	v_mul_f32_e32 v140, v140, v141
	v_mul_f32_e32 v141, v104, v138
	v_mul_f32_e32 v142, 0xbfb8aa3b, v141
	v_exp_f32_e32 v142, v142
	v_mul_f32_e32 v138, v105, v138
	v_add_f32_e32 v142, 1.0, v142
	v_rcp_f32_e32 v142, v142
	s_nop 0
	v_mul_f32_e32 v141, v141, v142
	v_mul_f32_e32 v142, 0xbfb8aa3b, v138
	v_exp_f32_e32 v142, v142
	s_nop 0
	v_add_f32_e32 v142, 1.0, v142
	v_rcp_f32_e32 v142, v142
	s_nop 0
	v_mul_f32_e32 v142, v138, v142
	v_cvt_pk_bf16_f32 v138, v139, v140
	v_cvt_pk_bf16_f32 v139, v141, v142
	ds_write_b64 v131, v[138:139] offset:64
	v_mov_b32_e32 v138, v149
	v_mul_f32_e32 v139, v70, v138
	v_mul_f32_e32 v140, 0xbfb8aa3b, v139
	v_exp_f32_e32 v140, v140
	s_nop 0
	v_add_f32_e32 v140, 1.0, v140
	v_rcp_f32_e32 v140, v140
	s_nop 0
	v_mul_f32_e32 v139, v139, v140
	v_mul_f32_e32 v140, v71, v138
	v_mul_f32_e32 v141, 0xbfb8aa3b, v140
	v_exp_f32_e32 v141, v141
	s_nop 0
	v_add_f32_e32 v141, 1.0, v141
	v_rcp_f32_e32 v141, v141
	s_nop 0
	v_mul_f32_e32 v140, v140, v141
	v_mul_f32_e32 v141, v72, v138
	v_mul_f32_e32 v142, 0xbfb8aa3b, v141
	v_exp_f32_e32 v142, v142
	v_mul_f32_e32 v138, v73, v138
	v_add_f32_e32 v142, 1.0, v142
	v_rcp_f32_e32 v142, v142
	s_nop 0
	v_mul_f32_e32 v141, v141, v142
	v_mul_f32_e32 v142, 0xbfb8aa3b, v138
	v_exp_f32_e32 v142, v142
	s_nop 0
	v_add_f32_e32 v142, 1.0, v142
	v_rcp_f32_e32 v142, v142
	s_nop 0
	v_mul_f32_e32 v142, v138, v142
	v_cvt_pk_bf16_f32 v138, v139, v140
	v_cvt_pk_bf16_f32 v139, v141, v142
	ds_write_b64 v131, v[138:139] offset:8768
	v_mov_b32_e32 v138, v150
	v_mul_f32_e32 v139, v38, v138
	v_mul_f32_e32 v140, 0xbfb8aa3b, v139
	v_exp_f32_e32 v140, v140
	s_nop 0
	v_add_f32_e32 v140, 1.0, v140
	v_rcp_f32_e32 v140, v140
	s_nop 0
	v_mul_f32_e32 v139, v139, v140
	v_mul_f32_e32 v140, v39, v138
	v_mul_f32_e32 v141, 0xbfb8aa3b, v140
	v_exp_f32_e32 v141, v141
	s_nop 0
	v_add_f32_e32 v141, 1.0, v141
	v_rcp_f32_e32 v141, v141
	s_nop 0
	v_mul_f32_e32 v140, v140, v141
	v_mul_f32_e32 v141, v40, v138
	v_mul_f32_e32 v142, 0xbfb8aa3b, v141
	v_exp_f32_e32 v142, v142
	v_mul_f32_e32 v138, v41, v138
	v_add_f32_e32 v142, 1.0, v142
	v_rcp_f32_e32 v142, v142
	s_nop 0
	v_mul_f32_e32 v141, v141, v142
	v_mul_f32_e32 v142, 0xbfb8aa3b, v138
	v_exp_f32_e32 v142, v142
	s_nop 0
	v_add_f32_e32 v142, 1.0, v142
	v_rcp_f32_e32 v142, v142
	s_nop 0
	v_mul_f32_e32 v142, v138, v142
	v_cvt_pk_bf16_f32 v138, v139, v140
	v_cvt_pk_bf16_f32 v139, v141, v142
	ds_write_b64 v130, v[138:139] offset:60992
	v_mov_b32_e32 v138, v151
; __device__ __forceinline__ float siluf(float x) { return x * __builtin_amdgcn_rcpf(1.f + __expf(-x)); }
; #define STAGE_TILE_F(XFORM) do { SW_BEGIN f32x4 v = acc[ai][bj][m][n2]; XFORM; \
;     *(u32x2*)(smem + mrow * SPITCH + nc0 * 2) = u32x2{cvtpk_t(v[0], v[1]), cvtpk_t(v[2], v[3])}; LOOP_END __syncthreads(); } while (0)
; template <int kind> __device__ __forceinline__ void gemm_phase_n(const Params& P, int layer, int b, const int wv) {
;     ...
;                 } else {
;                     STAGE_TILE_F(const float r = rs_lds[mrow]; v[0] = siluf(v[0] * r); v[1] = siluf(v[1] * r); v[2] = siluf(v[2] * r); v[3] = siluf(v[3] * r));
	v_mul_f32_e32 v139, v10, v138
	v_mul_f32_e32 v140, 0xbfb8aa3b, v139
	v_exp_f32_e32 v140, v140
	s_nop 0
	v_add_f32_e32 v140, 1.0, v140
	v_rcp_f32_e32 v140, v140
	s_nop 0
	v_mul_f32_e32 v139, v139, v140
	v_mul_f32_e32 v140, v11, v138
	v_mul_f32_e32 v141, 0xbfb8aa3b, v140
	v_exp_f32_e32 v141, v141
	s_nop 0
	v_add_f32_e32 v141, 1.0, v141
	v_rcp_f32_e32 v141, v141
	s_nop 0
	v_mul_f32_e32 v140, v140, v141
	v_mul_f32_e32 v141, v12, v138
	v_mul_f32_e32 v142, 0xbfb8aa3b, v141
	v_exp_f32_e32 v142, v142
	v_mul_f32_e32 v138, v13, v138
	v_add_f32_e32 v142, 1.0, v142
	v_rcp_f32_e32 v142, v142
	s_nop 0
	v_mul_f32_e32 v141, v141, v142
	v_mul_f32_e32 v142, 0xbfb8aa3b, v138
	v_exp_f32_e32 v142, v142
	s_nop 0
	v_add_f32_e32 v142, 1.0, v142
	v_rcp_f32_e32 v142, v142
	s_nop 0
	v_mul_f32_e32 v142, v138, v142
	v_cvt_pk_bf16_f32 v138, v139, v140
	v_cvt_pk_bf16_f32 v139, v141, v142
	ds_write_b64 v137, v[138:139] offset:8768
	v_mov_b32_e32 v138, v148
	v_mul_f32_e32 v139, v98, v138
	v_mul_f32_e32 v140, 0xbfb8aa3b, v139
	v_exp_f32_e32 v140, v140
	s_nop 0
	v_add_f32_e32 v140, 1.0, v140
	v_rcp_f32_e32 v140, v140
	s_nop 0
	v_mul_f32_e32 v139, v139, v140
	v_mul_f32_e32 v140, v99, v138
	v_mul_f32_e32 v141, 0xbfb8aa3b, v140
	v_exp_f32_e32 v141, v141
	s_nop 0
	v_add_f32_e32 v141, 1.0, v141
	v_rcp_f32_e32 v141, v141
	s_nop 0
	v_mul_f32_e32 v140, v140, v141
	v_mul_f32_e32 v141, v100, v138
	v_mul_f32_e32 v142, 0xbfb8aa3b, v141
	v_exp_f32_e32 v142, v142
	v_mul_f32_e32 v138, v101, v138
	v_add_f32_e32 v142, 1.0, v142
	v_rcp_f32_e32 v142, v142
	s_nop 0
	v_mul_f32_e32 v141, v141, v142
	v_mul_f32_e32 v142, 0xbfb8aa3b, v138
	v_exp_f32_e32 v142, v142
	s_nop 0
	v_add_f32_e32 v142, 1.0, v142
	v_rcp_f32_e32 v142, v142
	s_nop 0
	v_mul_f32_e32 v142, v138, v142
	v_cvt_pk_bf16_f32 v138, v139, v140
	v_cvt_pk_bf16_f32 v139, v141, v142
	ds_write_b64 v131, v[138:139] offset:96
	v_mov_b32_e32 v138, v149
	v_mul_f32_e32 v139, v66, v138
	v_mul_f32_e32 v140, 0xbfb8aa3b, v139
	v_exp_f32_e32 v140, v140
	s_nop 0
	v_add_f32_e32 v140, 1.0, v140
	v_rcp_f32_e32 v140, v140
	s_nop 0
	v_mul_f32_e32 v139, v139, v140
	v_mul_f32_e32 v140, v67, v138
	v_mul_f32_e32 v141, 0xbfb8aa3b, v140
	v_exp_f32_e32 v141, v141
	s_nop 0
	v_add_f32_e32 v141, 1.0, v141
	v_rcp_f32_e32 v141, v141
	s_nop 0
	v_mul_f32_e32 v140, v140, v141
	v_mul_f32_e32 v141, v68, v138
	v_mul_f32_e32 v142, 0xbfb8aa3b, v141
	v_exp_f32_e32 v142, v142
	v_mul_f32_e32 v138, v69, v138
	v_add_f32_e32 v142, 1.0, v142
	v_rcp_f32_e32 v142, v142
	s_nop 0
	v_mul_f32_e32 v141, v141, v142
	v_mul_f32_e32 v142, 0xbfb8aa3b, v138
	v_exp_f32_e32 v142, v142
	s_nop 0
	v_add_f32_e32 v142, 1.0, v142
	v_rcp_f32_e32 v142, v142
	s_nop 0
	v_mul_f32_e32 v142, v138, v142
	v_cvt_pk_bf16_f32 v138, v139, v140
	v_cvt_pk_bf16_f32 v139, v141, v142
	ds_write_b64 v131, v[138:139] offset:8800
	v_mov_b32_e32 v138, v150
	v_mul_f32_e32 v139, v34, v138
	v_mul_f32_e32 v140, 0xbfb8aa3b, v139
	v_exp_f32_e32 v140, v140
	s_nop 0
	v_add_f32_e32 v140, 1.0, v140
	v_rcp_f32_e32 v140, v140
	s_nop 0
	v_mul_f32_e32 v139, v139, v140
	v_mul_f32_e32 v140, v35, v138
	v_mul_f32_e32 v141, 0xbfb8aa3b, v140
	v_exp_f32_e32 v141, v141
	s_nop 0
	v_add_f32_e32 v141, 1.0, v141
	v_rcp_f32_e32 v141, v141
	s_nop 0
	v_mul_f32_e32 v140, v140, v141
	v_mul_f32_e32 v141, v36, v138
	v_mul_f32_e32 v142, 0xbfb8aa3b, v141
	v_exp_f32_e32 v142, v142
	v_mul_f32_e32 v138, v37, v138
	v_add_f32_e32 v142, 1.0, v142
	v_rcp_f32_e32 v142, v142
	s_nop 0
	v_mul_f32_e32 v141, v141, v142
	v_mul_f32_e32 v142, 0xbfb8aa3b, v138
	v_exp_f32_e32 v142, v142
	s_nop 0
	v_add_f32_e32 v142, 1.0, v142
	v_rcp_f32_e32 v142, v142
	s_nop 0
	v_mul_f32_e32 v142, v138, v142
	v_cvt_pk_bf16_f32 v138, v139, v140
	v_cvt_pk_bf16_f32 v139, v141, v142
	ds_write_b64 v130, v[138:139] offset:61024
	v_mov_b32_e32 v138, v151
	v_mul_f32_e32 v139, v2, v138
	v_mul_f32_e32 v140, 0xbfb8aa3b, v139
	v_exp_f32_e32 v140, v140
	s_nop 0
	v_add_f32_e32 v140, 1.0, v140
	v_rcp_f32_e32 v140, v140
	s_nop 0
	v_mul_f32_e32 v139, v139, v140
	v_mul_f32_e32 v140, v3, v138
	v_mul_f32_e32 v141, 0xbfb8aa3b, v140
	v_exp_f32_e32 v141, v141
	s_nop 0
	v_add_f32_e32 v141, 1.0, v141
	v_rcp_f32_e32 v141, v141
	s_nop 0
	v_mul_f32_e32 v140, v140, v141
	v_mul_f32_e32 v141, v4, v138
	v_mul_f32_e32 v142, 0xbfb8aa3b, v141
	v_exp_f32_e32 v142, v142
	v_mul_f32_e32 v138, v5, v138
	v_add_f32_e32 v142, 1.0, v142
	v_rcp_f32_e32 v142, v142
	s_nop 0
	v_mul_f32_e32 v141, v141, v142
	v_mul_f32_e32 v142, 0xbfb8aa3b, v138
	v_exp_f32_e32 v142, v142
	s_nop 0
	v_add_f32_e32 v142, 1.0, v142
	v_rcp_f32_e32 v142, v142
	s_nop 0
	v_mul_f32_e32 v142, v138, v142
	v_cvt_pk_bf16_f32 v138, v139, v140
	v_cvt_pk_bf16_f32 v139, v141, v142
	ds_write_b64 v137, v[138:139] offset:8800
	v_mov_b32_e32 v138, v148
	v_mul_f32_e32 v139, v126, v138
	v_mul_f32_e32 v140, 0xbfb8aa3b, v139
	v_exp_f32_e32 v140, v140
	s_nop 0
	v_add_f32_e32 v140, 1.0, v140
	v_rcp_f32_e32 v140, v140
	s_nop 0
	v_mul_f32_e32 v139, v139, v140
	v_mul_f32_e32 v140, v127, v138
	v_mul_f32_e32 v141, 0xbfb8aa3b, v140
	v_exp_f32_e32 v141, v141
	s_nop 0
	v_add_f32_e32 v141, 1.0, v141
	v_rcp_f32_e32 v141, v141
	s_nop 0
	v_mul_f32_e32 v140, v140, v141
	v_mul_f32_e32 v141, v128, v138
	v_mul_f32_e32 v142, 0xbfb8aa3b, v141
	v_exp_f32_e32 v142, v142
	v_mul_f32_e32 v138, v129, v138
	v_add_f32_e32 v142, 1.0, v142
	v_rcp_f32_e32 v142, v142
	s_nop 0
	v_mul_f32_e32 v141, v141, v142
	v_mul_f32_e32 v142, 0xbfb8aa3b, v138
	v_exp_f32_e32 v142, v142
	s_nop 0
	v_add_f32_e32 v142, 1.0, v142
	v_rcp_f32_e32 v142, v142
	s_nop 0
	v_mul_f32_e32 v142, v138, v142
	v_cvt_pk_bf16_f32 v138, v139, v140
	v_cvt_pk_bf16_f32 v139, v141, v142
	ds_write_b64 v131, v[138:139] offset:256
	v_mov_b32_e32 v138, v149
; __device__ __forceinline__ float siluf(float x) { return x * __builtin_amdgcn_rcpf(1.f + __expf(-x)); }
; #define STAGE_TILE_F(XFORM) do { SW_BEGIN f32x4 v = acc[ai][bj][m][n2]; XFORM; \
;     *(u32x2*)(smem + mrow * SPITCH + nc0 * 2) = u32x2{cvtpk_t(v[0], v[1]), cvtpk_t(v[2], v[3])}; LOOP_END __syncthreads(); } while (0)
; template <int kind> __device__ __forceinline__ void gemm_phase_n(const Params& P, int layer, int b, const int wv) {
;     ...
;                 } else {
;                     STAGE_TILE_F(const float r = rs_lds[mrow]; v[0] = siluf(v[0] * r); v[1] = siluf(v[1] * r); v[2] = siluf(v[2] * r); v[3] = siluf(v[3] * r));
	v_mul_f32_e32 v139, v94, v138
	v_mul_f32_e32 v140, 0xbfb8aa3b, v139
	v_exp_f32_e32 v140, v140
	s_nop 0
	v_add_f32_e32 v140, 1.0, v140
	v_rcp_f32_e32 v140, v140
	s_nop 0
	v_mul_f32_e32 v139, v139, v140
	v_mul_f32_e32 v140, v95, v138
	v_mul_f32_e32 v141, 0xbfb8aa3b, v140
	v_exp_f32_e32 v141, v141
	s_nop 0
	v_add_f32_e32 v141, 1.0, v141
	v_rcp_f32_e32 v141, v141
	s_nop 0
	v_mul_f32_e32 v140, v140, v141
	v_mul_f32_e32 v141, v96, v138
	v_mul_f32_e32 v142, 0xbfb8aa3b, v141
	v_exp_f32_e32 v142, v142
	v_mul_f32_e32 v138, v97, v138
	v_add_f32_e32 v142, 1.0, v142
	v_rcp_f32_e32 v142, v142
	s_nop 0
	v_mul_f32_e32 v141, v141, v142
	v_mul_f32_e32 v142, 0xbfb8aa3b, v138
	v_exp_f32_e32 v142, v142
	s_nop 0
	v_add_f32_e32 v142, 1.0, v142
	v_rcp_f32_e32 v142, v142
	s_nop 0
	v_mul_f32_e32 v142, v138, v142
	v_cvt_pk_bf16_f32 v138, v139, v140
	v_cvt_pk_bf16_f32 v139, v141, v142
	ds_write_b64 v131, v[138:139] offset:8960
	v_mov_b32_e32 v138, v150
	v_mul_f32_e32 v139, v62, v138
	v_mul_f32_e32 v140, 0xbfb8aa3b, v139
	v_exp_f32_e32 v140, v140
	s_nop 0
	v_add_f32_e32 v140, 1.0, v140
	v_rcp_f32_e32 v140, v140
	s_nop 0
	v_mul_f32_e32 v139, v139, v140
	v_mul_f32_e32 v140, v63, v138
	v_mul_f32_e32 v141, 0xbfb8aa3b, v140
	v_exp_f32_e32 v141, v141
	s_nop 0
	v_add_f32_e32 v141, 1.0, v141
	v_rcp_f32_e32 v141, v141
	s_nop 0
	v_mul_f32_e32 v140, v140, v141
	v_mul_f32_e32 v141, v64, v138
	v_mul_f32_e32 v142, 0xbfb8aa3b, v141
	v_exp_f32_e32 v142, v142
	v_mul_f32_e32 v138, v65, v138
	v_add_f32_e32 v142, 1.0, v142
	v_rcp_f32_e32 v142, v142
	s_nop 0
	v_mul_f32_e32 v141, v141, v142
	v_mul_f32_e32 v142, 0xbfb8aa3b, v138
	v_exp_f32_e32 v142, v142
	s_nop 0
	v_add_f32_e32 v142, 1.0, v142
	v_rcp_f32_e32 v142, v142
	s_nop 0
	v_mul_f32_e32 v142, v138, v142
	v_cvt_pk_bf16_f32 v138, v139, v140
	v_cvt_pk_bf16_f32 v139, v141, v142
	ds_write_b64 v130, v[138:139] offset:61184
	v_mov_b32_e32 v138, v151
	v_mul_f32_e32 v139, v30, v138
	v_mul_f32_e32 v140, 0xbfb8aa3b, v139
	v_exp_f32_e32 v140, v140
	s_nop 0
	v_add_f32_e32 v140, 1.0, v140
	v_rcp_f32_e32 v140, v140
	s_nop 0
	v_mul_f32_e32 v139, v139, v140
	v_mul_f32_e32 v140, v31, v138
	v_mul_f32_e32 v141, 0xbfb8aa3b, v140
	v_exp_f32_e32 v141, v141
	s_nop 0
	v_add_f32_e32 v141, 1.0, v141
	v_rcp_f32_e32 v141, v141
	s_nop 0
	v_mul_f32_e32 v140, v140, v141
	v_mul_f32_e32 v141, v32, v138
	v_mul_f32_e32 v142, 0xbfb8aa3b, v141
	v_exp_f32_e32 v142, v142
	v_mul_f32_e32 v138, v33, v138
	v_add_f32_e32 v142, 1.0, v142
	v_rcp_f32_e32 v142, v142
	s_nop 0
	v_mul_f32_e32 v141, v141, v142
	v_mul_f32_e32 v142, 0xbfb8aa3b, v138
	v_exp_f32_e32 v142, v142
	s_nop 0
	v_add_f32_e32 v142, 1.0, v142
	v_rcp_f32_e32 v142, v142
	s_nop 0
	v_mul_f32_e32 v142, v138, v142
	v_cvt_pk_bf16_f32 v138, v139, v140
	v_cvt_pk_bf16_f32 v139, v141, v142
	ds_write_b64 v137, v[138:139] offset:8960
	v_mov_b32_e32 v138, v148
	v_mul_f32_e32 v139, v118, v138
	v_mul_f32_e32 v140, 0xbfb8aa3b, v139
	v_exp_f32_e32 v140, v140
	s_nop 0
	v_add_f32_e32 v140, 1.0, v140
	v_rcp_f32_e32 v140, v140
	s_nop 0
	v_mul_f32_e32 v139, v139, v140
	v_mul_f32_e32 v140, v119, v138
	v_mul_f32_e32 v141, 0xbfb8aa3b, v140
	v_exp_f32_e32 v141, v141
	s_nop 0
	v_add_f32_e32 v141, 1.0, v141
	v_rcp_f32_e32 v141, v141
	s_nop 0
	v_mul_f32_e32 v140, v140, v141
	v_mul_f32_e32 v141, v120, v138
	v_mul_f32_e32 v142, 0xbfb8aa3b, v141
	v_exp_f32_e32 v142, v142
	v_mul_f32_e32 v138, v121, v138
	v_add_f32_e32 v142, 1.0, v142
	v_rcp_f32_e32 v142, v142
	s_nop 0
	v_mul_f32_e32 v141, v141, v142
	v_mul_f32_e32 v142, 0xbfb8aa3b, v138
	v_exp_f32_e32 v142, v142
	s_nop 0
	v_add_f32_e32 v142, 1.0, v142
	v_rcp_f32_e32 v142, v142
	s_nop 0
	v_mul_f32_e32 v142, v138, v142
	v_cvt_pk_bf16_f32 v138, v139, v140
	v_cvt_pk_bf16_f32 v139, v141, v142
	ds_write_b64 v131, v[138:139] offset:288
	v_mov_b32_e32 v138, v149
	v_mul_f32_e32 v139, v86, v138
	v_mul_f32_e32 v140, 0xbfb8aa3b, v139
	v_exp_f32_e32 v140, v140
	s_nop 0
	v_add_f32_e32 v140, 1.0, v140
	v_rcp_f32_e32 v140, v140
	s_nop 0
	v_mul_f32_e32 v139, v139, v140
	v_mul_f32_e32 v140, v87, v138
	v_mul_f32_e32 v141, 0xbfb8aa3b, v140
	v_exp_f32_e32 v141, v141
	s_nop 0
	v_add_f32_e32 v141, 1.0, v141
	v_rcp_f32_e32 v141, v141
	s_nop 0
	v_mul_f32_e32 v140, v140, v141
	v_mul_f32_e32 v141, v88, v138
	v_mul_f32_e32 v142, 0xbfb8aa3b, v141
	v_exp_f32_e32 v142, v142
	v_mul_f32_e32 v138, v89, v138
	v_add_f32_e32 v142, 1.0, v142
	v_rcp_f32_e32 v142, v142
	s_nop 0
	v_mul_f32_e32 v141, v141, v142
	v_mul_f32_e32 v142, 0xbfb8aa3b, v138
	v_exp_f32_e32 v142, v142
	s_nop 0
	v_add_f32_e32 v142, 1.0, v142
	v_rcp_f32_e32 v142, v142
	s_nop 0
	v_mul_f32_e32 v142, v138, v142
	v_cvt_pk_bf16_f32 v138, v139, v140
	v_cvt_pk_bf16_f32 v139, v141, v142
	ds_write_b64 v131, v[138:139] offset:8992
	v_mov_b32_e32 v138, v150
	v_mul_f32_e32 v139, v54, v138
	v_mul_f32_e32 v140, 0xbfb8aa3b, v139
	v_exp_f32_e32 v140, v140
	s_nop 0
	v_add_f32_e32 v140, 1.0, v140
	v_rcp_f32_e32 v140, v140
	s_nop 0
	v_mul_f32_e32 v139, v139, v140
	v_mul_f32_e32 v140, v55, v138
	v_mul_f32_e32 v141, 0xbfb8aa3b, v140
	v_exp_f32_e32 v141, v141
	s_nop 0
	v_add_f32_e32 v141, 1.0, v141
	v_rcp_f32_e32 v141, v141
	s_nop 0
	v_mul_f32_e32 v140, v140, v141
	v_mul_f32_e32 v141, v56, v138
	v_mul_f32_e32 v142, 0xbfb8aa3b, v141
	v_exp_f32_e32 v142, v142
	v_mul_f32_e32 v138, v57, v138
	v_add_f32_e32 v142, 1.0, v142
	v_rcp_f32_e32 v142, v142
	s_nop 0
	v_mul_f32_e32 v141, v141, v142
	v_mul_f32_e32 v142, 0xbfb8aa3b, v138
	v_exp_f32_e32 v142, v142
	s_nop 0
	v_add_f32_e32 v142, 1.0, v142
	v_rcp_f32_e32 v142, v142
	s_nop 0
	v_mul_f32_e32 v142, v138, v142
	v_cvt_pk_bf16_f32 v138, v139, v140
	v_cvt_pk_bf16_f32 v139, v141, v142
	ds_write_b64 v130, v[138:139] offset:61216
	v_mov_b32_e32 v138, v151
; __device__ __forceinline__ float siluf(float x) { return x * __builtin_amdgcn_rcpf(1.f + __expf(-x)); }
; #define STAGE_TILE_F(XFORM) do { SW_BEGIN f32x4 v = acc[ai][bj][m][n2]; XFORM; \
;     *(u32x2*)(smem + mrow * SPITCH + nc0 * 2) = u32x2{cvtpk_t(v[0], v[1]), cvtpk_t(v[2], v[3])}; LOOP_END __syncthreads(); } while (0)
; template <int kind> __device__ __forceinline__ void gemm_phase_n(const Params& P, int layer, int b, const int wv) {
;     ...
;                 } else {
;                     STAGE_TILE_F(const float r = rs_lds[mrow]; v[0] = siluf(v[0] * r); v[1] = siluf(v[1] * r); v[2] = siluf(v[2] * r); v[3] = siluf(v[3] * r));
	v_mul_f32_e32 v139, v22, v138
	v_mul_f32_e32 v140, 0xbfb8aa3b, v139
	v_exp_f32_e32 v140, v140
	s_nop 0
	v_add_f32_e32 v140, 1.0, v140
	v_rcp_f32_e32 v140, v140
	s_nop 0
	v_mul_f32_e32 v139, v139, v140
	v_mul_f32_e32 v140, v23, v138
	v_mul_f32_e32 v141, 0xbfb8aa3b, v140
	v_exp_f32_e32 v141, v141
	s_nop 0
	v_add_f32_e32 v141, 1.0, v141
	v_rcp_f32_e32 v141, v141
	s_nop 0
	v_mul_f32_e32 v140, v140, v141
	v_mul_f32_e32 v141, v24, v138
	v_mul_f32_e32 v142, 0xbfb8aa3b, v141
	v_exp_f32_e32 v142, v142
	v_mul_f32_e32 v138, v25, v138
	v_add_f32_e32 v142, 1.0, v142
	v_rcp_f32_e32 v142, v142
	s_nop 0
	v_mul_f32_e32 v141, v141, v142
	v_mul_f32_e32 v142, 0xbfb8aa3b, v138
	v_exp_f32_e32 v142, v142
	s_nop 0
	v_add_f32_e32 v142, 1.0, v142
	v_rcp_f32_e32 v142, v142
	s_nop 0
	v_mul_f32_e32 v142, v138, v142
	v_cvt_pk_bf16_f32 v138, v139, v140
	v_cvt_pk_bf16_f32 v139, v141, v142
	ds_write_b64 v137, v[138:139] offset:8992
	v_mov_b32_e32 v138, v148
	v_mul_f32_e32 v139, v110, v138
	v_mul_f32_e32 v140, 0xbfb8aa3b, v139
	v_exp_f32_e32 v140, v140
	s_nop 0
	v_add_f32_e32 v140, 1.0, v140
	v_rcp_f32_e32 v140, v140
	s_nop 0
	v_mul_f32_e32 v139, v139, v140
	v_mul_f32_e32 v140, v111, v138
	v_mul_f32_e32 v141, 0xbfb8aa3b, v140
	v_exp_f32_e32 v141, v141
	s_nop 0
	v_add_f32_e32 v141, 1.0, v141
	v_rcp_f32_e32 v141, v141
	s_nop 0
	v_mul_f32_e32 v140, v140, v141
	v_mul_f32_e32 v141, v112, v138
	v_mul_f32_e32 v142, 0xbfb8aa3b, v141
	v_exp_f32_e32 v142, v142
	v_mul_f32_e32 v138, v113, v138
	v_add_f32_e32 v142, 1.0, v142
	v_rcp_f32_e32 v142, v142
	s_nop 0
	v_mul_f32_e32 v141, v141, v142
	v_mul_f32_e32 v142, 0xbfb8aa3b, v138
	v_exp_f32_e32 v142, v142
	s_nop 0
	v_add_f32_e32 v142, 1.0, v142
	v_rcp_f32_e32 v142, v142
	s_nop 0
	v_mul_f32_e32 v142, v138, v142
	v_cvt_pk_bf16_f32 v138, v139, v140
	v_cvt_pk_bf16_f32 v139, v141, v142
	ds_write_b64 v131, v[138:139] offset:320
	v_mov_b32_e32 v138, v149
	v_mul_f32_e32 v139, v78, v138
	v_mul_f32_e32 v140, 0xbfb8aa3b, v139
	v_exp_f32_e32 v140, v140
	s_nop 0
	v_add_f32_e32 v140, 1.0, v140
	v_rcp_f32_e32 v140, v140
	s_nop 0
	v_mul_f32_e32 v139, v139, v140
	v_mul_f32_e32 v140, v79, v138
	v_mul_f32_e32 v141, 0xbfb8aa3b, v140
	v_exp_f32_e32 v141, v141
	s_nop 0
	v_add_f32_e32 v141, 1.0, v141
	v_rcp_f32_e32 v141, v141
	s_nop 0
	v_mul_f32_e32 v140, v140, v141
	v_mul_f32_e32 v141, v80, v138
	v_mul_f32_e32 v142, 0xbfb8aa3b, v141
	v_exp_f32_e32 v142, v142
	v_mul_f32_e32 v138, v81, v138
	v_add_f32_e32 v142, 1.0, v142
	v_rcp_f32_e32 v142, v142
	s_nop 0
	v_mul_f32_e32 v141, v141, v142
	v_mul_f32_e32 v142, 0xbfb8aa3b, v138
	v_exp_f32_e32 v142, v142
	s_nop 0
	v_add_f32_e32 v142, 1.0, v142
	v_rcp_f32_e32 v142, v142
	s_nop 0
	v_mul_f32_e32 v142, v138, v142
	v_cvt_pk_bf16_f32 v138, v139, v140
	v_cvt_pk_bf16_f32 v139, v141, v142
	ds_write_b64 v131, v[138:139] offset:9024
	v_mov_b32_e32 v138, v150
	v_mul_f32_e32 v139, v46, v138
	v_mul_f32_e32 v140, 0xbfb8aa3b, v139
	v_exp_f32_e32 v140, v140
	s_nop 0
	v_add_f32_e32 v140, 1.0, v140
	v_rcp_f32_e32 v140, v140
	s_nop 0
	v_mul_f32_e32 v139, v139, v140
	v_mul_f32_e32 v140, v47, v138
	v_mul_f32_e32 v141, 0xbfb8aa3b, v140
	v_exp_f32_e32 v141, v141
	s_nop 0
	v_add_f32_e32 v141, 1.0, v141
	v_rcp_f32_e32 v141, v141
	s_nop 0
	v_mul_f32_e32 v140, v140, v141
	v_mul_f32_e32 v141, v48, v138
	v_mul_f32_e32 v142, 0xbfb8aa3b, v141
	v_exp_f32_e32 v142, v142
	v_mul_f32_e32 v138, v49, v138
	v_add_f32_e32 v142, 1.0, v142
	v_rcp_f32_e32 v142, v142
	s_nop 0
	v_mul_f32_e32 v141, v141, v142
	v_mul_f32_e32 v142, 0xbfb8aa3b, v138
	v_exp_f32_e32 v142, v142
	s_nop 0
	v_add_f32_e32 v142, 1.0, v142
	v_rcp_f32_e32 v142, v142
	s_nop 0
	v_mul_f32_e32 v142, v138, v142
	v_cvt_pk_bf16_f32 v138, v139, v140
	v_cvt_pk_bf16_f32 v139, v141, v142
	ds_write_b64 v130, v[138:139] offset:61248
	v_mov_b32_e32 v138, v151
	v_mul_f32_e32 v139, v14, v138
	v_mul_f32_e32 v140, 0xbfb8aa3b, v139
	v_exp_f32_e32 v140, v140
	s_nop 0
	v_add_f32_e32 v140, 1.0, v140
	v_rcp_f32_e32 v140, v140
	s_nop 0
	v_mul_f32_e32 v139, v139, v140
	v_mul_f32_e32 v140, v15, v138
	v_mul_f32_e32 v141, 0xbfb8aa3b, v140
	v_exp_f32_e32 v141, v141
	s_nop 0
	v_add_f32_e32 v141, 1.0, v141
	v_rcp_f32_e32 v141, v141
	s_nop 0
	v_mul_f32_e32 v140, v140, v141
	v_mul_f32_e32 v141, v16, v138
	v_mul_f32_e32 v142, 0xbfb8aa3b, v141
	v_exp_f32_e32 v142, v142
	v_mul_f32_e32 v138, v17, v138
	v_add_f32_e32 v142, 1.0, v142
	v_rcp_f32_e32 v142, v142
	s_nop 0
	v_mul_f32_e32 v141, v141, v142
	v_mul_f32_e32 v142, 0xbfb8aa3b, v138
	v_exp_f32_e32 v142, v142
	s_nop 0
; __device__ __forceinline__ float siluf(float x) { return x * __builtin_amdgcn_rcpf(1.f + __expf(-x)); }
; #define STAGE_TILE_F(XFORM) do { SW_BEGIN f32x4 v = acc[ai][bj][m][n2]; XFORM; \
;     *(u32x2*)(smem + mrow * SPITCH + nc0 * 2) = u32x2{cvtpk_t(v[0], v[1]), cvtpk_t(v[2], v[3])}; LOOP_END __syncthreads(); } while (0)
; template <int kind> __device__ __forceinline__ void gemm_phase_n(const Params& P, int layer, int b, const int wv) {
;     ...
;                 } else {
;                     STAGE_TILE_F(const float r = rs_lds[mrow]; v[0] = siluf(v[0] * r); v[1] = siluf(v[1] * r); v[2] = siluf(v[2] * r); v[3] = siluf(v[3] * r));
;                     u16* dst = (u16*)(ws + O_SG) + (size_t)t0 * 2048 + (pn - 16) * 256;
;                     DRAIN_BEGIN *(u32x4*)(dst + (size_t)row * 2048 + chunk * 8) = w; LOOP_END
	v_add_f32_e32 v142, 1.0, v142
	v_rcp_f32_e32 v142, v142
	s_nop 0
	v_mul_f32_e32 v142, v138, v142
	v_cvt_pk_bf16_f32 v138, v139, v140
	v_cvt_pk_bf16_f32 v139, v141, v142
	ds_write_b64 v137, v[138:139] offset:9024
	v_mov_b32_e32 v138, v148
	v_mul_f32_e32 v139, v106, v138
	v_mul_f32_e32 v140, 0xbfb8aa3b, v139
	v_exp_f32_e32 v140, v140
	s_nop 0
	v_add_f32_e32 v140, 1.0, v140
	v_rcp_f32_e32 v140, v140
	s_nop 0
	v_mul_f32_e32 v139, v139, v140
	v_mul_f32_e32 v140, v107, v138
	v_mul_f32_e32 v141, 0xbfb8aa3b, v140
	v_exp_f32_e32 v141, v141
	s_nop 0
	v_add_f32_e32 v141, 1.0, v141
	v_rcp_f32_e32 v141, v141
	s_nop 0
	v_mul_f32_e32 v140, v140, v141
	v_mul_f32_e32 v141, v108, v138
	v_mul_f32_e32 v142, 0xbfb8aa3b, v141
	v_exp_f32_e32 v142, v142
	v_mul_f32_e32 v138, v109, v138
	v_add_f32_e32 v142, 1.0, v142
	v_rcp_f32_e32 v142, v142
	s_nop 0
	v_mul_f32_e32 v141, v141, v142
	v_mul_f32_e32 v142, 0xbfb8aa3b, v138
	v_exp_f32_e32 v142, v142
	s_nop 0
	v_add_f32_e32 v142, 1.0, v142
	v_rcp_f32_e32 v142, v142
	s_nop 0
	v_mul_f32_e32 v142, v138, v142
	v_cvt_pk_bf16_f32 v138, v139, v140
	v_cvt_pk_bf16_f32 v139, v141, v142
	ds_write_b64 v131, v[138:139] offset:352
	v_mov_b32_e32 v138, v149
	v_mul_f32_e32 v139, v74, v138
	v_mul_f32_e32 v140, 0xbfb8aa3b, v139
	v_exp_f32_e32 v140, v140
	s_nop 0
	v_add_f32_e32 v140, 1.0, v140
	v_rcp_f32_e32 v140, v140
	s_nop 0
	v_mul_f32_e32 v139, v139, v140
	v_mul_f32_e32 v140, v75, v138
	v_mul_f32_e32 v141, 0xbfb8aa3b, v140
	v_exp_f32_e32 v141, v141
	s_nop 0
	v_add_f32_e32 v141, 1.0, v141
	v_rcp_f32_e32 v141, v141
	s_nop 0
	v_mul_f32_e32 v140, v140, v141
	v_mul_f32_e32 v141, v76, v138
	v_mul_f32_e32 v142, 0xbfb8aa3b, v141
	v_exp_f32_e32 v142, v142
	v_mul_f32_e32 v138, v77, v138
	v_add_f32_e32 v142, 1.0, v142
	v_rcp_f32_e32 v142, v142
	s_nop 0
	v_mul_f32_e32 v141, v141, v142
	v_mul_f32_e32 v142, 0xbfb8aa3b, v138
	v_exp_f32_e32 v142, v142
	s_nop 0
	v_add_f32_e32 v142, 1.0, v142
	v_rcp_f32_e32 v142, v142
	s_nop 0
	v_mul_f32_e32 v142, v138, v142
	v_cvt_pk_bf16_f32 v138, v139, v140
	v_cvt_pk_bf16_f32 v139, v141, v142
	ds_write_b64 v131, v[138:139] offset:9056
	v_mov_b32_e32 v131, v150
	v_mul_f32_e32 v138, v42, v131
	v_mul_f32_e32 v139, 0xbfb8aa3b, v138
	v_exp_f32_e32 v139, v139
	s_nop 0
	v_add_f32_e32 v139, 1.0, v139
	v_rcp_f32_e32 v139, v139
	s_nop 0
	v_mul_f32_e32 v138, v138, v139
	v_mul_f32_e32 v139, v43, v131
	v_mul_f32_e32 v140, 0xbfb8aa3b, v139
	v_exp_f32_e32 v140, v140
	s_nop 0
	v_add_f32_e32 v140, 1.0, v140
	v_rcp_f32_e32 v140, v140
	s_nop 0
	v_mul_f32_e32 v139, v139, v140
	v_mul_f32_e32 v140, v44, v131
	v_mul_f32_e32 v141, 0xbfb8aa3b, v140
	v_exp_f32_e32 v141, v141
	v_mul_f32_e32 v131, v45, v131
	v_cvt_pk_bf16_f32 v138, v138, v139
	v_add_f32_e32 v141, 1.0, v141
	v_rcp_f32_e32 v141, v141
	s_nop 0
	v_mul_f32_e32 v140, v140, v141
	v_mul_f32_e32 v141, 0xbfb8aa3b, v131
	v_exp_f32_e32 v141, v141
	s_nop 0
	v_add_f32_e32 v141, 1.0, v141
	v_rcp_f32_e32 v141, v141
	s_nop 0
	v_mul_f32_e32 v131, v131, v141
	v_cvt_pk_bf16_f32 v139, v140, v131
	ds_write_b64 v130, v[138:139] offset:61280
	v_mov_b32_e32 v0, v151
	v_mul_f32_e32 v130, v6, v0
	v_mul_f32_e32 v131, 0xbfb8aa3b, v130
	v_exp_f32_e32 v131, v131
	s_nop 0
	v_add_f32_e32 v131, 1.0, v131
	v_rcp_f32_e32 v131, v131
	s_nop 0
	v_mul_f32_e32 v130, v130, v131
	v_mul_f32_e32 v131, v7, v0
	v_mul_f32_e32 v138, 0xbfb8aa3b, v131
	v_exp_f32_e32 v138, v138
	s_nop 0
	v_add_f32_e32 v138, 1.0, v138
	v_rcp_f32_e32 v138, v138
	s_nop 0
	v_mul_f32_e32 v131, v131, v138
	v_mul_f32_e32 v138, v8, v0
	v_mul_f32_e32 v139, 0xbfb8aa3b, v138
	v_exp_f32_e32 v139, v139
	v_mul_f32_e32 v0, v9, v0
	v_cvt_pk_bf16_f32 v130, v130, v131
	v_add_f32_e32 v139, 1.0, v139
	v_rcp_f32_e32 v139, v139
	s_nop 0
	v_mul_f32_e32 v138, v138, v139
	v_mul_f32_e32 v139, 0xbfb8aa3b, v0
	v_exp_f32_e32 v139, v139
	s_nop 0
	v_add_f32_e32 v139, 1.0, v139
	v_rcp_f32_e32 v139, v139
	s_nop 0
	v_mul_f32_e32 v0, v0, v139
	v_cvt_pk_bf16_f32 v131, v138, v0
	v_ashrrev_i32_e32 v138, 5, v132
	v_ashrrev_i32_e32 v139, 31, v138
	ds_write_b64 v137, v[130:131] offset:9056
	v_lshlrev_b64 v[130:131], 12, v[138:139]
	v_lshlrev_b32_e32 v0, 4, v132
	v_lshl_add_u64 v[130:131], v[130:131], 0, s[2:3]
	s_lshl_b64 s[2:3], s[14:15], 1
	v_and_b32_e32 v0, 0x1f0, v0
	s_add_u32 s2, s21, s2
	v_or_b32_e32 v130, v130, v0
	s_addc_u32 s3, s22, s3
	v_lshl_add_u64 v[130:131], s[2:3], 0, v[130:131]
	s_movk_i32 s2, 0x220
	v_mul_lo_u32 v137, v138, s2
	v_add3_u32 v0, v137, v0, 0
	s_mov_b64 s[2:3], 0
	s_waitcnt vmcnt(0) lgkmcnt(0)
	s_barrier

; #define STAGE_TILE_F(XFORM) do { SW_BEGIN f32x4 v = acc[ai][bj][m][n2]; XFORM; \
;     *(u32x2*)(smem + mrow * SPITCH + nc0 * 2) = u32x2{cvtpk_t(v[0], v[1]), cvtpk_t(v[2], v[3])}; LOOP_END __syncthreads(); } while (0)
; template <int kind> __device__ __forceinline__ void gemm_phase_n(const Params& P, int layer, int b, const int wv) {
;     ...
;                 } else if (pn < 16) {
;                     const int h = (pn - 8) >> 1, half = (pn - 8) & 1, item = h * 32 + pm;
;                     STAGE_TILE_F(v *= rs_lds[mrow]);
;                     u16* VS = (u16*)(ws + O_VS) + ((size_t)item * 512 + half * 256) * 512; TDRAIN(VS, 512);
.LBB0_724:
	s_and_b64 vcc, exec, s[2:3]
	s_mov_b64 s[14:15], 0x80
	s_cbranch_vccz .LBB0_727
	v_lshl_or_b32 v141, v136, 5, v135
	v_lshl_add_u32 v0, v141, 2, 0
	v_add_u32_e32 v142, 0x22000, v0
	ds_read_b32 v143, v142
	ds_read_b32 v144, v142 offset:64
	ds_read_b32 v145, v142 offset:512
	ds_read_b32 v146, v142 offset:576
	s_waitcnt lgkmcnt(0)
	v_mov_b32_e32 v0, v143
	v_lshlrev_b32_e32 v137, 7, v133
	v_lshl_add_u32 v140, v134, 3, 0
	s_movk_i32 s3, 0x1100
	s_lshl_b32 s2, s34, 4
	v_pk_mul_f32 v[130:131], v[124:125], v[0:1] op_sel_hi:[1,0]
	v_pk_mul_f32 v[138:139], v[122:123], v[0:1] op_sel_hi:[1,0]
	v_mul_u32_u24_e32 v0, 0x220, v141
	v_add3_u32 v137, v140, v137, v0
	v_cvt_pk_bf16_f32 v138, v138, v139
	v_cvt_pk_bf16_f32 v139, v130, v131
	ds_write_b64 v137, v[138:139]
	v_mov_b32_e32 v0, v144
	v_add_u32_e32 v140, 0x2200, v137
	v_add_u32_e32 v141, 0xee00, v140
	s_and_b32 s2, s2, 0xe0
	s_add_i32 s2, s2, s29
	v_pk_mul_f32 v[138:139], v[90:91], v[0:1] op_sel_hi:[1,0]
	v_pk_mul_f32 v[130:131], v[92:93], v[0:1] op_sel_hi:[1,0]
	v_cvt_pk_bf16_f32 v138, v138, v139
	s_and_b32 s5, s35, 1
	v_cvt_pk_bf16_f32 v139, v130, v131
	ds_write_b64 v137, v[138:139] offset:8704
	v_mov_b32_e32 v0, v145
	s_lshl_b32 s5, s5, 18
	v_pk_mul_f32 v[138:139], v[58:59], v[0:1] op_sel_hi:[1,0]
	v_pk_mul_f32 v[130:131], v[60:61], v[0:1] op_sel_hi:[1,0]
	v_cvt_pk_bf16_f32 v138, v138, v139
	s_nop 0
	v_cvt_pk_bf16_f32 v139, v130, v131
	ds_write_b64 v140, v[138:139] offset:60928
	v_mov_b32_e32 v0, v146
	v_pk_mul_f32 v[138:139], v[26:27], v[0:1] op_sel_hi:[1,0]
	v_pk_mul_f32 v[130:131], v[28:29], v[0:1] op_sel_hi:[1,0]
	v_cvt_pk_bf16_f32 v138, v138, v139
	s_nop 0
	v_cvt_pk_bf16_f32 v139, v130, v131
	ds_write_b64 v141, v[138:139] offset:8704
	s_waitcnt vmcnt(0)
	v_mov_b32_e32 v0, v143
	v_pk_mul_f32 v[138:139], v[114:115], v[0:1] op_sel_hi:[1,0]
	v_pk_mul_f32 v[130:131], v[116:117], v[0:1] op_sel_hi:[1,0]
	v_cvt_pk_bf16_f32 v138, v138, v139
	s_nop 0
	v_cvt_pk_bf16_f32 v139, v130, v131
	ds_write_b64 v137, v[138:139] offset:32
	v_mov_b32_e32 v0, v144
	v_pk_mul_f32 v[138:139], v[82:83], v[0:1] op_sel_hi:[1,0]
	v_pk_mul_f32 v[130:131], v[84:85], v[0:1] op_sel_hi:[1,0]
	v_cvt_pk_bf16_f32 v138, v138, v139
	s_nop 0
	v_cvt_pk_bf16_f32 v139, v130, v131
	ds_write_b64 v137, v[138:139] offset:8736
	v_mov_b32_e32 v0, v145
	v_pk_mul_f32 v[138:139], v[50:51], v[0:1] op_sel_hi:[1,0]
	v_pk_mul_f32 v[130:131], v[52:53], v[0:1] op_sel_hi:[1,0]
	v_cvt_pk_bf16_f32 v138, v138, v139
	s_nop 0
	v_cvt_pk_bf16_f32 v139, v130, v131
	ds_write_b64 v140, v[138:139] offset:60960
	v_mov_b32_e32 v0, v146
	v_pk_mul_f32 v[138:139], v[18:19], v[0:1] op_sel_hi:[1,0]
	v_pk_mul_f32 v[130:131], v[20:21], v[0:1] op_sel_hi:[1,0]
	v_cvt_pk_bf16_f32 v138, v138, v139
	s_nop 0
	v_cvt_pk_bf16_f32 v139, v130, v131
	ds_write_b64 v141, v[138:139] offset:8736
	v_mov_b32_e32 v0, v143
	v_pk_mul_f32 v[138:139], v[102:103], v[0:1] op_sel_hi:[1,0]
	v_pk_mul_f32 v[130:131], v[104:105], v[0:1] op_sel_hi:[1,0]
	v_cvt_pk_bf16_f32 v138, v138, v139
	s_nop 0
	v_cvt_pk_bf16_f32 v139, v130, v131
	ds_write_b64 v137, v[138:139] offset:64
	v_mov_b32_e32 v0, v144
	v_pk_mul_f32 v[138:139], v[70:71], v[0:1] op_sel_hi:[1,0]
	v_pk_mul_f32 v[130:131], v[72:73], v[0:1] op_sel_hi:[1,0]
	v_cvt_pk_bf16_f32 v138, v138, v139
	s_nop 0
	v_cvt_pk_bf16_f32 v139, v130, v131
	ds_write_b64 v137, v[138:139] offset:8768
	v_mov_b32_e32 v0, v145
	v_pk_mul_f32 v[138:139], v[38:39], v[0:1] op_sel_hi:[1,0]
	v_pk_mul_f32 v[130:131], v[40:41], v[0:1] op_sel_hi:[1,0]
	v_cvt_pk_bf16_f32 v138, v138, v139
	s_nop 0
	v_cvt_pk_bf16_f32 v139, v130, v131
	ds_write_b64 v140, v[138:139] offset:60992
	v_mov_b32_e32 v0, v146
	v_pk_mul_f32 v[138:139], v[10:11], v[0:1] op_sel_hi:[1,0]
	v_pk_mul_f32 v[130:131], v[12:13], v[0:1] op_sel_hi:[1,0]
	v_cvt_pk_bf16_f32 v138, v138, v139
	s_nop 0
	v_cvt_pk_bf16_f32 v139, v130, v131
	ds_write_b64 v141, v[138:139] offset:8768
	v_mov_b32_e32 v0, v143
	v_pk_mul_f32 v[138:139], v[98:99], v[0:1] op_sel_hi:[1,0]
	v_pk_mul_f32 v[130:131], v[100:101], v[0:1] op_sel_hi:[1,0]
	v_cvt_pk_bf16_f32 v138, v138, v139
	s_nop 0
	v_cvt_pk_bf16_f32 v139, v130, v131
	ds_write_b64 v137, v[138:139] offset:96
	v_mov_b32_e32 v0, v144
	v_pk_mul_f32 v[138:139], v[66:67], v[0:1] op_sel_hi:[1,0]
	v_pk_mul_f32 v[130:131], v[68:69], v[0:1] op_sel_hi:[1,0]
	v_cvt_pk_bf16_f32 v138, v138, v139
	s_nop 0
	v_cvt_pk_bf16_f32 v139, v130, v131
	ds_write_b64 v137, v[138:139] offset:8800
	v_mov_b32_e32 v0, v145
	v_pk_mul_f32 v[138:139], v[34:35], v[0:1] op_sel_hi:[1,0]
	v_pk_mul_f32 v[130:131], v[36:37], v[0:1] op_sel_hi:[1,0]
	v_cvt_pk_bf16_f32 v138, v138, v139
	s_nop 0
	v_cvt_pk_bf16_f32 v139, v130, v131
	ds_write_b64 v140, v[138:139] offset:61024
	v_mov_b32_e32 v0, v146
	v_pk_mul_f32 v[138:139], v[2:3], v[0:1] op_sel_hi:[1,0]
	v_pk_mul_f32 v[130:131], v[4:5], v[0:1] op_sel_hi:[1,0]
	v_cvt_pk_bf16_f32 v138, v138, v139
	s_nop 0
	v_cvt_pk_bf16_f32 v139, v130, v131
	ds_write_b64 v141, v[138:139] offset:8800
; #define STAGE_TILE_F(XFORM) do { SW_BEGIN f32x4 v = acc[ai][bj][m][n2]; XFORM; \
;     *(u32x2*)(smem + mrow * SPITCH + nc0 * 2) = u32x2{cvtpk_t(v[0], v[1]), cvtpk_t(v[2], v[3])}; LOOP_END __syncthreads(); } while (0)
; template <int kind> __device__ __forceinline__ void gemm_phase_n(const Params& P, int layer, int b, const int wv) {
;     ...
;                 } else if (pn < 16) {
;                     const int h = (pn - 8) >> 1, half = (pn - 8) & 1, item = h * 32 + pm;
;                     STAGE_TILE_F(v *= rs_lds[mrow]);
;                     u16* VS = (u16*)(ws + O_VS) + ((size_t)item * 512 + half * 256) * 512; TDRAIN(VS, 512);
	v_mov_b32_e32 v0, v143
	v_pk_mul_f32 v[138:139], v[126:127], v[0:1] op_sel_hi:[1,0]
	v_pk_mul_f32 v[130:131], v[128:129], v[0:1] op_sel_hi:[1,0]
	v_cvt_pk_bf16_f32 v138, v138, v139
	s_nop 0
	v_cvt_pk_bf16_f32 v139, v130, v131
	ds_write_b64 v137, v[138:139] offset:256
	v_mov_b32_e32 v0, v144
	v_pk_mul_f32 v[138:139], v[94:95], v[0:1] op_sel_hi:[1,0]
	v_pk_mul_f32 v[130:131], v[96:97], v[0:1] op_sel_hi:[1,0]
	v_cvt_pk_bf16_f32 v138, v138, v139
	s_nop 0
	v_cvt_pk_bf16_f32 v139, v130, v131
	ds_write_b64 v137, v[138:139] offset:8960
	v_mov_b32_e32 v0, v145
	v_pk_mul_f32 v[138:139], v[62:63], v[0:1] op_sel_hi:[1,0]
	v_pk_mul_f32 v[130:131], v[64:65], v[0:1] op_sel_hi:[1,0]
	v_cvt_pk_bf16_f32 v138, v138, v139
	s_nop 0
	v_cvt_pk_bf16_f32 v139, v130, v131
	ds_write_b64 v140, v[138:139] offset:61184
	v_mov_b32_e32 v0, v146
	v_pk_mul_f32 v[138:139], v[30:31], v[0:1] op_sel_hi:[1,0]
	v_pk_mul_f32 v[130:131], v[32:33], v[0:1] op_sel_hi:[1,0]
	v_cvt_pk_bf16_f32 v138, v138, v139
	s_nop 0
	v_cvt_pk_bf16_f32 v139, v130, v131
	ds_write_b64 v141, v[138:139] offset:8960
	v_mov_b32_e32 v0, v143
	v_pk_mul_f32 v[138:139], v[118:119], v[0:1] op_sel_hi:[1,0]
	v_pk_mul_f32 v[130:131], v[120:121], v[0:1] op_sel_hi:[1,0]
	v_cvt_pk_bf16_f32 v138, v138, v139
	s_nop 0
	v_cvt_pk_bf16_f32 v139, v130, v131
	ds_write_b64 v137, v[138:139] offset:288
	v_mov_b32_e32 v0, v144
	v_pk_mul_f32 v[138:139], v[86:87], v[0:1] op_sel_hi:[1,0]
	v_pk_mul_f32 v[130:131], v[88:89], v[0:1] op_sel_hi:[1,0]
	v_cvt_pk_bf16_f32 v138, v138, v139
	s_nop 0
	v_cvt_pk_bf16_f32 v139, v130, v131
	ds_write_b64 v137, v[138:139] offset:8992
	v_mov_b32_e32 v0, v145
	v_pk_mul_f32 v[138:139], v[54:55], v[0:1] op_sel_hi:[1,0]
	v_pk_mul_f32 v[130:131], v[56:57], v[0:1] op_sel_hi:[1,0]
	v_cvt_pk_bf16_f32 v138, v138, v139
	s_nop 0
	v_cvt_pk_bf16_f32 v139, v130, v131
	ds_write_b64 v140, v[138:139] offset:61216
	v_mov_b32_e32 v0, v146
	v_pk_mul_f32 v[138:139], v[22:23], v[0:1] op_sel_hi:[1,0]
	v_pk_mul_f32 v[130:131], v[24:25], v[0:1] op_sel_hi:[1,0]
	v_cvt_pk_bf16_f32 v138, v138, v139
	s_nop 0
	v_cvt_pk_bf16_f32 v139, v130, v131
	ds_write_b64 v141, v[138:139] offset:8992
	v_mov_b32_e32 v0, v143
	v_pk_mul_f32 v[138:139], v[110:111], v[0:1] op_sel_hi:[1,0]
	v_pk_mul_f32 v[130:131], v[112:113], v[0:1] op_sel_hi:[1,0]
	v_cvt_pk_bf16_f32 v138, v138, v139
	s_nop 0
	v_cvt_pk_bf16_f32 v139, v130, v131
	ds_write_b64 v137, v[138:139] offset:320
	v_mov_b32_e32 v0, v144
	v_pk_mul_f32 v[138:139], v[78:79], v[0:1] op_sel_hi:[1,0]
	v_pk_mul_f32 v[130:131], v[80:81], v[0:1] op_sel_hi:[1,0]
	v_cvt_pk_bf16_f32 v138, v138, v139
	s_nop 0
	v_cvt_pk_bf16_f32 v139, v130, v131
	ds_write_b64 v137, v[138:139] offset:9024
	v_mov_b32_e32 v0, v145
	v_pk_mul_f32 v[138:139], v[46:47], v[0:1] op_sel_hi:[1,0]
	v_pk_mul_f32 v[130:131], v[48:49], v[0:1] op_sel_hi:[1,0]
	v_cvt_pk_bf16_f32 v138, v138, v139
	s_nop 0
	v_cvt_pk_bf16_f32 v139, v130, v131
	ds_write_b64 v140, v[138:139] offset:61248
	v_mov_b32_e32 v0, v146
	v_pk_mul_f32 v[138:139], v[14:15], v[0:1] op_sel_hi:[1,0]
	v_pk_mul_f32 v[130:131], v[16:17], v[0:1] op_sel_hi:[1,0]
	v_cvt_pk_bf16_f32 v138, v138, v139
	s_nop 0
	v_cvt_pk_bf16_f32 v139, v130, v131
	ds_write_b64 v141, v[138:139] offset:9024
	v_mov_b32_e32 v0, v143
	v_pk_mul_f32 v[138:139], v[106:107], v[0:1] op_sel_hi:[1,0]
	v_pk_mul_f32 v[130:131], v[108:109], v[0:1] op_sel_hi:[1,0]
	v_cvt_pk_bf16_f32 v138, v138, v139
	s_nop 0
	v_cvt_pk_bf16_f32 v139, v130, v131
	ds_write_b64 v137, v[138:139] offset:352
	v_mov_b32_e32 v0, v144
	v_pk_mul_f32 v[138:139], v[74:75], v[0:1] op_sel_hi:[1,0]
	v_pk_mul_f32 v[130:131], v[76:77], v[0:1] op_sel_hi:[1,0]
	v_cvt_pk_bf16_f32 v138, v138, v139
	s_nop 0
	v_cvt_pk_bf16_f32 v139, v130, v131
	ds_write_b64 v137, v[138:139] offset:9056
	v_mov_b32_e32 v0, v145
	v_and_b32_e32 v137, 0xff, v132
	v_pk_mul_f32 v[138:139], v[42:43], v[0:1] op_sel_hi:[1,0]
	v_pk_mul_f32 v[130:131], v[44:45], v[0:1] op_sel_hi:[1,0]
	v_cvt_pk_bf16_f32 v138, v138, v139
	s_nop 0
	v_cvt_pk_bf16_f32 v139, v130, v131
	ds_write_b64 v140, v[138:139] offset:61280
	v_mov_b32_e32 v0, v146
	v_pk_mul_f32 v[130:131], v[8:9], v[0:1] op_sel_hi:[1,0]
	v_pk_mul_f32 v[138:139], v[6:7], v[0:1] op_sel_hi:[1,0]
	v_ashrrev_i32_e32 v0, 5, v132
	v_cvt_pk_bf16_f32 v138, v138, v139
	v_cvt_pk_bf16_f32 v139, v130, v131
	v_and_b32_e32 v130, -8, v0
	v_lshrrev_b32_e32 v0, 3, v0
	v_mul_lo_u32 v0, v0, s3
	s_sub_i32 s3, s36, s38
	s_sub_i32 s3, s3, s37
	s_sext_i32_i16 s3, s3
	s_add_i32 s2, s2, s3
	s_addk_i32 s2, 0xff80
	s_ashr_i32 s3, s2, 31
	s_lshl_b64 s[2:3], s[2:3], 19
	ds_write_b64 v141, v[138:139] offset:9056
	v_lshlrev_b32_e32 v138, 1, v137
	s_or_b32 s2, s2, s5
	v_ashrrev_i32_e32 v131, 31, v130
	v_add3_u32 v0, v0, v138, 0
	v_lshl_or_b32 v138, v137, 10, s2
	v_mov_b32_e32 v139, s3
	v_lshl_add_u64 v[130:131], v[130:131], 1, v[138:139]
	v_lshl_add_u64 v[130:131], s[10:11], 0, v[130:131]
	s_mov_b32 s2, 0
	s_waitcnt lgkmcnt(0)
	s_barrier
